# all 8 GEMM K-loops: LDS-DMA loads in saddr form (SGPR base + 32-bit VGPR offset), 16 v_lshl_add_u64 per iteration removed; loops padded so later code keeps its byte offsets
# baseline (speedup 1.0000x reference)
; #define PG8_STAGE(bufoff, gbase, voff) do { _Pragma("unroll") for (int _i = 0; _i < 2; ++_i) \
;         __builtin_amdgcn_global_load_lds((const unsigned*)((const char*)(gbase) + (voff)[_i]), (PG8_LAS unsigned*)(lds + (bufoff) + ldsw + _i * 8192), 16, 0, 0); } while (0)
; #define PG8_LDA(dst, b, h) do { _Pragma("unroll") for (int m = 0; m < 4; ++m) _Pragma("unroll") for (int k = 0; k < 2; ++k) dst[m][k] = *(const PG8_LAS bf16x8*)(lds + PG8_SA(b, h) + aoff + m * 2048 + k * 1024); } while (0)
; #define PG8_LDB(dst, b, h) do { _Pragma("unroll") for (int n = 0; n < 2; ++n) _Pragma("unroll") for (int k = 0; k < 2; ++k) dst[n][k] = *(const PG8_LAS bf16x8*)(lds + PG8_SB(b, h) + boff + n * 2048 + k * 1024); } while (0)
; #define PG8_MMA(ai, bj, At, Bt) do { __builtin_amdgcn_s_setprio(1); _Pragma("unroll") for (int m = 0; m < 4; ++m) _Pragma("unroll") for (int n = 0; n < 2; ++n) _Pragma("unroll") for (int k = 0; k < 2; ++k) \
;         acc[ai][bj][m][n] = __builtin_amdgcn_mfma_f32_16x16x32_bf16(Bt[n][k], At[m][k], acc[ai][bj][m][n], 0, 0, 0); __builtin_amdgcn_s_setprio(0); } while (0)
; #define PG8_WAIT_V(n) asm volatile("s_waitcnt vmcnt(" #n ")" ::: "memory")
; #define PG8_WAIT_L(n) asm volatile("s_waitcnt lgkmcnt(" #n ")" ::: "memory")
; template <class Epi, class Sched, bool ALIGN_EPI = false, bool SP2 = false>
; __device__ __forceinline__ void gemm_phase(PG8_LAS unsigned char* lds, const Gemm g, const Sched& S, const Epi& E) {
;     ...
;             const bool last = (t == nt - 2);
;             const char* a1 = cA + (size_t)(t + 1) * kstep;
;             const char* a2 = last ? nA : cA + (size_t)(t + 2) * kstep; const char* b2 = last ? nB : cB + (size_t)(t + 2) * kstep;
;             const char* a3 = a2 + kstep; const char* b3 = b2 + kstep;
;             if (last && has_next) S.a_ready(nxt);
;             if constexpr (SP2) {
;             PG8_LDB(B0, 0, 0); PG8_LDB(B1, 0, 1); PG8_SCHED; PG8_LDA(At, 0, 0); PG8_STAGE(PG8_SA(1, 1), a1 + hstep, voffA);
;             PG8_WAIT_V(8); PG8_WAIT_L(0); PG8_BAR; PG8_MMA(0, 0, At, B0); PG8_MMA(0, 1, At, B1); PG8_BAR; PG8_SCHED;
;             PG8_LDA(At, 0, 1); PG8_STAGE(PG8_SB(0, 0), b2, voffB); PG8_STAGE(PG8_SB(0, 1), b2 + hstep, voffB); PG8_STAGE(PG8_SA(0, 0), a2, voffA);
;             PG8_WAIT_V(8); PG8_WAIT_L(0); PG8_BAR; PG8_MMA(1, 0, At, B0); PG8_MMA(1, 1, At, B1); PG8_BAR; PG8_SCHED;
.LBB0_435:
	ds_read_b128 v[156:159], v150
	ds_read_b128 v[160:163], v150 offset:1024
	ds_read_b128 v[164:167], v150 offset:2048
	ds_read_b128 v[168:171], v150 offset:3072
	ds_read_b128 v[172:175], v151
	ds_read_b128 v[176:179], v151 offset:1024
	ds_read_b128 v[180:183], v151 offset:2048
	ds_read_b128 v[186:189], v151 offset:3072
	s_add_u32 s24, s22, 0xfffc0080
	s_addc_u32 s25, s23, -1
	s_cmp_eq_u32 s51, 12
	s_cselect_b32 s27, s13, s25
	s_cselect_b32 s26, s47, s24
	s_cselect_b32 s25, s11, s50
	s_cselect_b32 s24, s48, s49
	s_add_i32 m0, s21, 0xc000
	ds_read_b128 v[190:193], v152
	ds_read_b128 v[194:197], v152 offset:1024
	ds_read_b128 v[198:201], v152 offset:2048
	ds_read_b128 v[202:205], v152 offset:3072
	ds_read_b128 v[206:209], v152 offset:4096
	ds_read_b128 v[210:213], v152 offset:5120
	ds_read_b128 v[214:217], v152 offset:6144
	ds_read_b128 v[218:221], v152 offset:7168
	global_load_lds_dwordx4 v136, s[22:23]
	s_add_i32 m0, s21, 0xe000
	s_nop 0
	global_load_lds_dwordx4 v138, s[22:23]
	s_waitcnt vmcnt(8)
	s_waitcnt lgkmcnt(0)
	s_barrier
	s_setprio 1
	s_waitcnt lgkmcnt(0)
	v_mfma_f32_16x16x32_bf16 v[124:127], v[156:159], v[190:193], v[124:127]
	v_mfma_f32_16x16x32_bf16 v[120:123], v[164:167], v[190:193], v[120:123]
	v_mfma_f32_16x16x32_bf16 v[108:111], v[156:159], v[198:201], v[108:111]
	v_mfma_f32_16x16x32_bf16 v[104:107], v[164:167], v[198:201], v[104:107]
	v_mfma_f32_16x16x32_bf16 v[92:95], v[156:159], v[206:209], v[92:95]
	v_mfma_f32_16x16x32_bf16 v[88:91], v[164:167], v[206:209], v[88:91]
	v_mfma_f32_16x16x32_bf16 v[76:79], v[156:159], v[214:217], v[76:79]
	v_mfma_f32_16x16x32_bf16 v[72:75], v[164:167], v[214:217], v[72:75]
	v_mfma_f32_16x16x32_bf16 v[124:127], v[160:163], v[194:197], v[124:127]
	v_mfma_f32_16x16x32_bf16 v[120:123], v[168:171], v[194:197], v[120:123]
	v_mfma_f32_16x16x32_bf16 v[108:111], v[160:163], v[202:205], v[108:111]
	v_mfma_f32_16x16x32_bf16 v[104:107], v[168:171], v[202:205], v[104:107]
	v_mfma_f32_16x16x32_bf16 v[92:95], v[160:163], v[210:213], v[92:95]
	v_mfma_f32_16x16x32_bf16 v[88:91], v[168:171], v[210:213], v[88:91]
	v_mfma_f32_16x16x32_bf16 v[76:79], v[160:163], v[218:221], v[76:79]
	v_mfma_f32_16x16x32_bf16 v[72:75], v[168:171], v[218:221], v[72:75]
	s_setprio 0
	s_setprio 1
	v_mfma_f32_16x16x32_bf16 v[116:119], v[172:175], v[190:193], v[116:119]
	v_mfma_f32_16x16x32_bf16 v[112:115], v[180:183], v[190:193], v[112:115]
	v_mfma_f32_16x16x32_bf16 v[100:103], v[172:175], v[198:201], v[100:103]
	v_mfma_f32_16x16x32_bf16 v[96:99], v[180:183], v[198:201], v[96:99]
	v_mfma_f32_16x16x32_bf16 v[84:87], v[172:175], v[206:209], v[84:87]
	v_mfma_f32_16x16x32_bf16 v[80:83], v[180:183], v[206:209], v[80:83]
	v_mfma_f32_16x16x32_bf16 v[68:71], v[172:175], v[214:217], v[68:71]
	v_mfma_f32_16x16x32_bf16 v[64:67], v[180:183], v[214:217], v[64:67]
	v_mfma_f32_16x16x32_bf16 v[116:119], v[176:179], v[194:197], v[116:119]
	v_mfma_f32_16x16x32_bf16 v[112:115], v[186:189], v[194:197], v[112:115]
	v_mfma_f32_16x16x32_bf16 v[100:103], v[176:179], v[202:205], v[100:103]
	v_mfma_f32_16x16x32_bf16 v[96:99], v[186:189], v[202:205], v[96:99]
	v_mfma_f32_16x16x32_bf16 v[84:87], v[176:179], v[210:213], v[84:87]
	v_mfma_f32_16x16x32_bf16 v[80:83], v[186:189], v[210:213], v[80:83]
	v_mfma_f32_16x16x32_bf16 v[68:71], v[176:179], v[218:221], v[68:71]
	v_mfma_f32_16x16x32_bf16 v[64:67], v[186:189], v[218:221], v[64:67]
	s_setprio 0
	s_barrier
	s_add_i32 s52, s42, s30
	s_mov_b32 m0, s52
	ds_read_b128 v[190:193], v152 offset:16384
	ds_read_b128 v[194:197], v152 offset:17408
	ds_read_b128 v[198:201], v152 offset:18432
	ds_read_b128 v[202:205], v152 offset:19456
	ds_read_b128 v[206:209], v152 offset:20480
	ds_read_b128 v[210:213], v152 offset:21504
	ds_read_b128 v[214:217], v152 offset:22528
	ds_read_b128 v[218:221], v152 offset:23552
	global_load_lds_dwordx4 v132, s[24:25]
	s_add_i32 m0, s52, 0x2000
	s_add_u32 s52, s24, 0x40000
	s_addc_u32 s53, s25, 0
	s_add_i32 s54, s43, s30
	global_load_lds_dwordx4 v128, s[24:25]
	s_mov_b32 m0, s54
	s_nop 0
	global_load_lds_dwordx4 v132, s[52:53]
	s_add_i32 m0, s54, 0x2000
	s_nop 0
	global_load_lds_dwordx4 v128, s[52:53]
	s_mov_b32 m0, s21
	s_nop 0
	global_load_lds_dwordx4 v134, s[26:27]
	s_mov_b32 m0, s35
	s_nop 0
	global_load_lds_dwordx4 v130, s[26:27]
	s_waitcnt vmcnt(8)
	s_waitcnt lgkmcnt(0)
	s_barrier
	s_setprio 1
	s_waitcnt lgkmcnt(0)
	v_mfma_f32_16x16x32_bf16 v[60:63], v[156:159], v[190:193], v[60:63]
	v_mfma_f32_16x16x32_bf16 v[56:59], v[164:167], v[190:193], v[56:59]
	v_mfma_f32_16x16x32_bf16 v[44:47], v[156:159], v[198:201], v[44:47]
	v_mfma_f32_16x16x32_bf16 v[40:43], v[164:167], v[198:201], v[40:43]
	v_mfma_f32_16x16x32_bf16 v[28:31], v[156:159], v[206:209], v[28:31]
	v_mfma_f32_16x16x32_bf16 v[24:27], v[164:167], v[206:209], v[24:27]
	v_mfma_f32_16x16x32_bf16 v[12:15], v[156:159], v[214:217], v[12:15]
	v_mfma_f32_16x16x32_bf16 v[8:11], v[164:167], v[214:217], v[8:11]
	v_mfma_f32_16x16x32_bf16 v[60:63], v[160:163], v[194:197], v[60:63]
	v_mfma_f32_16x16x32_bf16 v[56:59], v[168:171], v[194:197], v[56:59]
	v_mfma_f32_16x16x32_bf16 v[44:47], v[160:163], v[202:205], v[44:47]
	v_mfma_f32_16x16x32_bf16 v[40:43], v[168:171], v[202:205], v[40:43]
	v_mfma_f32_16x16x32_bf16 v[28:31], v[160:163], v[210:213], v[28:31]
	v_mfma_f32_16x16x32_bf16 v[24:27], v[168:171], v[210:213], v[24:27]
	v_mfma_f32_16x16x32_bf16 v[12:15], v[160:163], v[218:221], v[12:15]
	v_mfma_f32_16x16x32_bf16 v[8:11], v[168:171], v[218:221], v[8:11]
	s_setprio 0
	s_setprio 1
	v_mfma_f32_16x16x32_bf16 v[52:55], v[172:175], v[190:193], v[52:55]
	v_mfma_f32_16x16x32_bf16 v[48:51], v[180:183], v[190:193], v[48:51]
	v_mfma_f32_16x16x32_bf16 v[36:39], v[172:175], v[198:201], v[36:39]
	v_mfma_f32_16x16x32_bf16 v[32:35], v[180:183], v[198:201], v[32:35]
	v_mfma_f32_16x16x32_bf16 v[20:23], v[172:175], v[206:209], v[20:23]
	v_mfma_f32_16x16x32_bf16 v[16:19], v[180:183], v[206:209], v[16:19]
	v_mfma_f32_16x16x32_bf16 v[4:7], v[172:175], v[214:217], v[4:7]
	v_mfma_f32_16x16x32_bf16 v[0:3], v[180:183], v[214:217], v[0:3]
	v_mfma_f32_16x16x32_bf16 v[52:55], v[176:179], v[194:197], v[52:55]
	v_mfma_f32_16x16x32_bf16 v[48:51], v[186:189], v[194:197], v[48:51]
	v_mfma_f32_16x16x32_bf16 v[36:39], v[176:179], v[202:205], v[36:39]
	v_mfma_f32_16x16x32_bf16 v[32:35], v[186:189], v[202:205], v[32:35]
	v_mfma_f32_16x16x32_bf16 v[20:23], v[176:179], v[210:213], v[20:23]
	v_mfma_f32_16x16x32_bf16 v[16:19], v[186:189], v[210:213], v[16:19]
	v_mfma_f32_16x16x32_bf16 v[4:7], v[176:179], v[218:221], v[4:7]
	v_mfma_f32_16x16x32_bf16 v[0:3], v[186:189], v[218:221], v[0:3]
	s_setprio 0
	s_barrier
; #define PG8_STAGE(bufoff, gbase, voff) do { _Pragma("unroll") for (int _i = 0; _i < 2; ++_i) \
;         __builtin_amdgcn_global_load_lds((const unsigned*)((const char*)(gbase) + (voff)[_i]), (PG8_LAS unsigned*)(lds + (bufoff) + ldsw + _i * 8192), 16, 0, 0); } while (0)
; #define PG8_LDA(dst, b, h) do { _Pragma("unroll") for (int m = 0; m < 4; ++m) _Pragma("unroll") for (int k = 0; k < 2; ++k) dst[m][k] = *(const PG8_LAS bf16x8*)(lds + PG8_SA(b, h) + aoff + m * 2048 + k * 1024); } while (0)
; #define PG8_LDB(dst, b, h) do { _Pragma("unroll") for (int n = 0; n < 2; ++n) _Pragma("unroll") for (int k = 0; k < 2; ++k) dst[n][k] = *(const PG8_LAS bf16x8*)(lds + PG8_SB(b, h) + boff + n * 2048 + k * 1024); } while (0)
; #define PG8_MMA(ai, bj, At, Bt) do { __builtin_amdgcn_s_setprio(1); _Pragma("unroll") for (int m = 0; m < 4; ++m) _Pragma("unroll") for (int n = 0; n < 2; ++n) _Pragma("unroll") for (int k = 0; k < 2; ++k) \
;         acc[ai][bj][m][n] = __builtin_amdgcn_mfma_f32_16x16x32_bf16(Bt[n][k], At[m][k], acc[ai][bj][m][n], 0, 0, 0); __builtin_amdgcn_s_setprio(0); } while (0)
; #define PG8_WAIT_V(n) asm volatile("s_waitcnt vmcnt(" #n ")" ::: "memory")
; #define PG8_WAIT_L(n) asm volatile("s_waitcnt lgkmcnt(" #n ")" ::: "memory")
; #define PG8_BAR __builtin_amdgcn_s_barrier()
; #define PG8_SCHED __builtin_amdgcn_sched_barrier(0)
; template <class Epi, class Sched, bool ALIGN_EPI = false, bool SP2 = false>
; __device__ __forceinline__ void gemm_phase(PG8_LAS unsigned char* lds, const Gemm g, const Sched& S, const Epi& E) {
;     ...
;         for (int t = 0; t < nt; t += 2) {
;     ...
;             PG8_LDB(B0, 1, 0); PG8_LDB(B1, 1, 1); PG8_SCHED; PG8_LDA(At, 1, 0); PG8_STAGE(PG8_SA(0, 1), a2 + hstep, voffA);
;             PG8_WAIT_V(8); PG8_WAIT_L(0); PG8_BAR; PG8_MMA(0, 0, At, B0); PG8_MMA(0, 1, At, B1); PG8_BAR; PG8_SCHED;
;             PG8_LDA(At, 1, 1); PG8_STAGE(PG8_SB(1, 0), b3, voffB); PG8_STAGE(PG8_SB(1, 1), b3 + hstep, voffB); PG8_STAGE(PG8_SA(1, 0), a3, voffA);
;             PG8_WAIT_V(8); PG8_WAIT_L(0); PG8_BAR; PG8_MMA(1, 0, At, B0); PG8_MMA(1, 1, At, B1); PG8_BAR; PG8_SCHED;
	ds_read_b128 v[156:159], v153
	ds_read_b128 v[160:163], v153 offset:1024
	ds_read_b128 v[164:167], v153 offset:2048
	ds_read_b128 v[168:171], v153 offset:3072
	ds_read_b128 v[172:175], v154
	ds_read_b128 v[176:179], v154 offset:1024
	ds_read_b128 v[180:183], v154 offset:2048
	ds_read_b128 v[186:189], v154 offset:3072
	s_add_u32 s100, s26, 0x40000
	s_addc_u32 s101, s27, 0
	s_mov_b32 m0, s36
	ds_read_b128 v[190:193], v152 offset:32768
	ds_read_b128 v[194:197], v152 offset:33792
	ds_read_b128 v[198:201], v152 offset:34816
	ds_read_b128 v[202:205], v152 offset:35840
	ds_read_b128 v[206:209], v152 offset:36864
	ds_read_b128 v[210:213], v152 offset:37888
	ds_read_b128 v[214:217], v152 offset:38912
	ds_read_b128 v[218:221], v152 offset:39936
	global_load_lds_dwordx4 v134, s[100:101]
	s_mov_b32 m0, s37
	s_nop 0
	global_load_lds_dwordx4 v130, s[100:101]
	s_waitcnt vmcnt(8)
	s_waitcnt lgkmcnt(0)
	s_barrier
	s_setprio 1
	s_waitcnt lgkmcnt(0)
	v_mfma_f32_16x16x32_bf16 v[124:127], v[156:159], v[190:193], v[124:127]
	v_mfma_f32_16x16x32_bf16 v[120:123], v[164:167], v[190:193], v[120:123]
	v_mfma_f32_16x16x32_bf16 v[108:111], v[156:159], v[198:201], v[108:111]
	v_mfma_f32_16x16x32_bf16 v[104:107], v[164:167], v[198:201], v[104:107]
	v_mfma_f32_16x16x32_bf16 v[92:95], v[156:159], v[206:209], v[92:95]
	v_mfma_f32_16x16x32_bf16 v[88:91], v[164:167], v[206:209], v[88:91]
	v_mfma_f32_16x16x32_bf16 v[76:79], v[156:159], v[214:217], v[76:79]
	v_mfma_f32_16x16x32_bf16 v[72:75], v[164:167], v[214:217], v[72:75]
	v_mfma_f32_16x16x32_bf16 v[124:127], v[160:163], v[194:197], v[124:127]
	v_mfma_f32_16x16x32_bf16 v[120:123], v[168:171], v[194:197], v[120:123]
	v_mfma_f32_16x16x32_bf16 v[108:111], v[160:163], v[202:205], v[108:111]
	v_mfma_f32_16x16x32_bf16 v[104:107], v[168:171], v[202:205], v[104:107]
	v_mfma_f32_16x16x32_bf16 v[92:95], v[160:163], v[210:213], v[92:95]
	v_mfma_f32_16x16x32_bf16 v[88:91], v[168:171], v[210:213], v[88:91]
	v_mfma_f32_16x16x32_bf16 v[76:79], v[160:163], v[218:221], v[76:79]
	v_mfma_f32_16x16x32_bf16 v[72:75], v[168:171], v[218:221], v[72:75]
	s_setprio 0
	s_setprio 1
	v_mfma_f32_16x16x32_bf16 v[116:119], v[172:175], v[190:193], v[116:119]
	v_mfma_f32_16x16x32_bf16 v[112:115], v[180:183], v[190:193], v[112:115]
	v_mfma_f32_16x16x32_bf16 v[100:103], v[172:175], v[198:201], v[100:103]
	v_mfma_f32_16x16x32_bf16 v[96:99], v[180:183], v[198:201], v[96:99]
	v_mfma_f32_16x16x32_bf16 v[84:87], v[172:175], v[206:209], v[84:87]
	v_mfma_f32_16x16x32_bf16 v[80:83], v[180:183], v[206:209], v[80:83]
	v_mfma_f32_16x16x32_bf16 v[68:71], v[172:175], v[214:217], v[68:71]
	v_mfma_f32_16x16x32_bf16 v[64:67], v[180:183], v[214:217], v[64:67]
	v_mfma_f32_16x16x32_bf16 v[116:119], v[176:179], v[194:197], v[116:119]
	v_mfma_f32_16x16x32_bf16 v[112:115], v[186:189], v[194:197], v[112:115]
	v_mfma_f32_16x16x32_bf16 v[100:103], v[176:179], v[202:205], v[100:103]
	v_mfma_f32_16x16x32_bf16 v[96:99], v[186:189], v[202:205], v[96:99]
	v_mfma_f32_16x16x32_bf16 v[84:87], v[176:179], v[210:213], v[84:87]
	v_mfma_f32_16x16x32_bf16 v[80:83], v[186:189], v[210:213], v[80:83]
	v_mfma_f32_16x16x32_bf16 v[68:71], v[176:179], v[218:221], v[68:71]
	v_mfma_f32_16x16x32_bf16 v[64:67], v[186:189], v[218:221], v[64:67]
	s_setprio 0
	s_barrier
	s_add_u32 s100, s24, 0x80
	s_addc_u32 s101, s25, 0
	s_add_i32 s98, s45, s30
	s_mov_b32 m0, s98
	ds_read_b128 v[190:193], v152 offset:49152
	ds_read_b128 v[194:197], v152 offset:50176
	ds_read_b128 v[198:201], v152 offset:51200
	ds_read_b128 v[202:205], v152 offset:52224
	ds_read_b128 v[206:209], v152 offset:53248
	ds_read_b128 v[210:213], v152 offset:54272
	ds_read_b128 v[214:217], v152 offset:55296
	ds_read_b128 v[218:221], v152 offset:56320
	global_load_lds_dwordx4 v132, s[100:101]
	s_add_i32 m0, s98, 0x2000
	s_add_u32 s24, s24, 0x40080
	s_addc_u32 s25, s25, 0
	s_add_i32 s98, s46, s30
	global_load_lds_dwordx4 v128, s[100:101]
	s_mov_b32 m0, s98
	s_nop 0
	global_load_lds_dwordx4 v132, s[24:25]
	s_add_i32 m0, s98, 0x2000
	s_nop 0
	global_load_lds_dwordx4 v128, s[24:25]
	s_add_u32 s100, s26, 0x80
	s_addc_u32 s101, s27, 0
	s_mov_b32 m0, s39
	s_nop 0
	global_load_lds_dwordx4 v134, s[100:101]
	s_mov_b32 m0, s40
	s_nop 0
	global_load_lds_dwordx4 v130, s[100:101]
	s_waitcnt vmcnt(8)
	s_waitcnt lgkmcnt(0)
	s_barrier
	s_setprio 1
	s_waitcnt lgkmcnt(0)
	v_mfma_f32_16x16x32_bf16 v[60:63], v[156:159], v[190:193], v[60:63]
	v_mfma_f32_16x16x32_bf16 v[56:59], v[164:167], v[190:193], v[56:59]
	v_mfma_f32_16x16x32_bf16 v[44:47], v[156:159], v[198:201], v[44:47]
	v_mfma_f32_16x16x32_bf16 v[40:43], v[164:167], v[198:201], v[40:43]
	v_mfma_f32_16x16x32_bf16 v[28:31], v[156:159], v[206:209], v[28:31]
	v_mfma_f32_16x16x32_bf16 v[24:27], v[164:167], v[206:209], v[24:27]
	v_mfma_f32_16x16x32_bf16 v[12:15], v[156:159], v[214:217], v[12:15]
	v_mfma_f32_16x16x32_bf16 v[8:11], v[164:167], v[214:217], v[8:11]
	v_mfma_f32_16x16x32_bf16 v[60:63], v[160:163], v[194:197], v[60:63]
	v_mfma_f32_16x16x32_bf16 v[56:59], v[168:171], v[194:197], v[56:59]
	v_mfma_f32_16x16x32_bf16 v[44:47], v[160:163], v[202:205], v[44:47]
	v_mfma_f32_16x16x32_bf16 v[40:43], v[168:171], v[202:205], v[40:43]
	v_mfma_f32_16x16x32_bf16 v[28:31], v[160:163], v[210:213], v[28:31]
	v_mfma_f32_16x16x32_bf16 v[24:27], v[168:171], v[210:213], v[24:27]
	v_mfma_f32_16x16x32_bf16 v[12:15], v[160:163], v[218:221], v[12:15]
	v_mfma_f32_16x16x32_bf16 v[8:11], v[168:171], v[218:221], v[8:11]
	s_setprio 0
	s_setprio 1
	v_mfma_f32_16x16x32_bf16 v[52:55], v[172:175], v[190:193], v[52:55]
	v_mfma_f32_16x16x32_bf16 v[48:51], v[180:183], v[190:193], v[48:51]
	v_mfma_f32_16x16x32_bf16 v[36:39], v[172:175], v[198:201], v[36:39]
	v_mfma_f32_16x16x32_bf16 v[32:35], v[180:183], v[198:201], v[32:35]
	v_mfma_f32_16x16x32_bf16 v[20:23], v[172:175], v[206:209], v[20:23]
	v_mfma_f32_16x16x32_bf16 v[16:19], v[180:183], v[206:209], v[16:19]
	v_mfma_f32_16x16x32_bf16 v[4:7], v[172:175], v[214:217], v[4:7]
	v_mfma_f32_16x16x32_bf16 v[0:3], v[180:183], v[214:217], v[0:3]
	v_mfma_f32_16x16x32_bf16 v[52:55], v[176:179], v[194:197], v[52:55]
	v_mfma_f32_16x16x32_bf16 v[48:51], v[186:189], v[194:197], v[48:51]
	v_mfma_f32_16x16x32_bf16 v[36:39], v[176:179], v[202:205], v[36:39]
	v_mfma_f32_16x16x32_bf16 v[32:35], v[186:189], v[202:205], v[32:35]
	v_mfma_f32_16x16x32_bf16 v[20:23], v[176:179], v[210:213], v[20:23]
	v_mfma_f32_16x16x32_bf16 v[16:19], v[186:189], v[210:213], v[16:19]
	v_mfma_f32_16x16x32_bf16 v[4:7], v[176:179], v[218:221], v[4:7]
	v_mfma_f32_16x16x32_bf16 v[0:3], v[186:189], v[218:221], v[0:3]
	s_setprio 0
	s_barrier
	s_add_i32 s51, s51, 2
	s_add_u32 s22, s22, 0x100
	s_addc_u32 s23, s23, 0
	s_add_u32 s49, s49, 0x100
	s_addc_u32 s50, s50, 0
	s_cmp_gt_u32 s51, 13
	s_cbranch_scc0 .LBB0_435
	s_nop 0
	s_nop 0
	s_nop 0
	s_nop 0
	s_nop 0
	s_nop 0
	s_nop 0
	s_nop 0
	s_nop 0
	s_nop 0
	s_nop 0
	s_nop 0
	s_nop 0
	s_nop 0
	s_nop 0
	s_nop 0
	s_nop 0
	s_nop 0
	s_nop 0
	s_nop 0
	s_nop 0
	s_nop 0
	s_nop 0
	s_nop 0
	s_nop 0
	s_and_b64 vcc, exec, s[8:9]
	s_cbranch_vccz .LBB0_438
	s_barrier

; #define PG8_STAGE(bufoff, gbase, voff) do { _Pragma("unroll") for (int _i = 0; _i < 2; ++_i) \
;         __builtin_amdgcn_global_load_lds((const unsigned*)((const char*)(gbase) + (voff)[_i]), (PG8_LAS unsigned*)(lds + (bufoff) + ldsw + _i * 8192), 16, 0, 0); } while (0)
; #define PG8_LDA(dst, b, h) do { _Pragma("unroll") for (int m = 0; m < 4; ++m) _Pragma("unroll") for (int k = 0; k < 2; ++k) dst[m][k] = *(const PG8_LAS bf16x8*)(lds + PG8_SA(b, h) + aoff + m * 2048 + k * 1024); } while (0)
; #define PG8_LDB(dst, b, h) do { _Pragma("unroll") for (int n = 0; n < 2; ++n) _Pragma("unroll") for (int k = 0; k < 2; ++k) dst[n][k] = *(const PG8_LAS bf16x8*)(lds + PG8_SB(b, h) + boff + n * 2048 + k * 1024); } while (0)
; #define PG8_MMA(ai, bj, At, Bt) do { __builtin_amdgcn_s_setprio(1); _Pragma("unroll") for (int m = 0; m < 4; ++m) _Pragma("unroll") for (int n = 0; n < 2; ++n) _Pragma("unroll") for (int k = 0; k < 2; ++k) \
;         acc[ai][bj][m][n] = __builtin_amdgcn_mfma_f32_16x16x32_bf16(Bt[n][k], At[m][k], acc[ai][bj][m][n], 0, 0, 0); __builtin_amdgcn_s_setprio(0); } while (0)
; #define PG8_WAIT_V(n) asm volatile("s_waitcnt vmcnt(" #n ")" ::: "memory")
; #define PG8_WAIT_L(n) asm volatile("s_waitcnt lgkmcnt(" #n ")" ::: "memory")
; template <class Epi, class Sched, bool ALIGN_EPI = false, bool SP2 = false>
; __device__ __forceinline__ void gemm_phase(PG8_LAS unsigned char* lds, const Gemm g, const Sched& S, const Epi& E) {
;     ...
;             const bool last = (t == nt - 2);
;             const char* a1 = cA + (size_t)(t + 1) * kstep;
;             const char* a2 = last ? nA : cA + (size_t)(t + 2) * kstep; const char* b2 = last ? nB : cB + (size_t)(t + 2) * kstep;
;             const char* a3 = a2 + kstep; const char* b3 = b2 + kstep;
;             if (last && has_next) S.a_ready(nxt);
;             if constexpr (SP2) {
;             PG8_LDB(B0, 0, 0); PG8_LDB(B1, 0, 1); PG8_SCHED; PG8_LDA(At, 0, 0); PG8_STAGE(PG8_SA(1, 1), a1 + hstep, voffA);
;             PG8_WAIT_V(8); PG8_WAIT_L(0); PG8_BAR; PG8_MMA(0, 0, At, B0); PG8_MMA(0, 1, At, B1); PG8_BAR; PG8_SCHED;
;             PG8_LDA(At, 0, 1); PG8_STAGE(PG8_SB(0, 0), b2, voffB); PG8_STAGE(PG8_SB(0, 1), b2 + hstep, voffB); PG8_STAGE(PG8_SA(0, 0), a2, voffA);
;             PG8_WAIT_V(8); PG8_WAIT_L(0); PG8_BAR; PG8_MMA(1, 0, At, B0); PG8_MMA(1, 1, At, B1); PG8_BAR; PG8_SCHED;
.LBB0_516:
	ds_read_b128 v[146:149], v162
	ds_read_b128 v[150:153], v162 offset:1024
	ds_read_b128 v[154:157], v162 offset:2048
	ds_read_b128 v[168:171], v162 offset:3072
	ds_read_b128 v[172:175], v163
	ds_read_b128 v[176:179], v163 offset:1024
	ds_read_b128 v[180:183], v163 offset:2048
	ds_read_b128 v[186:189], v163 offset:3072
	s_add_u32 s28, s26, 0xfff50080
	s_addc_u32 s29, s27, -1
	s_cmp_eq_u32 s57, 40
	s_cselect_b32 s31, s7, s29
	s_cselect_b32 s30, s6, s28
	s_cselect_b32 s29, s25, s56
	s_cselect_b32 s28, s24, s55
	s_add_i32 m0, s37, 0xc000
	ds_read_b128 v[190:193], v164
	ds_read_b128 v[194:197], v164 offset:1024
	ds_read_b128 v[198:201], v164 offset:2048
	ds_read_b128 v[202:205], v164 offset:3072
	ds_read_b128 v[206:209], v164 offset:4096
	ds_read_b128 v[210:213], v164 offset:5120
	ds_read_b128 v[214:217], v164 offset:6144
	ds_read_b128 v[218:221], v164 offset:7168
	global_load_lds_dwordx4 v136, s[26:27]
	s_add_i32 m0, s37, 0xe000
	s_nop 0
	global_load_lds_dwordx4 v138, s[26:27]
	s_waitcnt vmcnt(8)
	s_waitcnt lgkmcnt(0)
	s_barrier
	s_setprio 1
	s_waitcnt lgkmcnt(0)
	v_mfma_f32_16x16x32_bf16 v[124:127], v[146:149], v[190:193], v[124:127]
	v_mfma_f32_16x16x32_bf16 v[120:123], v[154:157], v[190:193], v[120:123]
	v_mfma_f32_16x16x32_bf16 v[108:111], v[146:149], v[198:201], v[108:111]
	v_mfma_f32_16x16x32_bf16 v[104:107], v[154:157], v[198:201], v[104:107]
	v_mfma_f32_16x16x32_bf16 v[92:95], v[146:149], v[206:209], v[92:95]
	v_mfma_f32_16x16x32_bf16 v[88:91], v[154:157], v[206:209], v[88:91]
	v_mfma_f32_16x16x32_bf16 v[76:79], v[146:149], v[214:217], v[76:79]
	v_mfma_f32_16x16x32_bf16 v[72:75], v[154:157], v[214:217], v[72:75]
	v_mfma_f32_16x16x32_bf16 v[124:127], v[150:153], v[194:197], v[124:127]
	v_mfma_f32_16x16x32_bf16 v[120:123], v[168:171], v[194:197], v[120:123]
	v_mfma_f32_16x16x32_bf16 v[108:111], v[150:153], v[202:205], v[108:111]
	v_mfma_f32_16x16x32_bf16 v[104:107], v[168:171], v[202:205], v[104:107]
	v_mfma_f32_16x16x32_bf16 v[92:95], v[150:153], v[210:213], v[92:95]
	v_mfma_f32_16x16x32_bf16 v[88:91], v[168:171], v[210:213], v[88:91]
	v_mfma_f32_16x16x32_bf16 v[76:79], v[150:153], v[218:221], v[76:79]
	v_mfma_f32_16x16x32_bf16 v[72:75], v[168:171], v[218:221], v[72:75]
	s_setprio 0
	s_setprio 1
	v_mfma_f32_16x16x32_bf16 v[116:119], v[172:175], v[190:193], v[116:119]
	v_mfma_f32_16x16x32_bf16 v[112:115], v[180:183], v[190:193], v[112:115]
	v_mfma_f32_16x16x32_bf16 v[100:103], v[172:175], v[198:201], v[100:103]
	v_mfma_f32_16x16x32_bf16 v[96:99], v[180:183], v[198:201], v[96:99]
	v_mfma_f32_16x16x32_bf16 v[84:87], v[172:175], v[206:209], v[84:87]
	v_mfma_f32_16x16x32_bf16 v[80:83], v[180:183], v[206:209], v[80:83]
	v_mfma_f32_16x16x32_bf16 v[68:71], v[172:175], v[214:217], v[68:71]
	v_mfma_f32_16x16x32_bf16 v[64:67], v[180:183], v[214:217], v[64:67]
	v_mfma_f32_16x16x32_bf16 v[116:119], v[176:179], v[194:197], v[116:119]
	v_mfma_f32_16x16x32_bf16 v[112:115], v[186:189], v[194:197], v[112:115]
	v_mfma_f32_16x16x32_bf16 v[100:103], v[176:179], v[202:205], v[100:103]
	v_mfma_f32_16x16x32_bf16 v[96:99], v[186:189], v[202:205], v[96:99]
	v_mfma_f32_16x16x32_bf16 v[84:87], v[176:179], v[210:213], v[84:87]
	v_mfma_f32_16x16x32_bf16 v[80:83], v[186:189], v[210:213], v[80:83]
	v_mfma_f32_16x16x32_bf16 v[68:71], v[176:179], v[218:221], v[68:71]
	v_mfma_f32_16x16x32_bf16 v[64:67], v[186:189], v[218:221], v[64:67]
	s_setprio 0
	s_barrier
	s_add_i32 s58, s48, s36
	s_mov_b32 m0, s58
	ds_read_b128 v[190:193], v164 offset:16384
	ds_read_b128 v[194:197], v164 offset:17408
	ds_read_b128 v[198:201], v164 offset:18432
	ds_read_b128 v[202:205], v164 offset:19456
	ds_read_b128 v[206:209], v164 offset:20480
	ds_read_b128 v[210:213], v164 offset:21504
	ds_read_b128 v[214:217], v164 offset:22528
	ds_read_b128 v[218:221], v164 offset:23552
	global_load_lds_dwordx4 v130, s[28:29]
	s_add_i32 m0, s58, 0x2000
	s_add_u32 s58, s28, 0xb0000
	s_addc_u32 s59, s29, 0
	s_add_i32 s60, s49, s36
	global_load_lds_dwordx4 v134, s[28:29]
	s_mov_b32 m0, s60
	s_nop 0
	global_load_lds_dwordx4 v130, s[58:59]
	s_add_i32 m0, s60, 0x2000
	s_nop 0
	global_load_lds_dwordx4 v134, s[58:59]
	s_mov_b32 m0, s37
	s_nop 0
	global_load_lds_dwordx4 v128, s[30:31]
	s_mov_b32 m0, s38
	s_nop 0
	global_load_lds_dwordx4 v132, s[30:31]
	s_waitcnt vmcnt(8)
	s_waitcnt lgkmcnt(0)
	s_barrier
	s_setprio 1
	s_waitcnt lgkmcnt(0)
	v_mfma_f32_16x16x32_bf16 v[60:63], v[146:149], v[190:193], v[60:63]
	v_mfma_f32_16x16x32_bf16 v[56:59], v[154:157], v[190:193], v[56:59]
	v_mfma_f32_16x16x32_bf16 v[44:47], v[146:149], v[198:201], v[44:47]
	v_mfma_f32_16x16x32_bf16 v[40:43], v[154:157], v[198:201], v[40:43]
	v_mfma_f32_16x16x32_bf16 v[28:31], v[146:149], v[206:209], v[28:31]
	v_mfma_f32_16x16x32_bf16 v[24:27], v[154:157], v[206:209], v[24:27]
	v_mfma_f32_16x16x32_bf16 v[12:15], v[146:149], v[214:217], v[12:15]
	v_mfma_f32_16x16x32_bf16 v[8:11], v[154:157], v[214:217], v[8:11]
	v_mfma_f32_16x16x32_bf16 v[60:63], v[150:153], v[194:197], v[60:63]
	v_mfma_f32_16x16x32_bf16 v[56:59], v[168:171], v[194:197], v[56:59]
	v_mfma_f32_16x16x32_bf16 v[44:47], v[150:153], v[202:205], v[44:47]
	v_mfma_f32_16x16x32_bf16 v[40:43], v[168:171], v[202:205], v[40:43]
	v_mfma_f32_16x16x32_bf16 v[28:31], v[150:153], v[210:213], v[28:31]
	v_mfma_f32_16x16x32_bf16 v[24:27], v[168:171], v[210:213], v[24:27]
	v_mfma_f32_16x16x32_bf16 v[12:15], v[150:153], v[218:221], v[12:15]
	v_mfma_f32_16x16x32_bf16 v[8:11], v[168:171], v[218:221], v[8:11]
	s_setprio 0
	s_setprio 1
	v_mfma_f32_16x16x32_bf16 v[52:55], v[172:175], v[190:193], v[52:55]
	v_mfma_f32_16x16x32_bf16 v[48:51], v[180:183], v[190:193], v[48:51]
	v_mfma_f32_16x16x32_bf16 v[36:39], v[172:175], v[198:201], v[36:39]
	v_mfma_f32_16x16x32_bf16 v[32:35], v[180:183], v[198:201], v[32:35]
	v_mfma_f32_16x16x32_bf16 v[20:23], v[172:175], v[206:209], v[20:23]
	v_mfma_f32_16x16x32_bf16 v[16:19], v[180:183], v[206:209], v[16:19]
	v_mfma_f32_16x16x32_bf16 v[4:7], v[172:175], v[214:217], v[4:7]
	v_mfma_f32_16x16x32_bf16 v[0:3], v[180:183], v[214:217], v[0:3]
	v_mfma_f32_16x16x32_bf16 v[52:55], v[176:179], v[194:197], v[52:55]
	v_mfma_f32_16x16x32_bf16 v[48:51], v[186:189], v[194:197], v[48:51]
	v_mfma_f32_16x16x32_bf16 v[36:39], v[176:179], v[202:205], v[36:39]
	v_mfma_f32_16x16x32_bf16 v[32:35], v[186:189], v[202:205], v[32:35]
	v_mfma_f32_16x16x32_bf16 v[20:23], v[176:179], v[210:213], v[20:23]
	v_mfma_f32_16x16x32_bf16 v[16:19], v[186:189], v[210:213], v[16:19]
	v_mfma_f32_16x16x32_bf16 v[4:7], v[176:179], v[218:221], v[4:7]
	v_mfma_f32_16x16x32_bf16 v[0:3], v[186:189], v[218:221], v[0:3]
	s_setprio 0
	s_barrier
; #define PG8_STAGE(bufoff, gbase, voff) do { _Pragma("unroll") for (int _i = 0; _i < 2; ++_i) \
;         __builtin_amdgcn_global_load_lds((const unsigned*)((const char*)(gbase) + (voff)[_i]), (PG8_LAS unsigned*)(lds + (bufoff) + ldsw + _i * 8192), 16, 0, 0); } while (0)
; #define PG8_LDA(dst, b, h) do { _Pragma("unroll") for (int m = 0; m < 4; ++m) _Pragma("unroll") for (int k = 0; k < 2; ++k) dst[m][k] = *(const PG8_LAS bf16x8*)(lds + PG8_SA(b, h) + aoff + m * 2048 + k * 1024); } while (0)
; #define PG8_LDB(dst, b, h) do { _Pragma("unroll") for (int n = 0; n < 2; ++n) _Pragma("unroll") for (int k = 0; k < 2; ++k) dst[n][k] = *(const PG8_LAS bf16x8*)(lds + PG8_SB(b, h) + boff + n * 2048 + k * 1024); } while (0)
; #define PG8_MMA(ai, bj, At, Bt) do { __builtin_amdgcn_s_setprio(1); _Pragma("unroll") for (int m = 0; m < 4; ++m) _Pragma("unroll") for (int n = 0; n < 2; ++n) _Pragma("unroll") for (int k = 0; k < 2; ++k) \
;         acc[ai][bj][m][n] = __builtin_amdgcn_mfma_f32_16x16x32_bf16(Bt[n][k], At[m][k], acc[ai][bj][m][n], 0, 0, 0); __builtin_amdgcn_s_setprio(0); } while (0)
; #define PG8_WAIT_V(n) asm volatile("s_waitcnt vmcnt(" #n ")" ::: "memory")
; #define PG8_WAIT_L(n) asm volatile("s_waitcnt lgkmcnt(" #n ")" ::: "memory")
; #define PG8_BAR __builtin_amdgcn_s_barrier()
; #define PG8_SCHED __builtin_amdgcn_sched_barrier(0)
; template <class Epi, class Sched, bool ALIGN_EPI = false, bool SP2 = false>
; __device__ __forceinline__ void gemm_phase(PG8_LAS unsigned char* lds, const Gemm g, const Sched& S, const Epi& E) {
;     ...
;         for (int t = 0; t < nt; t += 2) {
;     ...
;             PG8_LDB(B0, 1, 0); PG8_LDB(B1, 1, 1); PG8_SCHED; PG8_LDA(At, 1, 0); PG8_STAGE(PG8_SA(0, 1), a2 + hstep, voffA);
;             PG8_WAIT_V(8); PG8_WAIT_L(0); PG8_BAR; PG8_MMA(0, 0, At, B0); PG8_MMA(0, 1, At, B1); PG8_BAR; PG8_SCHED;
;             PG8_LDA(At, 1, 1); PG8_STAGE(PG8_SB(1, 0), b3, voffB); PG8_STAGE(PG8_SB(1, 1), b3 + hstep, voffB); PG8_STAGE(PG8_SA(1, 0), a3, voffA);
;             PG8_WAIT_V(8); PG8_WAIT_L(0); PG8_BAR; PG8_MMA(1, 0, At, B0); PG8_MMA(1, 1, At, B1); PG8_BAR; PG8_SCHED;
	ds_read_b128 v[146:149], v165
	ds_read_b128 v[150:153], v165 offset:1024
	ds_read_b128 v[154:157], v165 offset:2048
	ds_read_b128 v[168:171], v165 offset:3072
	ds_read_b128 v[172:175], v166
	ds_read_b128 v[176:179], v166 offset:1024
	ds_read_b128 v[180:183], v166 offset:2048
	ds_read_b128 v[186:189], v166 offset:3072
	s_add_u32 s100, s30, 0xb0000
	s_addc_u32 s101, s31, 0
	s_mov_b32 m0, s39
	ds_read_b128 v[190:193], v164 offset:32768
	ds_read_b128 v[194:197], v164 offset:33792
	ds_read_b128 v[198:201], v164 offset:34816
	ds_read_b128 v[202:205], v164 offset:35840
	ds_read_b128 v[206:209], v164 offset:36864
	ds_read_b128 v[210:213], v164 offset:37888
	ds_read_b128 v[214:217], v164 offset:38912
	ds_read_b128 v[218:221], v164 offset:39936
	global_load_lds_dwordx4 v128, s[100:101]
	s_mov_b32 m0, s40
	s_nop 0
	global_load_lds_dwordx4 v132, s[100:101]
	s_waitcnt vmcnt(8)
	s_waitcnt lgkmcnt(0)
	s_barrier
	s_setprio 1
	s_waitcnt lgkmcnt(0)
	v_mfma_f32_16x16x32_bf16 v[124:127], v[146:149], v[190:193], v[124:127]
	v_mfma_f32_16x16x32_bf16 v[120:123], v[154:157], v[190:193], v[120:123]
	v_mfma_f32_16x16x32_bf16 v[108:111], v[146:149], v[198:201], v[108:111]
	v_mfma_f32_16x16x32_bf16 v[104:107], v[154:157], v[198:201], v[104:107]
	v_mfma_f32_16x16x32_bf16 v[92:95], v[146:149], v[206:209], v[92:95]
	v_mfma_f32_16x16x32_bf16 v[88:91], v[154:157], v[206:209], v[88:91]
	v_mfma_f32_16x16x32_bf16 v[76:79], v[146:149], v[214:217], v[76:79]
	v_mfma_f32_16x16x32_bf16 v[72:75], v[154:157], v[214:217], v[72:75]
	v_mfma_f32_16x16x32_bf16 v[124:127], v[150:153], v[194:197], v[124:127]
	v_mfma_f32_16x16x32_bf16 v[120:123], v[168:171], v[194:197], v[120:123]
	v_mfma_f32_16x16x32_bf16 v[108:111], v[150:153], v[202:205], v[108:111]
	v_mfma_f32_16x16x32_bf16 v[104:107], v[168:171], v[202:205], v[104:107]
	v_mfma_f32_16x16x32_bf16 v[92:95], v[150:153], v[210:213], v[92:95]
	v_mfma_f32_16x16x32_bf16 v[88:91], v[168:171], v[210:213], v[88:91]
	v_mfma_f32_16x16x32_bf16 v[76:79], v[150:153], v[218:221], v[76:79]
	v_mfma_f32_16x16x32_bf16 v[72:75], v[168:171], v[218:221], v[72:75]
	s_setprio 0
	s_setprio 1
	v_mfma_f32_16x16x32_bf16 v[116:119], v[172:175], v[190:193], v[116:119]
	v_mfma_f32_16x16x32_bf16 v[112:115], v[180:183], v[190:193], v[112:115]
	v_mfma_f32_16x16x32_bf16 v[100:103], v[172:175], v[198:201], v[100:103]
	v_mfma_f32_16x16x32_bf16 v[96:99], v[180:183], v[198:201], v[96:99]
	v_mfma_f32_16x16x32_bf16 v[84:87], v[172:175], v[206:209], v[84:87]
	v_mfma_f32_16x16x32_bf16 v[80:83], v[180:183], v[206:209], v[80:83]
	v_mfma_f32_16x16x32_bf16 v[68:71], v[172:175], v[214:217], v[68:71]
	v_mfma_f32_16x16x32_bf16 v[64:67], v[180:183], v[214:217], v[64:67]
	v_mfma_f32_16x16x32_bf16 v[116:119], v[176:179], v[194:197], v[116:119]
	v_mfma_f32_16x16x32_bf16 v[112:115], v[186:189], v[194:197], v[112:115]
	v_mfma_f32_16x16x32_bf16 v[100:103], v[176:179], v[202:205], v[100:103]
	v_mfma_f32_16x16x32_bf16 v[96:99], v[186:189], v[202:205], v[96:99]
	v_mfma_f32_16x16x32_bf16 v[84:87], v[176:179], v[210:213], v[84:87]
	v_mfma_f32_16x16x32_bf16 v[80:83], v[186:189], v[210:213], v[80:83]
	v_mfma_f32_16x16x32_bf16 v[68:71], v[176:179], v[218:221], v[68:71]
	v_mfma_f32_16x16x32_bf16 v[64:67], v[186:189], v[218:221], v[64:67]
	s_setprio 0
	s_barrier
	s_add_u32 s100, s28, 0x80
	s_addc_u32 s101, s29, 0
	s_add_i32 s98, s50, s36
	s_mov_b32 m0, s98
	ds_read_b128 v[190:193], v164 offset:49152
	ds_read_b128 v[194:197], v164 offset:50176
	ds_read_b128 v[198:201], v164 offset:51200
	ds_read_b128 v[202:205], v164 offset:52224
	ds_read_b128 v[206:209], v164 offset:53248
	ds_read_b128 v[210:213], v164 offset:54272
	ds_read_b128 v[214:217], v164 offset:55296
	ds_read_b128 v[218:221], v164 offset:56320
	global_load_lds_dwordx4 v130, s[100:101]
	s_add_i32 m0, s98, 0x2000
	s_add_u32 s28, s28, 0xb0080
	s_addc_u32 s29, s29, 0
	s_add_i32 s98, s51, s36
	global_load_lds_dwordx4 v134, s[100:101]
	s_mov_b32 m0, s98
	s_nop 0
	global_load_lds_dwordx4 v130, s[28:29]
	s_add_i32 m0, s98, 0x2000
	s_nop 0
	global_load_lds_dwordx4 v134, s[28:29]
	s_add_u32 s100, s30, 0x80
	s_addc_u32 s101, s31, 0
	s_mov_b32 m0, s43
	s_nop 0
	global_load_lds_dwordx4 v128, s[100:101]
	s_mov_b32 m0, s44
	s_nop 0
	global_load_lds_dwordx4 v132, s[100:101]
	s_waitcnt vmcnt(8)
	s_waitcnt lgkmcnt(0)
	s_barrier
	s_setprio 1
	s_waitcnt lgkmcnt(0)
	v_mfma_f32_16x16x32_bf16 v[60:63], v[146:149], v[190:193], v[60:63]
	v_mfma_f32_16x16x32_bf16 v[56:59], v[154:157], v[190:193], v[56:59]
	v_mfma_f32_16x16x32_bf16 v[44:47], v[146:149], v[198:201], v[44:47]
	v_mfma_f32_16x16x32_bf16 v[40:43], v[154:157], v[198:201], v[40:43]
	v_mfma_f32_16x16x32_bf16 v[28:31], v[146:149], v[206:209], v[28:31]
	v_mfma_f32_16x16x32_bf16 v[24:27], v[154:157], v[206:209], v[24:27]
	v_mfma_f32_16x16x32_bf16 v[12:15], v[146:149], v[214:217], v[12:15]
	v_mfma_f32_16x16x32_bf16 v[8:11], v[154:157], v[214:217], v[8:11]
	v_mfma_f32_16x16x32_bf16 v[60:63], v[150:153], v[194:197], v[60:63]
	v_mfma_f32_16x16x32_bf16 v[56:59], v[168:171], v[194:197], v[56:59]
	v_mfma_f32_16x16x32_bf16 v[44:47], v[150:153], v[202:205], v[44:47]
	v_mfma_f32_16x16x32_bf16 v[40:43], v[168:171], v[202:205], v[40:43]
	v_mfma_f32_16x16x32_bf16 v[28:31], v[150:153], v[210:213], v[28:31]
	v_mfma_f32_16x16x32_bf16 v[24:27], v[168:171], v[210:213], v[24:27]
	v_mfma_f32_16x16x32_bf16 v[12:15], v[150:153], v[218:221], v[12:15]
	v_mfma_f32_16x16x32_bf16 v[8:11], v[168:171], v[218:221], v[8:11]
	s_setprio 0
	s_setprio 1
	v_mfma_f32_16x16x32_bf16 v[52:55], v[172:175], v[190:193], v[52:55]
	v_mfma_f32_16x16x32_bf16 v[48:51], v[180:183], v[190:193], v[48:51]
	v_mfma_f32_16x16x32_bf16 v[36:39], v[172:175], v[198:201], v[36:39]
	v_mfma_f32_16x16x32_bf16 v[32:35], v[180:183], v[198:201], v[32:35]
	v_mfma_f32_16x16x32_bf16 v[20:23], v[172:175], v[206:209], v[20:23]
	v_mfma_f32_16x16x32_bf16 v[16:19], v[180:183], v[206:209], v[16:19]
	v_mfma_f32_16x16x32_bf16 v[4:7], v[172:175], v[214:217], v[4:7]
	v_mfma_f32_16x16x32_bf16 v[0:3], v[180:183], v[214:217], v[0:3]
	v_mfma_f32_16x16x32_bf16 v[52:55], v[176:179], v[194:197], v[52:55]
	v_mfma_f32_16x16x32_bf16 v[48:51], v[186:189], v[194:197], v[48:51]
	v_mfma_f32_16x16x32_bf16 v[36:39], v[176:179], v[202:205], v[36:39]
	v_mfma_f32_16x16x32_bf16 v[32:35], v[186:189], v[202:205], v[32:35]
	v_mfma_f32_16x16x32_bf16 v[20:23], v[176:179], v[210:213], v[20:23]
	v_mfma_f32_16x16x32_bf16 v[16:19], v[186:189], v[210:213], v[16:19]
	v_mfma_f32_16x16x32_bf16 v[4:7], v[176:179], v[218:221], v[4:7]
	v_mfma_f32_16x16x32_bf16 v[0:3], v[186:189], v[218:221], v[0:3]
	s_setprio 0
	s_barrier
	s_add_i32 s57, s57, 2
	s_add_u32 s26, s26, 0x100
	s_addc_u32 s27, s27, 0
	s_add_u32 s55, s55, 0x100
	s_addc_u32 s56, s56, 0
	s_cmp_gt_u32 s57, 41
	s_cbranch_scc0 .LBB0_516
	s_nop 0
	s_nop 0
	s_nop 0
	s_nop 0
	s_nop 0
	s_nop 0
	s_nop 0
	s_nop 0
	s_nop 0
	s_nop 0
	s_nop 0
	s_nop 0
	s_nop 0
	s_nop 0
	s_nop 0
	s_nop 0
	s_nop 0
	s_nop 0
	s_nop 0
	s_nop 0
	s_nop 0
	s_nop 0
	s_nop 0
	s_nop 0
	s_nop 0
	s_and_b64 vcc, exec, s[14:15]
	s_cbranch_vccz .LBB0_519
	s_barrier

; #define PG8_STAGE(bufoff, gbase, voff) do { _Pragma("unroll") for (int _i = 0; _i < 2; ++_i) \
;         __builtin_amdgcn_global_load_lds((const unsigned*)((const char*)(gbase) + (voff)[_i]), (PG8_LAS unsigned*)(lds + (bufoff) + ldsw + _i * 8192), 16, 0, 0); } while (0)
; #define PG8_LDA(dst, b, h) do { _Pragma("unroll") for (int m = 0; m < 4; ++m) _Pragma("unroll") for (int k = 0; k < 2; ++k) dst[m][k] = *(const PG8_LAS bf16x8*)(lds + PG8_SA(b, h) + aoff + m * 2048 + k * 1024); } while (0)
; #define PG8_LDB(dst, b, h) do { _Pragma("unroll") for (int n = 0; n < 2; ++n) _Pragma("unroll") for (int k = 0; k < 2; ++k) dst[n][k] = *(const PG8_LAS bf16x8*)(lds + PG8_SB(b, h) + boff + n * 2048 + k * 1024); } while (0)
; #define PG8_MMA(ai, bj, At, Bt) do { __builtin_amdgcn_s_setprio(1); _Pragma("unroll") for (int m = 0; m < 4; ++m) _Pragma("unroll") for (int n = 0; n < 2; ++n) _Pragma("unroll") for (int k = 0; k < 2; ++k) \
;         acc[ai][bj][m][n] = __builtin_amdgcn_mfma_f32_16x16x32_bf16(Bt[n][k], At[m][k], acc[ai][bj][m][n], 0, 0, 0); __builtin_amdgcn_s_setprio(0); } while (0)
; #define PG8_WAIT_V(n) asm volatile("s_waitcnt vmcnt(" #n ")" ::: "memory")
; #define PG8_WAIT_L(n) asm volatile("s_waitcnt lgkmcnt(" #n ")" ::: "memory")
; template <class Epi, class Sched, bool ALIGN_EPI = false, bool SP2 = false>
; __device__ __forceinline__ void gemm_phase(PG8_LAS unsigned char* lds, const Gemm g, const Sched& S, const Epi& E) {
;     ...
;             const bool last = (t == nt - 2);
;             const char* a1 = cA + (size_t)(t + 1) * kstep;
;             const char* a2 = last ? nA : cA + (size_t)(t + 2) * kstep; const char* b2 = last ? nB : cB + (size_t)(t + 2) * kstep;
;             const char* a3 = a2 + kstep; const char* b3 = b2 + kstep;
;             if (last && has_next) S.a_ready(nxt);
;             if constexpr (SP2) {
;             PG8_LDB(B0, 0, 0); PG8_LDB(B1, 0, 1); PG8_SCHED; PG8_LDA(At, 0, 0); PG8_STAGE(PG8_SA(1, 1), a1 + hstep, voffA);
;             PG8_WAIT_V(8); PG8_WAIT_L(0); PG8_BAR; PG8_MMA(0, 0, At, B0); PG8_MMA(0, 1, At, B1); PG8_BAR; PG8_SCHED;
;             PG8_LDA(At, 0, 1); PG8_STAGE(PG8_SB(0, 0), b2, voffB); PG8_STAGE(PG8_SB(0, 1), b2 + hstep, voffB); PG8_STAGE(PG8_SA(0, 0), a2, voffA);
;             PG8_WAIT_V(8); PG8_WAIT_L(0); PG8_BAR; PG8_MMA(1, 0, At, B0); PG8_MMA(1, 1, At, B1); PG8_BAR; PG8_SCHED;
.LBB0_647:
	ds_read_b128 v[148:151], v154
	ds_read_b128 v[160:163], v154 offset:1024
	ds_read_b128 v[164:167], v154 offset:2048
	ds_read_b128 v[168:171], v154 offset:3072
	ds_read_b128 v[172:175], v155
	ds_read_b128 v[176:179], v155 offset:1024
	ds_read_b128 v[180:183], v155 offset:2048
	ds_read_b128 v[186:189], v155 offset:3072
	s_add_u32 s30, s28, 0xfffc0080
	s_addc_u32 s31, s29, -1
	s_cmp_eq_u32 s55, 12
	s_cselect_b32 s35, s19, s31
	s_cselect_b32 s34, s25, s30
	s_cselect_b32 s31, s15, s54
	s_cselect_b32 s30, s27, s53
	s_add_i32 m0, s38, 0xc000
	ds_read_b128 v[190:193], v156
	ds_read_b128 v[194:197], v156 offset:1024
	ds_read_b128 v[198:201], v156 offset:2048
	ds_read_b128 v[202:205], v156 offset:3072
	ds_read_b128 v[206:209], v156 offset:4096
	ds_read_b128 v[210:213], v156 offset:5120
	ds_read_b128 v[214:217], v156 offset:6144
	ds_read_b128 v[218:221], v156 offset:7168
	global_load_lds_dwordx4 v138, s[28:29]
	s_add_i32 m0, s38, 0xe000
	s_nop 0
	global_load_lds_dwordx4 v140, s[28:29]
	s_waitcnt vmcnt(8)
	s_waitcnt lgkmcnt(0)
	s_barrier
	s_setprio 1
	s_waitcnt lgkmcnt(0)
	v_mfma_f32_16x16x32_bf16 v[124:127], v[148:151], v[190:193], v[124:127]
	v_mfma_f32_16x16x32_bf16 v[120:123], v[164:167], v[190:193], v[120:123]
	v_mfma_f32_16x16x32_bf16 v[116:119], v[148:151], v[198:201], v[116:119]
	v_mfma_f32_16x16x32_bf16 v[112:115], v[164:167], v[198:201], v[112:115]
	v_mfma_f32_16x16x32_bf16 v[100:103], v[148:151], v[206:209], v[100:103]
	v_mfma_f32_16x16x32_bf16 v[96:99], v[164:167], v[206:209], v[96:99]
	v_mfma_f32_16x16x32_bf16 v[84:87], v[148:151], v[214:217], v[84:87]
	v_mfma_f32_16x16x32_bf16 v[80:83], v[164:167], v[214:217], v[80:83]
	v_mfma_f32_16x16x32_bf16 v[124:127], v[160:163], v[194:197], v[124:127]
	v_mfma_f32_16x16x32_bf16 v[120:123], v[168:171], v[194:197], v[120:123]
	v_mfma_f32_16x16x32_bf16 v[116:119], v[160:163], v[202:205], v[116:119]
	v_mfma_f32_16x16x32_bf16 v[112:115], v[168:171], v[202:205], v[112:115]
	v_mfma_f32_16x16x32_bf16 v[100:103], v[160:163], v[210:213], v[100:103]
	v_mfma_f32_16x16x32_bf16 v[96:99], v[168:171], v[210:213], v[96:99]
	v_mfma_f32_16x16x32_bf16 v[84:87], v[160:163], v[218:221], v[84:87]
	v_mfma_f32_16x16x32_bf16 v[80:83], v[168:171], v[218:221], v[80:83]
	s_setprio 0
	s_setprio 1
	v_mfma_f32_16x16x32_bf16 v[108:111], v[172:175], v[190:193], v[108:111]
	v_mfma_f32_16x16x32_bf16 v[104:107], v[180:183], v[190:193], v[104:107]
	v_mfma_f32_16x16x32_bf16 v[92:95], v[172:175], v[198:201], v[92:95]
	v_mfma_f32_16x16x32_bf16 v[88:91], v[180:183], v[198:201], v[88:91]
	v_mfma_f32_16x16x32_bf16 v[76:79], v[172:175], v[206:209], v[76:79]
	v_mfma_f32_16x16x32_bf16 v[72:75], v[180:183], v[206:209], v[72:75]
	v_mfma_f32_16x16x32_bf16 v[68:71], v[172:175], v[214:217], v[68:71]
	v_mfma_f32_16x16x32_bf16 v[64:67], v[180:183], v[214:217], v[64:67]
	v_mfma_f32_16x16x32_bf16 v[108:111], v[176:179], v[194:197], v[108:111]
	v_mfma_f32_16x16x32_bf16 v[104:107], v[186:189], v[194:197], v[104:107]
	v_mfma_f32_16x16x32_bf16 v[92:95], v[176:179], v[202:205], v[92:95]
	v_mfma_f32_16x16x32_bf16 v[88:91], v[186:189], v[202:205], v[88:91]
	v_mfma_f32_16x16x32_bf16 v[76:79], v[176:179], v[210:213], v[76:79]
	v_mfma_f32_16x16x32_bf16 v[72:75], v[186:189], v[210:213], v[72:75]
	v_mfma_f32_16x16x32_bf16 v[68:71], v[176:179], v[218:221], v[68:71]
	v_mfma_f32_16x16x32_bf16 v[64:67], v[186:189], v[218:221], v[64:67]
	s_setprio 0
	s_barrier
	s_add_i32 s56, s48, s37
	s_mov_b32 m0, s56
	ds_read_b128 v[190:193], v156 offset:16384
	ds_read_b128 v[194:197], v156 offset:17408
	ds_read_b128 v[198:201], v156 offset:18432
	ds_read_b128 v[202:205], v156 offset:19456
	ds_read_b128 v[206:209], v156 offset:20480
	ds_read_b128 v[210:213], v156 offset:21504
	ds_read_b128 v[214:217], v156 offset:22528
	ds_read_b128 v[218:221], v156 offset:23552
	global_load_lds_dwordx4 v130, s[30:31]
	s_add_i32 m0, s56, 0x2000
	s_add_u32 s56, s30, 0x40000
	s_addc_u32 s57, s31, 0
	s_add_i32 s58, s49, s37
	global_load_lds_dwordx4 v134, s[30:31]
	s_mov_b32 m0, s58
	s_nop 0
	global_load_lds_dwordx4 v130, s[56:57]
	s_add_i32 m0, s58, 0x2000
	s_nop 0
	global_load_lds_dwordx4 v134, s[56:57]
	s_mov_b32 m0, s38
	s_nop 0
	global_load_lds_dwordx4 v128, s[34:35]
	s_mov_b32 m0, s39
	s_nop 0
	global_load_lds_dwordx4 v132, s[34:35]
	s_waitcnt vmcnt(8)
	s_waitcnt lgkmcnt(0)
	s_barrier
	s_setprio 1
	s_waitcnt lgkmcnt(0)
	v_mfma_f32_16x16x32_bf16 v[60:63], v[148:151], v[190:193], v[60:63]
	v_mfma_f32_16x16x32_bf16 v[56:59], v[164:167], v[190:193], v[56:59]
	v_mfma_f32_16x16x32_bf16 v[52:55], v[148:151], v[198:201], v[52:55]
	v_mfma_f32_16x16x32_bf16 v[48:51], v[164:167], v[198:201], v[48:51]
	v_mfma_f32_16x16x32_bf16 v[36:39], v[148:151], v[206:209], v[36:39]
	v_mfma_f32_16x16x32_bf16 v[32:35], v[164:167], v[206:209], v[32:35]
	v_mfma_f32_16x16x32_bf16 v[20:23], v[148:151], v[214:217], v[20:23]
	v_mfma_f32_16x16x32_bf16 v[16:19], v[164:167], v[214:217], v[16:19]
	v_mfma_f32_16x16x32_bf16 v[60:63], v[160:163], v[194:197], v[60:63]
	v_mfma_f32_16x16x32_bf16 v[56:59], v[168:171], v[194:197], v[56:59]
	v_mfma_f32_16x16x32_bf16 v[52:55], v[160:163], v[202:205], v[52:55]
	v_mfma_f32_16x16x32_bf16 v[48:51], v[168:171], v[202:205], v[48:51]
	v_mfma_f32_16x16x32_bf16 v[36:39], v[160:163], v[210:213], v[36:39]
	v_mfma_f32_16x16x32_bf16 v[32:35], v[168:171], v[210:213], v[32:35]
	v_mfma_f32_16x16x32_bf16 v[20:23], v[160:163], v[218:221], v[20:23]
	v_mfma_f32_16x16x32_bf16 v[16:19], v[168:171], v[218:221], v[16:19]
	s_setprio 0
	s_setprio 1
	v_mfma_f32_16x16x32_bf16 v[44:47], v[172:175], v[190:193], v[44:47]
	v_mfma_f32_16x16x32_bf16 v[40:43], v[180:183], v[190:193], v[40:43]
	v_mfma_f32_16x16x32_bf16 v[28:31], v[172:175], v[198:201], v[28:31]
	v_mfma_f32_16x16x32_bf16 v[24:27], v[180:183], v[198:201], v[24:27]
	v_mfma_f32_16x16x32_bf16 v[12:15], v[172:175], v[206:209], v[12:15]
	v_mfma_f32_16x16x32_bf16 v[8:11], v[180:183], v[206:209], v[8:11]
	v_mfma_f32_16x16x32_bf16 v[4:7], v[172:175], v[214:217], v[4:7]
	v_mfma_f32_16x16x32_bf16 v[0:3], v[180:183], v[214:217], v[0:3]
	v_mfma_f32_16x16x32_bf16 v[44:47], v[176:179], v[194:197], v[44:47]
	v_mfma_f32_16x16x32_bf16 v[40:43], v[186:189], v[194:197], v[40:43]
	v_mfma_f32_16x16x32_bf16 v[28:31], v[176:179], v[202:205], v[28:31]
	v_mfma_f32_16x16x32_bf16 v[24:27], v[186:189], v[202:205], v[24:27]
	v_mfma_f32_16x16x32_bf16 v[12:15], v[176:179], v[210:213], v[12:15]
	v_mfma_f32_16x16x32_bf16 v[8:11], v[186:189], v[210:213], v[8:11]
	v_mfma_f32_16x16x32_bf16 v[4:7], v[176:179], v[218:221], v[4:7]
	v_mfma_f32_16x16x32_bf16 v[0:3], v[186:189], v[218:221], v[0:3]
	s_setprio 0
	s_barrier
; #define PG8_STAGE(bufoff, gbase, voff) do { _Pragma("unroll") for (int _i = 0; _i < 2; ++_i) \
;         __builtin_amdgcn_global_load_lds((const unsigned*)((const char*)(gbase) + (voff)[_i]), (PG8_LAS unsigned*)(lds + (bufoff) + ldsw + _i * 8192), 16, 0, 0); } while (0)
; #define PG8_LDA(dst, b, h) do { _Pragma("unroll") for (int m = 0; m < 4; ++m) _Pragma("unroll") for (int k = 0; k < 2; ++k) dst[m][k] = *(const PG8_LAS bf16x8*)(lds + PG8_SA(b, h) + aoff + m * 2048 + k * 1024); } while (0)
; #define PG8_LDB(dst, b, h) do { _Pragma("unroll") for (int n = 0; n < 2; ++n) _Pragma("unroll") for (int k = 0; k < 2; ++k) dst[n][k] = *(const PG8_LAS bf16x8*)(lds + PG8_SB(b, h) + boff + n * 2048 + k * 1024); } while (0)
; #define PG8_MMA(ai, bj, At, Bt) do { __builtin_amdgcn_s_setprio(1); _Pragma("unroll") for (int m = 0; m < 4; ++m) _Pragma("unroll") for (int n = 0; n < 2; ++n) _Pragma("unroll") for (int k = 0; k < 2; ++k) \
;         acc[ai][bj][m][n] = __builtin_amdgcn_mfma_f32_16x16x32_bf16(Bt[n][k], At[m][k], acc[ai][bj][m][n], 0, 0, 0); __builtin_amdgcn_s_setprio(0); } while (0)
; #define PG8_WAIT_V(n) asm volatile("s_waitcnt vmcnt(" #n ")" ::: "memory")
; #define PG8_WAIT_L(n) asm volatile("s_waitcnt lgkmcnt(" #n ")" ::: "memory")
; #define PG8_BAR __builtin_amdgcn_s_barrier()
; #define PG8_SCHED __builtin_amdgcn_sched_barrier(0)
; template <class Epi, class Sched, bool ALIGN_EPI = false, bool SP2 = false>
; __device__ __forceinline__ void gemm_phase(PG8_LAS unsigned char* lds, const Gemm g, const Sched& S, const Epi& E) {
;     ...
;         for (int t = 0; t < nt; t += 2) {
;     ...
;             PG8_LDB(B0, 1, 0); PG8_LDB(B1, 1, 1); PG8_SCHED; PG8_LDA(At, 1, 0); PG8_STAGE(PG8_SA(0, 1), a2 + hstep, voffA);
;             PG8_WAIT_V(8); PG8_WAIT_L(0); PG8_BAR; PG8_MMA(0, 0, At, B0); PG8_MMA(0, 1, At, B1); PG8_BAR; PG8_SCHED;
;             PG8_LDA(At, 1, 1); PG8_STAGE(PG8_SB(1, 0), b3, voffB); PG8_STAGE(PG8_SB(1, 1), b3 + hstep, voffB); PG8_STAGE(PG8_SA(1, 0), a3, voffA);
;             PG8_WAIT_V(8); PG8_WAIT_L(0); PG8_BAR; PG8_MMA(1, 0, At, B0); PG8_MMA(1, 1, At, B1); PG8_BAR; PG8_SCHED;
	ds_read_b128 v[148:151], v157
	ds_read_b128 v[160:163], v157 offset:1024
	ds_read_b128 v[164:167], v157 offset:2048
	ds_read_b128 v[168:171], v157 offset:3072
	ds_read_b128 v[172:175], v158
	ds_read_b128 v[176:179], v158 offset:1024
	ds_read_b128 v[180:183], v158 offset:2048
	ds_read_b128 v[186:189], v158 offset:3072
	s_add_u32 s100, s34, 0x40000
	s_addc_u32 s101, s35, 0
	s_mov_b32 m0, s33
	ds_read_b128 v[190:193], v156 offset:32768
	ds_read_b128 v[194:197], v156 offset:33792
	ds_read_b128 v[198:201], v156 offset:34816
	ds_read_b128 v[202:205], v156 offset:35840
	ds_read_b128 v[206:209], v156 offset:36864
	ds_read_b128 v[210:213], v156 offset:37888
	ds_read_b128 v[214:217], v156 offset:38912
	ds_read_b128 v[218:221], v156 offset:39936
	global_load_lds_dwordx4 v128, s[100:101]
	s_mov_b32 m0, s40
	s_nop 0
	global_load_lds_dwordx4 v132, s[100:101]
	s_waitcnt vmcnt(8)
	s_waitcnt lgkmcnt(0)
	s_barrier
	s_setprio 1
	s_waitcnt lgkmcnt(0)
	v_mfma_f32_16x16x32_bf16 v[124:127], v[148:151], v[190:193], v[124:127]
	v_mfma_f32_16x16x32_bf16 v[120:123], v[164:167], v[190:193], v[120:123]
	v_mfma_f32_16x16x32_bf16 v[116:119], v[148:151], v[198:201], v[116:119]
	v_mfma_f32_16x16x32_bf16 v[112:115], v[164:167], v[198:201], v[112:115]
	v_mfma_f32_16x16x32_bf16 v[100:103], v[148:151], v[206:209], v[100:103]
	v_mfma_f32_16x16x32_bf16 v[96:99], v[164:167], v[206:209], v[96:99]
	v_mfma_f32_16x16x32_bf16 v[84:87], v[148:151], v[214:217], v[84:87]
	v_mfma_f32_16x16x32_bf16 v[80:83], v[164:167], v[214:217], v[80:83]
	v_mfma_f32_16x16x32_bf16 v[124:127], v[160:163], v[194:197], v[124:127]
	v_mfma_f32_16x16x32_bf16 v[120:123], v[168:171], v[194:197], v[120:123]
	v_mfma_f32_16x16x32_bf16 v[116:119], v[160:163], v[202:205], v[116:119]
	v_mfma_f32_16x16x32_bf16 v[112:115], v[168:171], v[202:205], v[112:115]
	v_mfma_f32_16x16x32_bf16 v[100:103], v[160:163], v[210:213], v[100:103]
	v_mfma_f32_16x16x32_bf16 v[96:99], v[168:171], v[210:213], v[96:99]
	v_mfma_f32_16x16x32_bf16 v[84:87], v[160:163], v[218:221], v[84:87]
	v_mfma_f32_16x16x32_bf16 v[80:83], v[168:171], v[218:221], v[80:83]
	s_setprio 0
	s_setprio 1
	v_mfma_f32_16x16x32_bf16 v[108:111], v[172:175], v[190:193], v[108:111]
	v_mfma_f32_16x16x32_bf16 v[104:107], v[180:183], v[190:193], v[104:107]
	v_mfma_f32_16x16x32_bf16 v[92:95], v[172:175], v[198:201], v[92:95]
	v_mfma_f32_16x16x32_bf16 v[88:91], v[180:183], v[198:201], v[88:91]
	v_mfma_f32_16x16x32_bf16 v[76:79], v[172:175], v[206:209], v[76:79]
	v_mfma_f32_16x16x32_bf16 v[72:75], v[180:183], v[206:209], v[72:75]
	v_mfma_f32_16x16x32_bf16 v[68:71], v[172:175], v[214:217], v[68:71]
	v_mfma_f32_16x16x32_bf16 v[64:67], v[180:183], v[214:217], v[64:67]
	v_mfma_f32_16x16x32_bf16 v[108:111], v[176:179], v[194:197], v[108:111]
	v_mfma_f32_16x16x32_bf16 v[104:107], v[186:189], v[194:197], v[104:107]
	v_mfma_f32_16x16x32_bf16 v[92:95], v[176:179], v[202:205], v[92:95]
	v_mfma_f32_16x16x32_bf16 v[88:91], v[186:189], v[202:205], v[88:91]
	v_mfma_f32_16x16x32_bf16 v[76:79], v[176:179], v[210:213], v[76:79]
	v_mfma_f32_16x16x32_bf16 v[72:75], v[186:189], v[210:213], v[72:75]
	v_mfma_f32_16x16x32_bf16 v[68:71], v[176:179], v[218:221], v[68:71]
	v_mfma_f32_16x16x32_bf16 v[64:67], v[186:189], v[218:221], v[64:67]
	s_setprio 0
	s_barrier
	s_add_u32 s100, s30, 0x80
	s_addc_u32 s101, s31, 0
	s_add_i32 s98, s51, s37
	s_mov_b32 m0, s98
	ds_read_b128 v[190:193], v156 offset:49152
	ds_read_b128 v[194:197], v156 offset:50176
	ds_read_b128 v[198:201], v156 offset:51200
	ds_read_b128 v[202:205], v156 offset:52224
	ds_read_b128 v[206:209], v156 offset:53248
	ds_read_b128 v[210:213], v156 offset:54272
	ds_read_b128 v[214:217], v156 offset:55296
	ds_read_b128 v[218:221], v156 offset:56320
	global_load_lds_dwordx4 v130, s[100:101]
	s_add_i32 m0, s98, 0x2000
	s_add_u32 s30, s30, 0x40080
	s_addc_u32 s31, s31, 0
	s_add_i32 s98, s52, s37
	global_load_lds_dwordx4 v134, s[100:101]
	s_mov_b32 m0, s98
	s_nop 0
	global_load_lds_dwordx4 v130, s[30:31]
	s_add_i32 m0, s98, 0x2000
	s_nop 0
	global_load_lds_dwordx4 v134, s[30:31]
	s_add_u32 s100, s34, 0x80
	s_addc_u32 s101, s35, 0
	s_mov_b32 m0, s41
	s_nop 0
	global_load_lds_dwordx4 v128, s[100:101]
	s_mov_b32 m0, s42
	s_nop 0
	global_load_lds_dwordx4 v132, s[100:101]
	s_waitcnt vmcnt(8)
	s_waitcnt lgkmcnt(0)
	s_barrier
	s_setprio 1
	s_waitcnt lgkmcnt(0)
	v_mfma_f32_16x16x32_bf16 v[60:63], v[148:151], v[190:193], v[60:63]
	v_mfma_f32_16x16x32_bf16 v[56:59], v[164:167], v[190:193], v[56:59]
	v_mfma_f32_16x16x32_bf16 v[52:55], v[148:151], v[198:201], v[52:55]
	v_mfma_f32_16x16x32_bf16 v[48:51], v[164:167], v[198:201], v[48:51]
	v_mfma_f32_16x16x32_bf16 v[36:39], v[148:151], v[206:209], v[36:39]
	v_mfma_f32_16x16x32_bf16 v[32:35], v[164:167], v[206:209], v[32:35]
	v_mfma_f32_16x16x32_bf16 v[20:23], v[148:151], v[214:217], v[20:23]
	v_mfma_f32_16x16x32_bf16 v[16:19], v[164:167], v[214:217], v[16:19]
	v_mfma_f32_16x16x32_bf16 v[60:63], v[160:163], v[194:197], v[60:63]
	v_mfma_f32_16x16x32_bf16 v[56:59], v[168:171], v[194:197], v[56:59]
	v_mfma_f32_16x16x32_bf16 v[52:55], v[160:163], v[202:205], v[52:55]
	v_mfma_f32_16x16x32_bf16 v[48:51], v[168:171], v[202:205], v[48:51]
	v_mfma_f32_16x16x32_bf16 v[36:39], v[160:163], v[210:213], v[36:39]
	v_mfma_f32_16x16x32_bf16 v[32:35], v[168:171], v[210:213], v[32:35]
	v_mfma_f32_16x16x32_bf16 v[20:23], v[160:163], v[218:221], v[20:23]
	v_mfma_f32_16x16x32_bf16 v[16:19], v[168:171], v[218:221], v[16:19]
	s_setprio 0
	s_setprio 1
	v_mfma_f32_16x16x32_bf16 v[44:47], v[172:175], v[190:193], v[44:47]
	v_mfma_f32_16x16x32_bf16 v[40:43], v[180:183], v[190:193], v[40:43]
	v_mfma_f32_16x16x32_bf16 v[28:31], v[172:175], v[198:201], v[28:31]
	v_mfma_f32_16x16x32_bf16 v[24:27], v[180:183], v[198:201], v[24:27]
	v_mfma_f32_16x16x32_bf16 v[12:15], v[172:175], v[206:209], v[12:15]
	v_mfma_f32_16x16x32_bf16 v[8:11], v[180:183], v[206:209], v[8:11]
	v_mfma_f32_16x16x32_bf16 v[4:7], v[172:175], v[214:217], v[4:7]
	v_mfma_f32_16x16x32_bf16 v[0:3], v[180:183], v[214:217], v[0:3]
	v_mfma_f32_16x16x32_bf16 v[44:47], v[176:179], v[194:197], v[44:47]
	v_mfma_f32_16x16x32_bf16 v[40:43], v[186:189], v[194:197], v[40:43]
	v_mfma_f32_16x16x32_bf16 v[28:31], v[176:179], v[202:205], v[28:31]
	v_mfma_f32_16x16x32_bf16 v[24:27], v[186:189], v[202:205], v[24:27]
	v_mfma_f32_16x16x32_bf16 v[12:15], v[176:179], v[210:213], v[12:15]
	v_mfma_f32_16x16x32_bf16 v[8:11], v[186:189], v[210:213], v[8:11]
	v_mfma_f32_16x16x32_bf16 v[4:7], v[176:179], v[218:221], v[4:7]
	v_mfma_f32_16x16x32_bf16 v[0:3], v[186:189], v[218:221], v[0:3]
	s_setprio 0
	s_barrier
	s_add_i32 s55, s55, 2
	s_add_u32 s28, s28, 0x100
	s_addc_u32 s29, s29, 0
	s_add_u32 s53, s53, 0x100
	s_addc_u32 s54, s54, 0
	s_cmp_gt_u32 s55, 13
	s_cbranch_scc0 .LBB0_647
	s_nop 0
	s_nop 0
	s_nop 0
	s_nop 0
	s_nop 0
	s_nop 0
	s_nop 0
	s_nop 0
	s_nop 0
	s_nop 0
	s_nop 0
	s_nop 0
	s_nop 0
	s_nop 0
	s_nop 0
	s_nop 0
	s_nop 0
	s_nop 0
	s_nop 0
	s_nop 0
	s_nop 0
	s_nop 0
	s_nop 0
	s_nop 0
	s_nop 0
	s_and_b64 vcc, exec, s[10:11]
	s_cbranch_vccz .LBB0_650
	s_barrier

; #define PG8_STAGE(bufoff, gbase, voff) do { _Pragma("unroll") for (int _i = 0; _i < 2; ++_i) \
;         __builtin_amdgcn_global_load_lds((const unsigned*)((const char*)(gbase) + (voff)[_i]), (PG8_LAS unsigned*)(lds + (bufoff) + ldsw + _i * 8192), 16, 0, 0); } while (0)
; #define PG8_LDA(dst, b, h) do { _Pragma("unroll") for (int m = 0; m < 4; ++m) _Pragma("unroll") for (int k = 0; k < 2; ++k) dst[m][k] = *(const PG8_LAS bf16x8*)(lds + PG8_SA(b, h) + aoff + m * 2048 + k * 1024); } while (0)
; #define PG8_LDB(dst, b, h) do { _Pragma("unroll") for (int n = 0; n < 2; ++n) _Pragma("unroll") for (int k = 0; k < 2; ++k) dst[n][k] = *(const PG8_LAS bf16x8*)(lds + PG8_SB(b, h) + boff + n * 2048 + k * 1024); } while (0)
; #define PG8_MMA(ai, bj, At, Bt) do { __builtin_amdgcn_s_setprio(1); _Pragma("unroll") for (int m = 0; m < 4; ++m) _Pragma("unroll") for (int n = 0; n < 2; ++n) _Pragma("unroll") for (int k = 0; k < 2; ++k) \
;         acc[ai][bj][m][n] = __builtin_amdgcn_mfma_f32_16x16x32_bf16(Bt[n][k], At[m][k], acc[ai][bj][m][n], 0, 0, 0); __builtin_amdgcn_s_setprio(0); } while (0)
; #define PG8_WAIT_V(n) asm volatile("s_waitcnt vmcnt(" #n ")" ::: "memory")
; #define PG8_WAIT_L(n) asm volatile("s_waitcnt lgkmcnt(" #n ")" ::: "memory")
; template <class Epi, class Sched, bool ALIGN_EPI = false, bool SP2 = false>
; __device__ __forceinline__ void gemm_phase(PG8_LAS unsigned char* lds, const Gemm g, const Sched& S, const Epi& E) {
;     ...
;             const bool last = (t == nt - 2);
;             const char* a1 = cA + (size_t)(t + 1) * kstep;
;             const char* a2 = last ? nA : cA + (size_t)(t + 2) * kstep; const char* b2 = last ? nB : cB + (size_t)(t + 2) * kstep;
;             const char* a3 = a2 + kstep; const char* b3 = b2 + kstep;
;             if (last && has_next) S.a_ready(nxt);
;             if constexpr (SP2) {
;             PG8_LDB(B0, 0, 0); PG8_LDB(B1, 0, 1); PG8_SCHED; PG8_LDA(At, 0, 0); PG8_STAGE(PG8_SA(1, 1), a1 + hstep, voffA);
;             PG8_WAIT_V(8); PG8_WAIT_L(0); PG8_BAR; PG8_MMA(0, 0, At, B0); PG8_MMA(0, 1, At, B1); PG8_BAR; PG8_SCHED;
;             PG8_LDA(At, 0, 1); PG8_STAGE(PG8_SB(0, 0), b2, voffB); PG8_STAGE(PG8_SB(0, 1), b2 + hstep, voffB); PG8_STAGE(PG8_SA(0, 0), a2, voffA);
;             PG8_WAIT_V(8); PG8_WAIT_L(0); PG8_BAR; PG8_MMA(1, 0, At, B0); PG8_MMA(1, 1, At, B1); PG8_BAR; PG8_SCHED;
.LBB0_1960:
	ds_read_b128 v[146:149], v162
	ds_read_b128 v[166:169], v162 offset:1024
	ds_read_b128 v[170:173], v162 offset:2048
	ds_read_b128 v[174:177], v162 offset:3072
	ds_read_b128 v[178:181], v163
	ds_read_b128 v[182:185], v163 offset:1024
	ds_read_b128 v[186:189], v163 offset:2048
	ds_read_b128 v[190:193], v163 offset:3072
	s_add_u32 s26, s24, 0xfffe0080
	s_addc_u32 s27, s25, -1
	s_cmp_eq_u32 s53, 4
	s_cselect_b32 s29, s19, s27
	s_cselect_b32 s28, s33, s26
	s_cselect_b32 s27, s17, s52
	s_cselect_b32 s26, s50, s51
	s_add_i32 m0, s36, 0xc000
	ds_read_b128 v[194:197], v164
	ds_read_b128 v[198:201], v164 offset:1024
	ds_read_b128 v[202:205], v164 offset:2048
	ds_read_b128 v[206:209], v164 offset:3072
	ds_read_b128 v[210:213], v164 offset:4096
	ds_read_b128 v[214:217], v164 offset:5120
	ds_read_b128 v[218:221], v164 offset:6144
	ds_read_b128 v[222:225], v164 offset:7168
	global_load_lds_dwordx4 v136, s[24:25]
	s_add_i32 m0, s36, 0xe000
	s_nop 0
	global_load_lds_dwordx4 v138, s[24:25]
	s_waitcnt vmcnt(8)
	s_waitcnt lgkmcnt(0)
	s_barrier
	s_setprio 1
	s_waitcnt lgkmcnt(0)
	v_mfma_f32_16x16x32_bf16 v[124:127], v[146:149], v[194:197], v[124:127]
	v_mfma_f32_16x16x32_bf16 v[120:123], v[170:173], v[194:197], v[120:123]
	v_mfma_f32_16x16x32_bf16 v[108:111], v[146:149], v[202:205], v[108:111]
	v_mfma_f32_16x16x32_bf16 v[104:107], v[170:173], v[202:205], v[104:107]
	v_mfma_f32_16x16x32_bf16 v[92:95], v[146:149], v[210:213], v[92:95]
	v_mfma_f32_16x16x32_bf16 v[88:91], v[170:173], v[210:213], v[88:91]
	v_mfma_f32_16x16x32_bf16 v[76:79], v[146:149], v[218:221], v[76:79]
	v_mfma_f32_16x16x32_bf16 v[72:75], v[170:173], v[218:221], v[72:75]
	v_mfma_f32_16x16x32_bf16 v[124:127], v[166:169], v[198:201], v[124:127]
	v_mfma_f32_16x16x32_bf16 v[120:123], v[174:177], v[198:201], v[120:123]
	v_mfma_f32_16x16x32_bf16 v[108:111], v[166:169], v[206:209], v[108:111]
	v_mfma_f32_16x16x32_bf16 v[104:107], v[174:177], v[206:209], v[104:107]
	v_mfma_f32_16x16x32_bf16 v[92:95], v[166:169], v[214:217], v[92:95]
	v_mfma_f32_16x16x32_bf16 v[88:91], v[174:177], v[214:217], v[88:91]
	v_mfma_f32_16x16x32_bf16 v[76:79], v[166:169], v[222:225], v[76:79]
	v_mfma_f32_16x16x32_bf16 v[72:75], v[174:177], v[222:225], v[72:75]
	s_setprio 0
	s_setprio 1
	v_mfma_f32_16x16x32_bf16 v[116:119], v[178:181], v[194:197], v[116:119]
	v_mfma_f32_16x16x32_bf16 v[112:115], v[186:189], v[194:197], v[112:115]
	v_mfma_f32_16x16x32_bf16 v[100:103], v[178:181], v[202:205], v[100:103]
	v_mfma_f32_16x16x32_bf16 v[96:99], v[186:189], v[202:205], v[96:99]
	v_mfma_f32_16x16x32_bf16 v[84:87], v[178:181], v[210:213], v[84:87]
	v_mfma_f32_16x16x32_bf16 v[80:83], v[186:189], v[210:213], v[80:83]
	v_mfma_f32_16x16x32_bf16 v[68:71], v[178:181], v[218:221], v[68:71]
	v_mfma_f32_16x16x32_bf16 v[64:67], v[186:189], v[218:221], v[64:67]
	v_mfma_f32_16x16x32_bf16 v[116:119], v[182:185], v[198:201], v[116:119]
	v_mfma_f32_16x16x32_bf16 v[112:115], v[190:193], v[198:201], v[112:115]
	v_mfma_f32_16x16x32_bf16 v[100:103], v[182:185], v[206:209], v[100:103]
	v_mfma_f32_16x16x32_bf16 v[96:99], v[190:193], v[206:209], v[96:99]
	v_mfma_f32_16x16x32_bf16 v[84:87], v[182:185], v[214:217], v[84:87]
	v_mfma_f32_16x16x32_bf16 v[80:83], v[190:193], v[214:217], v[80:83]
	v_mfma_f32_16x16x32_bf16 v[68:71], v[182:185], v[222:225], v[68:71]
	v_mfma_f32_16x16x32_bf16 v[64:67], v[190:193], v[222:225], v[64:67]
	s_setprio 0
	s_barrier
	s_add_i32 s54, s46, s35
	s_mov_b32 m0, s54
	ds_read_b128 v[194:197], v164 offset:16384
	ds_read_b128 v[198:201], v164 offset:17408
	ds_read_b128 v[202:205], v164 offset:18432
	ds_read_b128 v[206:209], v164 offset:19456
	ds_read_b128 v[210:213], v164 offset:20480
	ds_read_b128 v[214:217], v164 offset:21504
	ds_read_b128 v[218:221], v164 offset:22528
	ds_read_b128 v[222:225], v164 offset:23552
	global_load_lds_dwordx4 v130, s[26:27]
	s_add_i32 m0, s54, 0x2000
	s_add_u32 s54, s26, 0x20000
	s_addc_u32 s55, s27, 0
	s_add_i32 s56, s47, s35
	global_load_lds_dwordx4 v134, s[26:27]
	s_mov_b32 m0, s56
	s_nop 0
	global_load_lds_dwordx4 v130, s[54:55]
	s_add_i32 m0, s56, 0x2000
	s_nop 0
	global_load_lds_dwordx4 v134, s[54:55]
	s_mov_b32 m0, s36
	s_nop 0
	global_load_lds_dwordx4 v128, s[28:29]
	s_mov_b32 m0, s37
	s_nop 0
	global_load_lds_dwordx4 v132, s[28:29]
	s_waitcnt vmcnt(8)
	s_waitcnt lgkmcnt(0)
	s_barrier
	s_setprio 1
	s_waitcnt lgkmcnt(0)
	v_mfma_f32_16x16x32_bf16 v[60:63], v[146:149], v[194:197], v[60:63]
	v_mfma_f32_16x16x32_bf16 v[56:59], v[170:173], v[194:197], v[56:59]
	v_mfma_f32_16x16x32_bf16 v[44:47], v[146:149], v[202:205], v[44:47]
	v_mfma_f32_16x16x32_bf16 v[40:43], v[170:173], v[202:205], v[40:43]
	v_mfma_f32_16x16x32_bf16 v[28:31], v[146:149], v[210:213], v[28:31]
	v_mfma_f32_16x16x32_bf16 v[24:27], v[170:173], v[210:213], v[24:27]
	v_mfma_f32_16x16x32_bf16 v[12:15], v[146:149], v[218:221], v[12:15]
	v_mfma_f32_16x16x32_bf16 v[8:11], v[170:173], v[218:221], v[8:11]
	v_mfma_f32_16x16x32_bf16 v[60:63], v[166:169], v[198:201], v[60:63]
	v_mfma_f32_16x16x32_bf16 v[56:59], v[174:177], v[198:201], v[56:59]
	v_mfma_f32_16x16x32_bf16 v[44:47], v[166:169], v[206:209], v[44:47]
	v_mfma_f32_16x16x32_bf16 v[40:43], v[174:177], v[206:209], v[40:43]
	v_mfma_f32_16x16x32_bf16 v[28:31], v[166:169], v[214:217], v[28:31]
	v_mfma_f32_16x16x32_bf16 v[24:27], v[174:177], v[214:217], v[24:27]
	v_mfma_f32_16x16x32_bf16 v[12:15], v[166:169], v[222:225], v[12:15]
	v_mfma_f32_16x16x32_bf16 v[8:11], v[174:177], v[222:225], v[8:11]
	s_setprio 0
	s_setprio 1
	v_mfma_f32_16x16x32_bf16 v[52:55], v[178:181], v[194:197], v[52:55]
	v_mfma_f32_16x16x32_bf16 v[48:51], v[186:189], v[194:197], v[48:51]
	v_mfma_f32_16x16x32_bf16 v[36:39], v[178:181], v[202:205], v[36:39]
	v_mfma_f32_16x16x32_bf16 v[32:35], v[186:189], v[202:205], v[32:35]
	v_mfma_f32_16x16x32_bf16 v[20:23], v[178:181], v[210:213], v[20:23]
	v_mfma_f32_16x16x32_bf16 v[16:19], v[186:189], v[210:213], v[16:19]
	v_mfma_f32_16x16x32_bf16 v[4:7], v[178:181], v[218:221], v[4:7]
	v_mfma_f32_16x16x32_bf16 v[0:3], v[186:189], v[218:221], v[0:3]
	v_mfma_f32_16x16x32_bf16 v[52:55], v[182:185], v[198:201], v[52:55]
	v_mfma_f32_16x16x32_bf16 v[48:51], v[190:193], v[198:201], v[48:51]
	v_mfma_f32_16x16x32_bf16 v[36:39], v[182:185], v[206:209], v[36:39]
	v_mfma_f32_16x16x32_bf16 v[32:35], v[190:193], v[206:209], v[32:35]
	v_mfma_f32_16x16x32_bf16 v[20:23], v[182:185], v[214:217], v[20:23]
	v_mfma_f32_16x16x32_bf16 v[16:19], v[190:193], v[214:217], v[16:19]
	v_mfma_f32_16x16x32_bf16 v[4:7], v[182:185], v[222:225], v[4:7]
	v_mfma_f32_16x16x32_bf16 v[0:3], v[190:193], v[222:225], v[0:3]
	s_setprio 0
	s_barrier
; #define PG8_STAGE(bufoff, gbase, voff) do { _Pragma("unroll") for (int _i = 0; _i < 2; ++_i) \
;         __builtin_amdgcn_global_load_lds((const unsigned*)((const char*)(gbase) + (voff)[_i]), (PG8_LAS unsigned*)(lds + (bufoff) + ldsw + _i * 8192), 16, 0, 0); } while (0)
; #define PG8_LDA(dst, b, h) do { _Pragma("unroll") for (int m = 0; m < 4; ++m) _Pragma("unroll") for (int k = 0; k < 2; ++k) dst[m][k] = *(const PG8_LAS bf16x8*)(lds + PG8_SA(b, h) + aoff + m * 2048 + k * 1024); } while (0)
; #define PG8_LDB(dst, b, h) do { _Pragma("unroll") for (int n = 0; n < 2; ++n) _Pragma("unroll") for (int k = 0; k < 2; ++k) dst[n][k] = *(const PG8_LAS bf16x8*)(lds + PG8_SB(b, h) + boff + n * 2048 + k * 1024); } while (0)
; #define PG8_MMA(ai, bj, At, Bt) do { __builtin_amdgcn_s_setprio(1); _Pragma("unroll") for (int m = 0; m < 4; ++m) _Pragma("unroll") for (int n = 0; n < 2; ++n) _Pragma("unroll") for (int k = 0; k < 2; ++k) \
;         acc[ai][bj][m][n] = __builtin_amdgcn_mfma_f32_16x16x32_bf16(Bt[n][k], At[m][k], acc[ai][bj][m][n], 0, 0, 0); __builtin_amdgcn_s_setprio(0); } while (0)
; #define PG8_WAIT_V(n) asm volatile("s_waitcnt vmcnt(" #n ")" ::: "memory")
; #define PG8_WAIT_L(n) asm volatile("s_waitcnt lgkmcnt(" #n ")" ::: "memory")
; #define PG8_BAR __builtin_amdgcn_s_barrier()
; #define PG8_SCHED __builtin_amdgcn_sched_barrier(0)
; template <class Epi, class Sched, bool ALIGN_EPI = false, bool SP2 = false>
; __device__ __forceinline__ void gemm_phase(PG8_LAS unsigned char* lds, const Gemm g, const Sched& S, const Epi& E) {
;     ...
;             PG8_LDB(B0, 1, 0); PG8_LDB(B1, 1, 1); PG8_SCHED; PG8_LDA(At, 1, 0); PG8_STAGE(PG8_SA(0, 1), a2 + hstep, voffA);
;             PG8_WAIT_V(8); PG8_WAIT_L(0); PG8_BAR; PG8_MMA(0, 0, At, B0); PG8_MMA(0, 1, At, B1); PG8_BAR; PG8_SCHED;
	s_add_i32 s54, s42, 0x100
	v_add_u32_e32 v190, s54, v160
	ds_read_b128 v[146:149], v165
	ds_read_b128 v[166:169], v165 offset:1024
	ds_read_b128 v[170:173], v165 offset:2048
	ds_read_b128 v[174:177], v165 offset:3072
	ds_read_b128 v[178:181], v190
	ds_read_b128 v[182:185], v190 offset:1024
	ds_read_b128 v[186:189], v190 offset:2048
	ds_read_b128 v[190:193], v190 offset:3072
	s_add_u32 s100, s28, 0x20000
	s_addc_u32 s101, s29, 0
	s_mov_b32 m0, s38
	ds_read_b128 v[194:197], v164 offset:32768
	ds_read_b128 v[198:201], v164 offset:33792
	ds_read_b128 v[202:205], v164 offset:34816
	ds_read_b128 v[206:209], v164 offset:35840
	ds_read_b128 v[210:213], v164 offset:36864
	ds_read_b128 v[214:217], v164 offset:37888
	ds_read_b128 v[218:221], v164 offset:38912
	ds_read_b128 v[222:225], v164 offset:39936
	global_load_lds_dwordx4 v128, s[100:101]
	s_mov_b32 m0, s39
	s_nop 0
	global_load_lds_dwordx4 v132, s[100:101]
	s_waitcnt vmcnt(8)
	s_waitcnt lgkmcnt(0)
	s_barrier
	s_setprio 1
	s_waitcnt lgkmcnt(0)
	v_mfma_f32_16x16x32_bf16 v[124:127], v[146:149], v[194:197], v[124:127]
	v_mfma_f32_16x16x32_bf16 v[120:123], v[170:173], v[194:197], v[120:123]
	v_mfma_f32_16x16x32_bf16 v[108:111], v[146:149], v[202:205], v[108:111]
	v_mfma_f32_16x16x32_bf16 v[104:107], v[170:173], v[202:205], v[104:107]
	v_mfma_f32_16x16x32_bf16 v[92:95], v[146:149], v[210:213], v[92:95]
	v_mfma_f32_16x16x32_bf16 v[88:91], v[170:173], v[210:213], v[88:91]
	v_mfma_f32_16x16x32_bf16 v[76:79], v[146:149], v[218:221], v[76:79]
	v_mfma_f32_16x16x32_bf16 v[72:75], v[170:173], v[218:221], v[72:75]
	v_mfma_f32_16x16x32_bf16 v[124:127], v[166:169], v[198:201], v[124:127]
	v_mfma_f32_16x16x32_bf16 v[120:123], v[174:177], v[198:201], v[120:123]
	v_mfma_f32_16x16x32_bf16 v[108:111], v[166:169], v[206:209], v[108:111]
	v_mfma_f32_16x16x32_bf16 v[104:107], v[174:177], v[206:209], v[104:107]
	v_mfma_f32_16x16x32_bf16 v[92:95], v[166:169], v[214:217], v[92:95]
	v_mfma_f32_16x16x32_bf16 v[88:91], v[174:177], v[214:217], v[88:91]
	v_mfma_f32_16x16x32_bf16 v[76:79], v[166:169], v[222:225], v[76:79]
	v_mfma_f32_16x16x32_bf16 v[72:75], v[174:177], v[222:225], v[72:75]
	s_setprio 0
	s_setprio 1
	v_mfma_f32_16x16x32_bf16 v[116:119], v[178:181], v[194:197], v[116:119]
	v_mfma_f32_16x16x32_bf16 v[112:115], v[186:189], v[194:197], v[112:115]
	v_mfma_f32_16x16x32_bf16 v[100:103], v[178:181], v[202:205], v[100:103]
	v_mfma_f32_16x16x32_bf16 v[96:99], v[186:189], v[202:205], v[96:99]
	v_mfma_f32_16x16x32_bf16 v[84:87], v[178:181], v[210:213], v[84:87]
	v_mfma_f32_16x16x32_bf16 v[80:83], v[186:189], v[210:213], v[80:83]
	v_mfma_f32_16x16x32_bf16 v[68:71], v[178:181], v[218:221], v[68:71]
	v_mfma_f32_16x16x32_bf16 v[64:67], v[186:189], v[218:221], v[64:67]
	v_mfma_f32_16x16x32_bf16 v[116:119], v[182:185], v[198:201], v[116:119]
	v_mfma_f32_16x16x32_bf16 v[112:115], v[190:193], v[198:201], v[112:115]
	v_mfma_f32_16x16x32_bf16 v[100:103], v[182:185], v[206:209], v[100:103]
	v_mfma_f32_16x16x32_bf16 v[96:99], v[190:193], v[206:209], v[96:99]
	v_mfma_f32_16x16x32_bf16 v[84:87], v[182:185], v[214:217], v[84:87]
	v_mfma_f32_16x16x32_bf16 v[80:83], v[190:193], v[214:217], v[80:83]
	v_mfma_f32_16x16x32_bf16 v[68:71], v[182:185], v[222:225], v[68:71]
	v_mfma_f32_16x16x32_bf16 v[64:67], v[190:193], v[222:225], v[64:67]
	s_setprio 0
	s_barrier
; #define PG8_STAGE(bufoff, gbase, voff) do { _Pragma("unroll") for (int _i = 0; _i < 2; ++_i) \
;         __builtin_amdgcn_global_load_lds((const unsigned*)((const char*)(gbase) + (voff)[_i]), (PG8_LAS unsigned*)(lds + (bufoff) + ldsw + _i * 8192), 16, 0, 0); } while (0)
; #define PG8_LDA(dst, b, h) do { _Pragma("unroll") for (int m = 0; m < 4; ++m) _Pragma("unroll") for (int k = 0; k < 2; ++k) dst[m][k] = *(const PG8_LAS bf16x8*)(lds + PG8_SA(b, h) + aoff + m * 2048 + k * 1024); } while (0)
; #define PG8_MMA(ai, bj, At, Bt) do { __builtin_amdgcn_s_setprio(1); _Pragma("unroll") for (int m = 0; m < 4; ++m) _Pragma("unroll") for (int n = 0; n < 2; ++n) _Pragma("unroll") for (int k = 0; k < 2; ++k) \
;         acc[ai][bj][m][n] = __builtin_amdgcn_mfma_f32_16x16x32_bf16(Bt[n][k], At[m][k], acc[ai][bj][m][n], 0, 0, 0); __builtin_amdgcn_s_setprio(0); } while (0)
; #define PG8_WAIT_V(n) asm volatile("s_waitcnt vmcnt(" #n ")" ::: "memory")
; #define PG8_WAIT_L(n) asm volatile("s_waitcnt lgkmcnt(" #n ")" ::: "memory")
; #define PG8_BAR __builtin_amdgcn_s_barrier()
; #define PG8_SCHED __builtin_amdgcn_sched_barrier(0)
; template <class Epi, class Sched, bool ALIGN_EPI = false, bool SP2 = false>
; __device__ __forceinline__ void gemm_phase(PG8_LAS unsigned char* lds, const Gemm g, const Sched& S, const Epi& E) {
;     ...
;         for (int t = 0; t < nt; t += 2) {
;     ...
;             PG8_LDA(At, 1, 1); PG8_STAGE(PG8_SB(1, 0), b3, voffB); PG8_STAGE(PG8_SB(1, 1), b3 + hstep, voffB); PG8_STAGE(PG8_SA(1, 0), a3, voffA);
;             PG8_WAIT_V(8); PG8_WAIT_L(0); PG8_BAR; PG8_MMA(1, 0, At, B0); PG8_MMA(1, 1, At, B1); PG8_BAR; PG8_SCHED;
	s_add_u32 s100, s26, 0x80
	s_addc_u32 s101, s27, 0
	s_add_i32 s98, s49, s35
	s_mov_b32 m0, s98
	ds_read_b128 v[194:197], v164 offset:49152
	ds_read_b128 v[198:201], v164 offset:50176
	ds_read_b128 v[202:205], v164 offset:51200
	ds_read_b128 v[206:209], v164 offset:52224
	ds_read_b128 v[210:213], v164 offset:53248
	ds_read_b128 v[214:217], v164 offset:54272
	ds_read_b128 v[218:221], v164 offset:55296
	ds_read_b128 v[222:225], v164 offset:56320
	global_load_lds_dwordx4 v130, s[100:101]
	s_add_i32 m0, s98, 0x2000
	s_add_u32 s26, s26, 0x20080
	s_addc_u32 s27, s27, 0
	s_add_i32 s98, s54, s35
	global_load_lds_dwordx4 v134, s[100:101]
	s_mov_b32 m0, s98
	s_nop 0
	global_load_lds_dwordx4 v130, s[26:27]
	s_add_i32 m0, s98, 0x2000
	s_nop 0
	global_load_lds_dwordx4 v134, s[26:27]
	s_add_u32 s100, s28, 0x80
	s_addc_u32 s101, s29, 0
	s_mov_b32 m0, s40
	s_nop 0
	global_load_lds_dwordx4 v128, s[100:101]
	s_mov_b32 m0, s41
	s_nop 0
	global_load_lds_dwordx4 v132, s[100:101]
	s_waitcnt vmcnt(8)
	s_waitcnt lgkmcnt(0)
	s_barrier
	s_setprio 1
	s_waitcnt lgkmcnt(0)
	v_mfma_f32_16x16x32_bf16 v[60:63], v[146:149], v[194:197], v[60:63]
	v_mfma_f32_16x16x32_bf16 v[56:59], v[170:173], v[194:197], v[56:59]
	v_mfma_f32_16x16x32_bf16 v[44:47], v[146:149], v[202:205], v[44:47]
	v_mfma_f32_16x16x32_bf16 v[40:43], v[170:173], v[202:205], v[40:43]
	v_mfma_f32_16x16x32_bf16 v[28:31], v[146:149], v[210:213], v[28:31]
	v_mfma_f32_16x16x32_bf16 v[24:27], v[170:173], v[210:213], v[24:27]
	v_mfma_f32_16x16x32_bf16 v[12:15], v[146:149], v[218:221], v[12:15]
	v_mfma_f32_16x16x32_bf16 v[8:11], v[170:173], v[218:221], v[8:11]
	v_mfma_f32_16x16x32_bf16 v[60:63], v[166:169], v[198:201], v[60:63]
	v_mfma_f32_16x16x32_bf16 v[56:59], v[174:177], v[198:201], v[56:59]
	v_mfma_f32_16x16x32_bf16 v[44:47], v[166:169], v[206:209], v[44:47]
	v_mfma_f32_16x16x32_bf16 v[40:43], v[174:177], v[206:209], v[40:43]
	v_mfma_f32_16x16x32_bf16 v[28:31], v[166:169], v[214:217], v[28:31]
	v_mfma_f32_16x16x32_bf16 v[24:27], v[174:177], v[214:217], v[24:27]
	v_mfma_f32_16x16x32_bf16 v[12:15], v[166:169], v[222:225], v[12:15]
	v_mfma_f32_16x16x32_bf16 v[8:11], v[174:177], v[222:225], v[8:11]
	s_setprio 0
	s_setprio 1
	v_mfma_f32_16x16x32_bf16 v[52:55], v[178:181], v[194:197], v[52:55]
	v_mfma_f32_16x16x32_bf16 v[48:51], v[186:189], v[194:197], v[48:51]
	v_mfma_f32_16x16x32_bf16 v[36:39], v[178:181], v[202:205], v[36:39]
	v_mfma_f32_16x16x32_bf16 v[32:35], v[186:189], v[202:205], v[32:35]
	v_mfma_f32_16x16x32_bf16 v[20:23], v[178:181], v[210:213], v[20:23]
	v_mfma_f32_16x16x32_bf16 v[16:19], v[186:189], v[210:213], v[16:19]
	v_mfma_f32_16x16x32_bf16 v[4:7], v[178:181], v[218:221], v[4:7]
	v_mfma_f32_16x16x32_bf16 v[0:3], v[186:189], v[218:221], v[0:3]
	v_mfma_f32_16x16x32_bf16 v[52:55], v[182:185], v[198:201], v[52:55]
	v_mfma_f32_16x16x32_bf16 v[48:51], v[190:193], v[198:201], v[48:51]
	v_mfma_f32_16x16x32_bf16 v[36:39], v[182:185], v[206:209], v[36:39]
	v_mfma_f32_16x16x32_bf16 v[32:35], v[190:193], v[206:209], v[32:35]
	v_mfma_f32_16x16x32_bf16 v[20:23], v[182:185], v[214:217], v[20:23]
	v_mfma_f32_16x16x32_bf16 v[16:19], v[190:193], v[214:217], v[16:19]
	v_mfma_f32_16x16x32_bf16 v[4:7], v[182:185], v[222:225], v[4:7]
	v_mfma_f32_16x16x32_bf16 v[0:3], v[190:193], v[222:225], v[0:3]
	s_setprio 0
	s_barrier
	s_add_i32 s53, s53, 2
	s_add_u32 s24, s24, 0x100
	s_addc_u32 s25, s25, 0
	s_add_u32 s51, s51, 0x100
	s_addc_u32 s52, s52, 0
	s_cmp_gt_u32 s53, 5
	s_cbranch_scc0 .LBB0_1960
	s_nop 0
	s_nop 0
	s_nop 0
	s_nop 0
	s_nop 0
	s_nop 0
	s_nop 0
	s_nop 0
	s_nop 0
	s_nop 0
	s_nop 0
	s_nop 0
	s_nop 0
	s_nop 0
	s_nop 0
	s_nop 0
	s_nop 0
	s_nop 0
	s_nop 0
	s_nop 0
	s_nop 0
	s_nop 0
	s_nop 0
	s_nop 0
	s_nop 0
	s_and_b64 vcc, exec, s[14:15]
	s_cbranch_vccz .LBB0_1963
	s_barrier

; #define PG8_STAGE(bufoff, gbase, voff) do { _Pragma("unroll") for (int _i = 0; _i < 2; ++_i) \
;         __builtin_amdgcn_global_load_lds((const unsigned*)((const char*)(gbase) + (voff)[_i]), (PG8_LAS unsigned*)(lds + (bufoff) + ldsw + _i * 8192), 16, 0, 0); } while (0)
; #define PG8_LDA(dst, b, h) do { _Pragma("unroll") for (int m = 0; m < 4; ++m) _Pragma("unroll") for (int k = 0; k < 2; ++k) dst[m][k] = *(const PG8_LAS bf16x8*)(lds + PG8_SA(b, h) + aoff + m * 2048 + k * 1024); } while (0)
; #define PG8_LDB(dst, b, h) do { _Pragma("unroll") for (int n = 0; n < 2; ++n) _Pragma("unroll") for (int k = 0; k < 2; ++k) dst[n][k] = *(const PG8_LAS bf16x8*)(lds + PG8_SB(b, h) + boff + n * 2048 + k * 1024); } while (0)
; #define PG8_MMA(ai, bj, At, Bt) do { __builtin_amdgcn_s_setprio(1); _Pragma("unroll") for (int m = 0; m < 4; ++m) _Pragma("unroll") for (int n = 0; n < 2; ++n) _Pragma("unroll") for (int k = 0; k < 2; ++k) \
;         acc[ai][bj][m][n] = __builtin_amdgcn_mfma_f32_16x16x32_bf16(Bt[n][k], At[m][k], acc[ai][bj][m][n], 0, 0, 0); __builtin_amdgcn_s_setprio(0); } while (0)
; #define PG8_WAIT_V(n) asm volatile("s_waitcnt vmcnt(" #n ")" ::: "memory")
; #define PG8_WAIT_L(n) asm volatile("s_waitcnt lgkmcnt(" #n ")" ::: "memory")
; template <class Epi, class Sched, bool ALIGN_EPI = false, bool SP2 = false>
; __device__ __forceinline__ void gemm_phase(PG8_LAS unsigned char* lds, const Gemm g, const Sched& S, const Epi& E) {
;     ...
;             const bool last = (t == nt - 2);
;             const char* a1 = cA + (size_t)(t + 1) * kstep;
;             const char* a2 = last ? nA : cA + (size_t)(t + 2) * kstep; const char* b2 = last ? nB : cB + (size_t)(t + 2) * kstep;
;             const char* a3 = a2 + kstep; const char* b3 = b2 + kstep;
;             if (last && has_next) S.a_ready(nxt);
;             if constexpr (SP2) {
;             PG8_LDB(B0, 0, 0); PG8_LDB(B1, 0, 1); PG8_SCHED; PG8_LDA(At, 0, 0); PG8_STAGE(PG8_SA(1, 1), a1 + hstep, voffA);
;             PG8_WAIT_V(8); PG8_WAIT_L(0); PG8_BAR; PG8_MMA(0, 0, At, B0); PG8_MMA(0, 1, At, B1); PG8_BAR; PG8_SCHED;
;             PG8_LDA(At, 0, 1); PG8_STAGE(PG8_SB(0, 0), b2, voffB); PG8_STAGE(PG8_SB(0, 1), b2 + hstep, voffB); PG8_STAGE(PG8_SA(0, 0), a2, voffA);
;             PG8_WAIT_V(8); PG8_WAIT_L(0); PG8_BAR; PG8_MMA(1, 0, At, B0); PG8_MMA(1, 1, At, B1); PG8_BAR; PG8_SCHED;
.LBB0_1984:
	ds_read_b128 v[146:149], v145
	ds_read_b128 v[150:153], v145 offset:1024
	ds_read_b128 v[160:163], v145 offset:2048
	ds_read_b128 v[164:167], v145 offset:3072
	ds_read_b128 v[168:171], v155
	ds_read_b128 v[172:175], v155 offset:1024
	ds_read_b128 v[176:179], v155 offset:2048
	ds_read_b128 v[180:183], v155 offset:3072
	s_add_u32 s24, s22, 0xfffe0080
	s_addc_u32 s25, s23, -1
	s_cmp_eq_u32 s53, 4
	s_cselect_b32 s27, s17, s25
	s_cselect_b32 s26, s33, s24
	s_cselect_b32 s25, s15, s52
	s_cselect_b32 s24, s50, s51
	s_add_i32 m0, s36, 0xc000
	ds_read_b128 v[184:187], v158
	ds_read_b128 v[188:191], v158 offset:1024
	ds_read_b128 v[192:195], v158 offset:2048
	ds_read_b128 v[196:199], v158 offset:3072
	ds_read_b128 v[200:203], v158 offset:4096
	ds_read_b128 v[204:207], v158 offset:5120
	ds_read_b128 v[208:211], v158 offset:6144
	ds_read_b128 v[212:215], v158 offset:7168
	global_load_lds_dwordx4 v136, s[22:23]
	s_add_i32 m0, s36, 0xe000
	s_nop 0
	global_load_lds_dwordx4 v138, s[22:23]
	s_waitcnt vmcnt(8)
	s_waitcnt lgkmcnt(0)
	s_barrier
	s_setprio 1
	s_waitcnt lgkmcnt(0)
	v_mfma_f32_16x16x32_bf16 v[124:127], v[146:149], v[184:187], v[124:127]
	v_mfma_f32_16x16x32_bf16 v[120:123], v[160:163], v[184:187], v[120:123]
	v_mfma_f32_16x16x32_bf16 v[108:111], v[146:149], v[192:195], v[108:111]
	v_mfma_f32_16x16x32_bf16 v[104:107], v[160:163], v[192:195], v[104:107]
	v_mfma_f32_16x16x32_bf16 v[92:95], v[146:149], v[200:203], v[92:95]
	v_mfma_f32_16x16x32_bf16 v[88:91], v[160:163], v[200:203], v[88:91]
	v_mfma_f32_16x16x32_bf16 v[76:79], v[146:149], v[208:211], v[76:79]
	v_mfma_f32_16x16x32_bf16 v[72:75], v[160:163], v[208:211], v[72:75]
	v_mfma_f32_16x16x32_bf16 v[124:127], v[150:153], v[188:191], v[124:127]
	v_mfma_f32_16x16x32_bf16 v[120:123], v[164:167], v[188:191], v[120:123]
	v_mfma_f32_16x16x32_bf16 v[108:111], v[150:153], v[196:199], v[108:111]
	v_mfma_f32_16x16x32_bf16 v[104:107], v[164:167], v[196:199], v[104:107]
	v_mfma_f32_16x16x32_bf16 v[92:95], v[150:153], v[204:207], v[92:95]
	v_mfma_f32_16x16x32_bf16 v[88:91], v[164:167], v[204:207], v[88:91]
	v_mfma_f32_16x16x32_bf16 v[76:79], v[150:153], v[212:215], v[76:79]
	v_mfma_f32_16x16x32_bf16 v[72:75], v[164:167], v[212:215], v[72:75]
	s_setprio 0
	s_setprio 1
	v_mfma_f32_16x16x32_bf16 v[116:119], v[168:171], v[184:187], v[116:119]
	v_mfma_f32_16x16x32_bf16 v[112:115], v[176:179], v[184:187], v[112:115]
	v_mfma_f32_16x16x32_bf16 v[100:103], v[168:171], v[192:195], v[100:103]
	v_mfma_f32_16x16x32_bf16 v[96:99], v[176:179], v[192:195], v[96:99]
	v_mfma_f32_16x16x32_bf16 v[84:87], v[168:171], v[200:203], v[84:87]
	v_mfma_f32_16x16x32_bf16 v[80:83], v[176:179], v[200:203], v[80:83]
	v_mfma_f32_16x16x32_bf16 v[68:71], v[168:171], v[208:211], v[68:71]
	v_mfma_f32_16x16x32_bf16 v[64:67], v[176:179], v[208:211], v[64:67]
	v_mfma_f32_16x16x32_bf16 v[116:119], v[172:175], v[188:191], v[116:119]
	v_mfma_f32_16x16x32_bf16 v[112:115], v[180:183], v[188:191], v[112:115]
	v_mfma_f32_16x16x32_bf16 v[100:103], v[172:175], v[196:199], v[100:103]
	v_mfma_f32_16x16x32_bf16 v[96:99], v[180:183], v[196:199], v[96:99]
	v_mfma_f32_16x16x32_bf16 v[84:87], v[172:175], v[204:207], v[84:87]
	v_mfma_f32_16x16x32_bf16 v[80:83], v[180:183], v[204:207], v[80:83]
	v_mfma_f32_16x16x32_bf16 v[68:71], v[172:175], v[212:215], v[68:71]
	v_mfma_f32_16x16x32_bf16 v[64:67], v[180:183], v[212:215], v[64:67]
	s_setprio 0
	s_barrier
	s_add_i32 s54, s46, s35
	s_mov_b32 m0, s54
	ds_read_b128 v[184:187], v158 offset:16384
	ds_read_b128 v[188:191], v158 offset:17408
	ds_read_b128 v[192:195], v158 offset:18432
	ds_read_b128 v[196:199], v158 offset:19456
	ds_read_b128 v[200:203], v158 offset:20480
	ds_read_b128 v[204:207], v158 offset:21504
	ds_read_b128 v[208:211], v158 offset:22528
	ds_read_b128 v[212:215], v158 offset:23552
	global_load_lds_dwordx4 v130, s[24:25]
	s_add_i32 m0, s54, 0x2000
	s_add_u32 s54, s24, 0x20000
	s_addc_u32 s55, s25, 0
	s_add_i32 s56, s47, s35
	global_load_lds_dwordx4 v134, s[24:25]
	s_mov_b32 m0, s56
	s_nop 0
	global_load_lds_dwordx4 v130, s[54:55]
	s_add_i32 m0, s56, 0x2000
	s_nop 0
	global_load_lds_dwordx4 v134, s[54:55]
	s_mov_b32 m0, s36
	s_nop 0
	global_load_lds_dwordx4 v128, s[26:27]
	s_mov_b32 m0, s37
	s_nop 0
	global_load_lds_dwordx4 v132, s[26:27]
	s_waitcnt vmcnt(8)
	s_waitcnt lgkmcnt(0)
	s_barrier
	s_setprio 1
	s_waitcnt lgkmcnt(0)
	v_mfma_f32_16x16x32_bf16 v[60:63], v[146:149], v[184:187], v[60:63]
	v_mfma_f32_16x16x32_bf16 v[56:59], v[160:163], v[184:187], v[56:59]
	v_mfma_f32_16x16x32_bf16 v[44:47], v[146:149], v[192:195], v[44:47]
	v_mfma_f32_16x16x32_bf16 v[40:43], v[160:163], v[192:195], v[40:43]
	v_mfma_f32_16x16x32_bf16 v[28:31], v[146:149], v[200:203], v[28:31]
	v_mfma_f32_16x16x32_bf16 v[24:27], v[160:163], v[200:203], v[24:27]
	v_mfma_f32_16x16x32_bf16 v[12:15], v[146:149], v[208:211], v[12:15]
	v_mfma_f32_16x16x32_bf16 v[8:11], v[160:163], v[208:211], v[8:11]
	v_mfma_f32_16x16x32_bf16 v[60:63], v[150:153], v[188:191], v[60:63]
	v_mfma_f32_16x16x32_bf16 v[56:59], v[164:167], v[188:191], v[56:59]
	v_mfma_f32_16x16x32_bf16 v[44:47], v[150:153], v[196:199], v[44:47]
	v_mfma_f32_16x16x32_bf16 v[40:43], v[164:167], v[196:199], v[40:43]
	v_mfma_f32_16x16x32_bf16 v[28:31], v[150:153], v[204:207], v[28:31]
	v_mfma_f32_16x16x32_bf16 v[24:27], v[164:167], v[204:207], v[24:27]
	v_mfma_f32_16x16x32_bf16 v[12:15], v[150:153], v[212:215], v[12:15]
	v_mfma_f32_16x16x32_bf16 v[8:11], v[164:167], v[212:215], v[8:11]
	s_setprio 0
	s_setprio 1
	v_mfma_f32_16x16x32_bf16 v[52:55], v[168:171], v[184:187], v[52:55]
	v_mfma_f32_16x16x32_bf16 v[48:51], v[176:179], v[184:187], v[48:51]
	v_mfma_f32_16x16x32_bf16 v[36:39], v[168:171], v[192:195], v[36:39]
	v_mfma_f32_16x16x32_bf16 v[32:35], v[176:179], v[192:195], v[32:35]
	v_mfma_f32_16x16x32_bf16 v[20:23], v[168:171], v[200:203], v[20:23]
	v_mfma_f32_16x16x32_bf16 v[16:19], v[176:179], v[200:203], v[16:19]
	v_mfma_f32_16x16x32_bf16 v[4:7], v[168:171], v[208:211], v[4:7]
	v_mfma_f32_16x16x32_bf16 v[0:3], v[176:179], v[208:211], v[0:3]
	v_mfma_f32_16x16x32_bf16 v[52:55], v[172:175], v[188:191], v[52:55]
	v_mfma_f32_16x16x32_bf16 v[48:51], v[180:183], v[188:191], v[48:51]
	v_mfma_f32_16x16x32_bf16 v[36:39], v[172:175], v[196:199], v[36:39]
	v_mfma_f32_16x16x32_bf16 v[32:35], v[180:183], v[196:199], v[32:35]
	v_mfma_f32_16x16x32_bf16 v[20:23], v[172:175], v[204:207], v[20:23]
	v_mfma_f32_16x16x32_bf16 v[16:19], v[180:183], v[204:207], v[16:19]
	v_mfma_f32_16x16x32_bf16 v[4:7], v[172:175], v[212:215], v[4:7]
	v_mfma_f32_16x16x32_bf16 v[0:3], v[180:183], v[212:215], v[0:3]
	s_setprio 0
	s_barrier
; #define PG8_STAGE(bufoff, gbase, voff) do { _Pragma("unroll") for (int _i = 0; _i < 2; ++_i) \
;         __builtin_amdgcn_global_load_lds((const unsigned*)((const char*)(gbase) + (voff)[_i]), (PG8_LAS unsigned*)(lds + (bufoff) + ldsw + _i * 8192), 16, 0, 0); } while (0)
; #define PG8_LDA(dst, b, h) do { _Pragma("unroll") for (int m = 0; m < 4; ++m) _Pragma("unroll") for (int k = 0; k < 2; ++k) dst[m][k] = *(const PG8_LAS bf16x8*)(lds + PG8_SA(b, h) + aoff + m * 2048 + k * 1024); } while (0)
; #define PG8_LDB(dst, b, h) do { _Pragma("unroll") for (int n = 0; n < 2; ++n) _Pragma("unroll") for (int k = 0; k < 2; ++k) dst[n][k] = *(const PG8_LAS bf16x8*)(lds + PG8_SB(b, h) + boff + n * 2048 + k * 1024); } while (0)
; #define PG8_MMA(ai, bj, At, Bt) do { __builtin_amdgcn_s_setprio(1); _Pragma("unroll") for (int m = 0; m < 4; ++m) _Pragma("unroll") for (int n = 0; n < 2; ++n) _Pragma("unroll") for (int k = 0; k < 2; ++k) \
;         acc[ai][bj][m][n] = __builtin_amdgcn_mfma_f32_16x16x32_bf16(Bt[n][k], At[m][k], acc[ai][bj][m][n], 0, 0, 0); __builtin_amdgcn_s_setprio(0); } while (0)
; #define PG8_WAIT_V(n) asm volatile("s_waitcnt vmcnt(" #n ")" ::: "memory")
; #define PG8_WAIT_L(n) asm volatile("s_waitcnt lgkmcnt(" #n ")" ::: "memory")
; #define PG8_BAR __builtin_amdgcn_s_barrier()
; #define PG8_SCHED __builtin_amdgcn_sched_barrier(0)
; template <class Epi, class Sched, bool ALIGN_EPI = false, bool SP2 = false>
; __device__ __forceinline__ void gemm_phase(PG8_LAS unsigned char* lds, const Gemm g, const Sched& S, const Epi& E) {
;     ...
;             PG8_LDB(B0, 1, 0); PG8_LDB(B1, 1, 1); PG8_SCHED; PG8_LDA(At, 1, 0); PG8_STAGE(PG8_SA(0, 1), a2 + hstep, voffA);
;             PG8_WAIT_V(8); PG8_WAIT_L(0); PG8_BAR; PG8_MMA(0, 0, At, B0); PG8_MMA(0, 1, At, B1); PG8_BAR; PG8_SCHED;
	s_add_i32 s54, s42, 0x100
	v_add_u32_e32 v180, s54, v157
	ds_read_b128 v[146:149], v159
	ds_read_b128 v[150:153], v159 offset:1024
	ds_read_b128 v[160:163], v159 offset:2048
	ds_read_b128 v[164:167], v159 offset:3072
	ds_read_b128 v[168:171], v180
	ds_read_b128 v[172:175], v180 offset:1024
	ds_read_b128 v[176:179], v180 offset:2048
	ds_read_b128 v[180:183], v180 offset:3072
	s_add_u32 s100, s26, 0x20000
	s_addc_u32 s101, s27, 0
	s_mov_b32 m0, s38
	ds_read_b128 v[184:187], v158 offset:32768
	ds_read_b128 v[188:191], v158 offset:33792
	ds_read_b128 v[192:195], v158 offset:34816
	ds_read_b128 v[196:199], v158 offset:35840
	ds_read_b128 v[200:203], v158 offset:36864
	ds_read_b128 v[204:207], v158 offset:37888
	ds_read_b128 v[208:211], v158 offset:38912
	ds_read_b128 v[212:215], v158 offset:39936
	global_load_lds_dwordx4 v128, s[100:101]
	s_mov_b32 m0, s39
	s_nop 0
	global_load_lds_dwordx4 v132, s[100:101]
	s_waitcnt vmcnt(8)
	s_waitcnt lgkmcnt(0)
	s_barrier
	s_setprio 1
	s_waitcnt lgkmcnt(0)
	v_mfma_f32_16x16x32_bf16 v[124:127], v[146:149], v[184:187], v[124:127]
	v_mfma_f32_16x16x32_bf16 v[120:123], v[160:163], v[184:187], v[120:123]
	v_mfma_f32_16x16x32_bf16 v[108:111], v[146:149], v[192:195], v[108:111]
	v_mfma_f32_16x16x32_bf16 v[104:107], v[160:163], v[192:195], v[104:107]
	v_mfma_f32_16x16x32_bf16 v[92:95], v[146:149], v[200:203], v[92:95]
	v_mfma_f32_16x16x32_bf16 v[88:91], v[160:163], v[200:203], v[88:91]
	v_mfma_f32_16x16x32_bf16 v[76:79], v[146:149], v[208:211], v[76:79]
	v_mfma_f32_16x16x32_bf16 v[72:75], v[160:163], v[208:211], v[72:75]
	v_mfma_f32_16x16x32_bf16 v[124:127], v[150:153], v[188:191], v[124:127]
	v_mfma_f32_16x16x32_bf16 v[120:123], v[164:167], v[188:191], v[120:123]
	v_mfma_f32_16x16x32_bf16 v[108:111], v[150:153], v[196:199], v[108:111]
	v_mfma_f32_16x16x32_bf16 v[104:107], v[164:167], v[196:199], v[104:107]
	v_mfma_f32_16x16x32_bf16 v[92:95], v[150:153], v[204:207], v[92:95]
	v_mfma_f32_16x16x32_bf16 v[88:91], v[164:167], v[204:207], v[88:91]
	v_mfma_f32_16x16x32_bf16 v[76:79], v[150:153], v[212:215], v[76:79]
	v_mfma_f32_16x16x32_bf16 v[72:75], v[164:167], v[212:215], v[72:75]
	s_setprio 0
	s_setprio 1
	v_mfma_f32_16x16x32_bf16 v[116:119], v[168:171], v[184:187], v[116:119]
	v_mfma_f32_16x16x32_bf16 v[112:115], v[176:179], v[184:187], v[112:115]
	v_mfma_f32_16x16x32_bf16 v[100:103], v[168:171], v[192:195], v[100:103]
	v_mfma_f32_16x16x32_bf16 v[96:99], v[176:179], v[192:195], v[96:99]
	v_mfma_f32_16x16x32_bf16 v[84:87], v[168:171], v[200:203], v[84:87]
	v_mfma_f32_16x16x32_bf16 v[80:83], v[176:179], v[200:203], v[80:83]
	v_mfma_f32_16x16x32_bf16 v[68:71], v[168:171], v[208:211], v[68:71]
	v_mfma_f32_16x16x32_bf16 v[64:67], v[176:179], v[208:211], v[64:67]
	v_mfma_f32_16x16x32_bf16 v[116:119], v[172:175], v[188:191], v[116:119]
	v_mfma_f32_16x16x32_bf16 v[112:115], v[180:183], v[188:191], v[112:115]
	v_mfma_f32_16x16x32_bf16 v[100:103], v[172:175], v[196:199], v[100:103]
	v_mfma_f32_16x16x32_bf16 v[96:99], v[180:183], v[196:199], v[96:99]
	v_mfma_f32_16x16x32_bf16 v[84:87], v[172:175], v[204:207], v[84:87]
	v_mfma_f32_16x16x32_bf16 v[80:83], v[180:183], v[204:207], v[80:83]
	v_mfma_f32_16x16x32_bf16 v[68:71], v[172:175], v[212:215], v[68:71]
	v_mfma_f32_16x16x32_bf16 v[64:67], v[180:183], v[212:215], v[64:67]
	s_setprio 0
	s_barrier
; #define PG8_STAGE(bufoff, gbase, voff) do { _Pragma("unroll") for (int _i = 0; _i < 2; ++_i) \
;         __builtin_amdgcn_global_load_lds((const unsigned*)((const char*)(gbase) + (voff)[_i]), (PG8_LAS unsigned*)(lds + (bufoff) + ldsw + _i * 8192), 16, 0, 0); } while (0)
; #define PG8_LDA(dst, b, h) do { _Pragma("unroll") for (int m = 0; m < 4; ++m) _Pragma("unroll") for (int k = 0; k < 2; ++k) dst[m][k] = *(const PG8_LAS bf16x8*)(lds + PG8_SA(b, h) + aoff + m * 2048 + k * 1024); } while (0)
; #define PG8_MMA(ai, bj, At, Bt) do { __builtin_amdgcn_s_setprio(1); _Pragma("unroll") for (int m = 0; m < 4; ++m) _Pragma("unroll") for (int n = 0; n < 2; ++n) _Pragma("unroll") for (int k = 0; k < 2; ++k) \
;         acc[ai][bj][m][n] = __builtin_amdgcn_mfma_f32_16x16x32_bf16(Bt[n][k], At[m][k], acc[ai][bj][m][n], 0, 0, 0); __builtin_amdgcn_s_setprio(0); } while (0)
; #define PG8_WAIT_V(n) asm volatile("s_waitcnt vmcnt(" #n ")" ::: "memory")
; #define PG8_WAIT_L(n) asm volatile("s_waitcnt lgkmcnt(" #n ")" ::: "memory")
; #define PG8_BAR __builtin_amdgcn_s_barrier()
; #define PG8_SCHED __builtin_amdgcn_sched_barrier(0)
; template <class Epi, class Sched, bool ALIGN_EPI = false, bool SP2 = false>
; __device__ __forceinline__ void gemm_phase(PG8_LAS unsigned char* lds, const Gemm g, const Sched& S, const Epi& E) {
;     ...
;         for (int t = 0; t < nt; t += 2) {
;     ...
;             PG8_LDA(At, 1, 1); PG8_STAGE(PG8_SB(1, 0), b3, voffB); PG8_STAGE(PG8_SB(1, 1), b3 + hstep, voffB); PG8_STAGE(PG8_SA(1, 0), a3, voffA);
;             PG8_WAIT_V(8); PG8_WAIT_L(0); PG8_BAR; PG8_MMA(1, 0, At, B0); PG8_MMA(1, 1, At, B1); PG8_BAR; PG8_SCHED;
	s_add_u32 s100, s24, 0x80
	s_addc_u32 s101, s25, 0
	s_add_i32 s98, s49, s35
	s_mov_b32 m0, s98
	ds_read_b128 v[184:187], v158 offset:49152
	ds_read_b128 v[188:191], v158 offset:50176
	ds_read_b128 v[192:195], v158 offset:51200
	ds_read_b128 v[196:199], v158 offset:52224
	ds_read_b128 v[200:203], v158 offset:53248
	ds_read_b128 v[204:207], v158 offset:54272
	ds_read_b128 v[208:211], v158 offset:55296
	ds_read_b128 v[212:215], v158 offset:56320
	global_load_lds_dwordx4 v130, s[100:101]
	s_add_i32 m0, s98, 0x2000
	s_add_u32 s24, s24, 0x20080
	s_addc_u32 s25, s25, 0
	s_add_i32 s98, s54, s35
	global_load_lds_dwordx4 v134, s[100:101]
	s_mov_b32 m0, s98
	s_nop 0
	global_load_lds_dwordx4 v130, s[24:25]
	s_add_i32 m0, s98, 0x2000
	s_nop 0
	global_load_lds_dwordx4 v134, s[24:25]
	s_add_u32 s100, s26, 0x80
	s_addc_u32 s101, s27, 0
	s_mov_b32 m0, s40
	s_nop 0
	global_load_lds_dwordx4 v128, s[100:101]
	s_mov_b32 m0, s41
	s_nop 0
	global_load_lds_dwordx4 v132, s[100:101]
	s_waitcnt vmcnt(8)
	s_waitcnt lgkmcnt(0)
	s_barrier
	s_setprio 1
	s_waitcnt lgkmcnt(0)
	v_mfma_f32_16x16x32_bf16 v[60:63], v[146:149], v[184:187], v[60:63]
	v_mfma_f32_16x16x32_bf16 v[56:59], v[160:163], v[184:187], v[56:59]
	v_mfma_f32_16x16x32_bf16 v[44:47], v[146:149], v[192:195], v[44:47]
	v_mfma_f32_16x16x32_bf16 v[40:43], v[160:163], v[192:195], v[40:43]
	v_mfma_f32_16x16x32_bf16 v[28:31], v[146:149], v[200:203], v[28:31]
	v_mfma_f32_16x16x32_bf16 v[24:27], v[160:163], v[200:203], v[24:27]
	v_mfma_f32_16x16x32_bf16 v[12:15], v[146:149], v[208:211], v[12:15]
	v_mfma_f32_16x16x32_bf16 v[8:11], v[160:163], v[208:211], v[8:11]
	v_mfma_f32_16x16x32_bf16 v[60:63], v[150:153], v[188:191], v[60:63]
	v_mfma_f32_16x16x32_bf16 v[56:59], v[164:167], v[188:191], v[56:59]
	v_mfma_f32_16x16x32_bf16 v[44:47], v[150:153], v[196:199], v[44:47]
	v_mfma_f32_16x16x32_bf16 v[40:43], v[164:167], v[196:199], v[40:43]
	v_mfma_f32_16x16x32_bf16 v[28:31], v[150:153], v[204:207], v[28:31]
	v_mfma_f32_16x16x32_bf16 v[24:27], v[164:167], v[204:207], v[24:27]
	v_mfma_f32_16x16x32_bf16 v[12:15], v[150:153], v[212:215], v[12:15]
	v_mfma_f32_16x16x32_bf16 v[8:11], v[164:167], v[212:215], v[8:11]
	s_setprio 0
	s_setprio 1
	v_mfma_f32_16x16x32_bf16 v[52:55], v[168:171], v[184:187], v[52:55]
	v_mfma_f32_16x16x32_bf16 v[48:51], v[176:179], v[184:187], v[48:51]
	v_mfma_f32_16x16x32_bf16 v[36:39], v[168:171], v[192:195], v[36:39]
	v_mfma_f32_16x16x32_bf16 v[32:35], v[176:179], v[192:195], v[32:35]
	v_mfma_f32_16x16x32_bf16 v[20:23], v[168:171], v[200:203], v[20:23]
	v_mfma_f32_16x16x32_bf16 v[16:19], v[176:179], v[200:203], v[16:19]
	v_mfma_f32_16x16x32_bf16 v[4:7], v[168:171], v[208:211], v[4:7]
	v_mfma_f32_16x16x32_bf16 v[0:3], v[176:179], v[208:211], v[0:3]
	v_mfma_f32_16x16x32_bf16 v[52:55], v[172:175], v[188:191], v[52:55]
	v_mfma_f32_16x16x32_bf16 v[48:51], v[180:183], v[188:191], v[48:51]
	v_mfma_f32_16x16x32_bf16 v[36:39], v[172:175], v[196:199], v[36:39]
	v_mfma_f32_16x16x32_bf16 v[32:35], v[180:183], v[196:199], v[32:35]
	v_mfma_f32_16x16x32_bf16 v[20:23], v[172:175], v[204:207], v[20:23]
	v_mfma_f32_16x16x32_bf16 v[16:19], v[180:183], v[204:207], v[16:19]
	v_mfma_f32_16x16x32_bf16 v[4:7], v[172:175], v[212:215], v[4:7]
	v_mfma_f32_16x16x32_bf16 v[0:3], v[180:183], v[212:215], v[0:3]
	s_setprio 0
	s_barrier
	s_add_i32 s53, s53, 2
	s_add_u32 s22, s22, 0x100
	s_addc_u32 s23, s23, 0
	s_add_u32 s51, s51, 0x100
	s_addc_u32 s52, s52, 0
	s_cmp_gt_u32 s53, 5
	s_cbranch_scc0 .LBB0_1984
	s_nop 0
	s_nop 0
	s_nop 0
	s_nop 0
	s_nop 0
	s_nop 0
	s_nop 0
	s_nop 0
	s_nop 0
	s_nop 0
	s_nop 0
	s_nop 0
	s_nop 0
	s_nop 0
	s_nop 0
	s_nop 0
	s_nop 0
	s_nop 0
	s_nop 0
	s_nop 0
	s_nop 0
	s_nop 0
	s_nop 0
	s_nop 0
	s_nop 0
	s_and_b64 vcc, exec, s[12:13]
	s_cbranch_vccz .LBB0_1987
	s_barrier

; #define PG8_STAGE(bufoff, gbase, voff) do { _Pragma("unroll") for (int _i = 0; _i < 2; ++_i) \
;         __builtin_amdgcn_global_load_lds((const unsigned*)((const char*)(gbase) + (voff)[_i]), (PG8_LAS unsigned*)(lds + (bufoff) + ldsw + _i * 8192), 16, 0, 0); } while (0)
; #define PG8_LDA(dst, b, h) do { _Pragma("unroll") for (int m = 0; m < 4; ++m) _Pragma("unroll") for (int k = 0; k < 2; ++k) dst[m][k] = *(const PG8_LAS bf16x8*)(lds + PG8_SA(b, h) + aoff + m * 2048 + k * 1024); } while (0)
; #define PG8_LDB(dst, b, h) do { _Pragma("unroll") for (int n = 0; n < 2; ++n) _Pragma("unroll") for (int k = 0; k < 2; ++k) dst[n][k] = *(const PG8_LAS bf16x8*)(lds + PG8_SB(b, h) + boff + n * 2048 + k * 1024); } while (0)
; #define PG8_MMA(ai, bj, At, Bt) do { __builtin_amdgcn_s_setprio(1); _Pragma("unroll") for (int m = 0; m < 4; ++m) _Pragma("unroll") for (int n = 0; n < 2; ++n) _Pragma("unroll") for (int k = 0; k < 2; ++k) \
;         acc[ai][bj][m][n] = __builtin_amdgcn_mfma_f32_16x16x32_bf16(Bt[n][k], At[m][k], acc[ai][bj][m][n], 0, 0, 0); __builtin_amdgcn_s_setprio(0); } while (0)
; #define PG8_WAIT_V(n) asm volatile("s_waitcnt vmcnt(" #n ")" ::: "memory")
; #define PG8_WAIT_L(n) asm volatile("s_waitcnt lgkmcnt(" #n ")" ::: "memory")
; template <class Epi, class Sched, bool ALIGN_EPI = false, bool SP2 = false>
; __device__ __forceinline__ void gemm_phase(PG8_LAS unsigned char* lds, const Gemm g, const Sched& S, const Epi& E) {
;     ...
;             const bool last = (t == nt - 2);
;             const char* a1 = cA + (size_t)(t + 1) * kstep;
;             const char* a2 = last ? nA : cA + (size_t)(t + 2) * kstep; const char* b2 = last ? nB : cB + (size_t)(t + 2) * kstep;
;             const char* a3 = a2 + kstep; const char* b3 = b2 + kstep;
;             if (last && has_next) S.a_ready(nxt);
;             if constexpr (SP2) {
;             PG8_LDB(B0, 0, 0); PG8_LDB(B1, 0, 1); PG8_SCHED; PG8_LDA(At, 0, 0); PG8_STAGE(PG8_SA(1, 1), a1 + hstep, voffA);
;             PG8_WAIT_V(8); PG8_WAIT_L(0); PG8_BAR; PG8_MMA(0, 0, At, B0); PG8_MMA(0, 1, At, B1); PG8_BAR; PG8_SCHED;
;             PG8_LDA(At, 0, 1); PG8_STAGE(PG8_SB(0, 0), b2, voffB); PG8_STAGE(PG8_SB(0, 1), b2 + hstep, voffB); PG8_STAGE(PG8_SA(0, 0), a2, voffA);
;             PG8_WAIT_V(8); PG8_WAIT_L(0); PG8_BAR; PG8_MMA(1, 0, At, B0); PG8_MMA(1, 1, At, B1); PG8_BAR; PG8_SCHED;
.LBB0_2061:
	ds_read_b128 v[104:107], v169
	ds_read_b128 v[112:115], v169 offset:1024
	ds_read_b128 v[120:123], v169 offset:2048
	ds_read_b128 v[124:127], v169 offset:3072
	ds_read_b128 v[162:165], v170
	ds_read_b128 v[174:177], v170 offset:1024
	ds_read_b128 v[178:181], v170 offset:2048
	ds_read_b128 v[182:185], v170 offset:3072
	s_add_u32 s30, s28, 0xfffc0080
	s_addc_u32 s31, s29, -1
	s_cmp_eq_u32 s58, 12
	s_cselect_b32 s35, s21, s31
	s_cselect_b32 s34, s54, s30
	s_cselect_b32 s31, s19, s57
	s_cselect_b32 s30, s55, s56
	s_add_i32 m0, s27, 0xc000
	ds_read_b128 v[186:189], v171
	ds_read_b128 v[190:193], v171 offset:1024
	ds_read_b128 v[194:197], v171 offset:2048
	ds_read_b128 v[198:201], v171 offset:3072
	ds_read_b128 v[202:205], v171 offset:4096
	ds_read_b128 v[206:209], v171 offset:5120
	ds_read_b128 v[210:213], v171 offset:6144
	ds_read_b128 v[214:217], v171 offset:7168
	global_load_lds_dwordx4 v154, s[28:29]
	s_add_i32 m0, s27, 0xe000
	s_nop 0
	global_load_lds_dwordx4 v156, s[28:29]
	s_waitcnt vmcnt(8)
	s_waitcnt lgkmcnt(0)
	s_barrier
	s_setprio 1
	s_waitcnt lgkmcnt(0)
	v_mfma_f32_16x16x32_bf16 v[140:143], v[104:107], v[186:189], v[140:143]
	v_mfma_f32_16x16x32_bf16 v[136:139], v[120:123], v[186:189], v[136:139]
	v_mfma_f32_16x16x32_bf16 v[116:119], v[104:107], v[194:197], v[116:119]
	v_mfma_f32_16x16x32_bf16 v[108:111], v[120:123], v[194:197], v[108:111]
	v_mfma_f32_16x16x32_bf16 v[92:95], v[104:107], v[202:205], v[92:95]
	v_mfma_f32_16x16x32_bf16 v[88:91], v[120:123], v[202:205], v[88:91]
	v_mfma_f32_16x16x32_bf16 v[76:79], v[104:107], v[210:213], v[76:79]
	v_mfma_f32_16x16x32_bf16 v[72:75], v[120:123], v[210:213], v[72:75]
	v_mfma_f32_16x16x32_bf16 v[140:143], v[112:115], v[190:193], v[140:143]
	v_mfma_f32_16x16x32_bf16 v[136:139], v[124:127], v[190:193], v[136:139]
	v_mfma_f32_16x16x32_bf16 v[116:119], v[112:115], v[198:201], v[116:119]
	v_mfma_f32_16x16x32_bf16 v[108:111], v[124:127], v[198:201], v[108:111]
	v_mfma_f32_16x16x32_bf16 v[92:95], v[112:115], v[206:209], v[92:95]
	v_mfma_f32_16x16x32_bf16 v[88:91], v[124:127], v[206:209], v[88:91]
	v_mfma_f32_16x16x32_bf16 v[76:79], v[112:115], v[214:217], v[76:79]
	v_mfma_f32_16x16x32_bf16 v[72:75], v[124:127], v[214:217], v[72:75]
	s_setprio 0
	s_setprio 1
	v_mfma_f32_16x16x32_bf16 v[132:135], v[162:165], v[186:189], v[132:135]
	v_mfma_f32_16x16x32_bf16 v[128:131], v[178:181], v[186:189], v[128:131]
	v_mfma_f32_16x16x32_bf16 v[100:103], v[162:165], v[194:197], v[100:103]
	v_mfma_f32_16x16x32_bf16 v[96:99], v[178:181], v[194:197], v[96:99]
	v_mfma_f32_16x16x32_bf16 v[84:87], v[162:165], v[202:205], v[84:87]
	v_mfma_f32_16x16x32_bf16 v[80:83], v[178:181], v[202:205], v[80:83]
	v_mfma_f32_16x16x32_bf16 v[68:71], v[162:165], v[210:213], v[68:71]
	v_mfma_f32_16x16x32_bf16 v[64:67], v[178:181], v[210:213], v[64:67]
	v_mfma_f32_16x16x32_bf16 v[132:135], v[174:177], v[190:193], v[132:135]
	v_mfma_f32_16x16x32_bf16 v[128:131], v[182:185], v[190:193], v[128:131]
	v_mfma_f32_16x16x32_bf16 v[100:103], v[174:177], v[198:201], v[100:103]
	v_mfma_f32_16x16x32_bf16 v[96:99], v[182:185], v[198:201], v[96:99]
	v_mfma_f32_16x16x32_bf16 v[84:87], v[174:177], v[206:209], v[84:87]
	v_mfma_f32_16x16x32_bf16 v[80:83], v[182:185], v[206:209], v[80:83]
	v_mfma_f32_16x16x32_bf16 v[68:71], v[174:177], v[214:217], v[68:71]
	v_mfma_f32_16x16x32_bf16 v[64:67], v[182:185], v[214:217], v[64:67]
	s_setprio 0
	s_barrier
	s_add_i32 s59, s50, s39
	s_mov_b32 m0, s59
	ds_read_b128 v[186:189], v171 offset:16384
	ds_read_b128 v[190:193], v171 offset:17408
	ds_read_b128 v[194:197], v171 offset:18432
	ds_read_b128 v[198:201], v171 offset:19456
	ds_read_b128 v[202:205], v171 offset:20480
	ds_read_b128 v[206:209], v171 offset:21504
	ds_read_b128 v[210:213], v171 offset:22528
	ds_read_b128 v[214:217], v171 offset:23552
	global_load_lds_dwordx4 v148, s[30:31]
	s_add_i32 m0, s59, 0x2000
	s_add_u32 s60, s30, 0x40000
	s_addc_u32 s61, s31, 0
	s_add_i32 s59, s51, s39
	global_load_lds_dwordx4 v152, s[30:31]
	s_mov_b32 m0, s59
	s_nop 0
	global_load_lds_dwordx4 v148, s[60:61]
	s_add_i32 m0, s59, 0x2000
	s_nop 0
	global_load_lds_dwordx4 v152, s[60:61]
	s_mov_b32 m0, s27
	s_nop 0
	global_load_lds_dwordx4 v146, s[34:35]
	s_mov_b32 m0, s40
	s_nop 0
	global_load_lds_dwordx4 v150, s[34:35]
	s_waitcnt vmcnt(8)
	s_waitcnt lgkmcnt(0)
	s_barrier
	s_setprio 1
	s_waitcnt lgkmcnt(0)
	v_mfma_f32_16x16x32_bf16 v[60:63], v[104:107], v[186:189], v[60:63]
	v_mfma_f32_16x16x32_bf16 v[56:59], v[120:123], v[186:189], v[56:59]
	v_mfma_f32_16x16x32_bf16 v[44:47], v[104:107], v[194:197], v[44:47]
	v_mfma_f32_16x16x32_bf16 v[40:43], v[120:123], v[194:197], v[40:43]
	v_mfma_f32_16x16x32_bf16 v[28:31], v[104:107], v[202:205], v[28:31]
	v_mfma_f32_16x16x32_bf16 v[24:27], v[120:123], v[202:205], v[24:27]
	v_mfma_f32_16x16x32_bf16 v[12:15], v[104:107], v[210:213], v[12:15]
	v_mfma_f32_16x16x32_bf16 v[8:11], v[120:123], v[210:213], v[8:11]
	v_mfma_f32_16x16x32_bf16 v[60:63], v[112:115], v[190:193], v[60:63]
	v_mfma_f32_16x16x32_bf16 v[56:59], v[124:127], v[190:193], v[56:59]
	v_mfma_f32_16x16x32_bf16 v[44:47], v[112:115], v[198:201], v[44:47]
	v_mfma_f32_16x16x32_bf16 v[40:43], v[124:127], v[198:201], v[40:43]
	v_mfma_f32_16x16x32_bf16 v[28:31], v[112:115], v[206:209], v[28:31]
	v_mfma_f32_16x16x32_bf16 v[24:27], v[124:127], v[206:209], v[24:27]
	v_mfma_f32_16x16x32_bf16 v[12:15], v[112:115], v[214:217], v[12:15]
	v_mfma_f32_16x16x32_bf16 v[8:11], v[124:127], v[214:217], v[8:11]
	s_setprio 0
	s_setprio 1
	v_mfma_f32_16x16x32_bf16 v[52:55], v[162:165], v[186:189], v[52:55]
	v_mfma_f32_16x16x32_bf16 v[48:51], v[178:181], v[186:189], v[48:51]
	v_mfma_f32_16x16x32_bf16 v[36:39], v[162:165], v[194:197], v[36:39]
	v_mfma_f32_16x16x32_bf16 v[32:35], v[178:181], v[194:197], v[32:35]
	v_mfma_f32_16x16x32_bf16 v[20:23], v[162:165], v[202:205], v[20:23]
	v_mfma_f32_16x16x32_bf16 v[16:19], v[178:181], v[202:205], v[16:19]
	v_mfma_f32_16x16x32_bf16 v[4:7], v[162:165], v[210:213], v[4:7]
	v_mfma_f32_16x16x32_bf16 v[0:3], v[178:181], v[210:213], v[0:3]
	v_mfma_f32_16x16x32_bf16 v[52:55], v[174:177], v[190:193], v[52:55]
	v_mfma_f32_16x16x32_bf16 v[48:51], v[182:185], v[190:193], v[48:51]
	v_mfma_f32_16x16x32_bf16 v[36:39], v[174:177], v[198:201], v[36:39]
	v_mfma_f32_16x16x32_bf16 v[32:35], v[182:185], v[198:201], v[32:35]
	v_mfma_f32_16x16x32_bf16 v[20:23], v[174:177], v[206:209], v[20:23]
	v_mfma_f32_16x16x32_bf16 v[16:19], v[182:185], v[206:209], v[16:19]
	v_mfma_f32_16x16x32_bf16 v[4:7], v[174:177], v[214:217], v[4:7]
	v_mfma_f32_16x16x32_bf16 v[0:3], v[182:185], v[214:217], v[0:3]
	s_setprio 0
	s_barrier
; #define PG8_STAGE(bufoff, gbase, voff) do { _Pragma("unroll") for (int _i = 0; _i < 2; ++_i) \
;         __builtin_amdgcn_global_load_lds((const unsigned*)((const char*)(gbase) + (voff)[_i]), (PG8_LAS unsigned*)(lds + (bufoff) + ldsw + _i * 8192), 16, 0, 0); } while (0)
; #define PG8_LDA(dst, b, h) do { _Pragma("unroll") for (int m = 0; m < 4; ++m) _Pragma("unroll") for (int k = 0; k < 2; ++k) dst[m][k] = *(const PG8_LAS bf16x8*)(lds + PG8_SA(b, h) + aoff + m * 2048 + k * 1024); } while (0)
; #define PG8_LDB(dst, b, h) do { _Pragma("unroll") for (int n = 0; n < 2; ++n) _Pragma("unroll") for (int k = 0; k < 2; ++k) dst[n][k] = *(const PG8_LAS bf16x8*)(lds + PG8_SB(b, h) + boff + n * 2048 + k * 1024); } while (0)
; #define PG8_MMA(ai, bj, At, Bt) do { __builtin_amdgcn_s_setprio(1); _Pragma("unroll") for (int m = 0; m < 4; ++m) _Pragma("unroll") for (int n = 0; n < 2; ++n) _Pragma("unroll") for (int k = 0; k < 2; ++k) \
;         acc[ai][bj][m][n] = __builtin_amdgcn_mfma_f32_16x16x32_bf16(Bt[n][k], At[m][k], acc[ai][bj][m][n], 0, 0, 0); __builtin_amdgcn_s_setprio(0); } while (0)
; #define PG8_WAIT_V(n) asm volatile("s_waitcnt vmcnt(" #n ")" ::: "memory")
; #define PG8_WAIT_L(n) asm volatile("s_waitcnt lgkmcnt(" #n ")" ::: "memory")
; #define PG8_BAR __builtin_amdgcn_s_barrier()
; #define PG8_SCHED __builtin_amdgcn_sched_barrier(0)
; template <class Epi, class Sched, bool ALIGN_EPI = false, bool SP2 = false>
; __device__ __forceinline__ void gemm_phase(PG8_LAS unsigned char* lds, const Gemm g, const Sched& S, const Epi& E) {
;     ...
;         for (int t = 0; t < nt; t += 2) {
;     ...
;             PG8_LDB(B0, 1, 0); PG8_LDB(B1, 1, 1); PG8_SCHED; PG8_LDA(At, 1, 0); PG8_STAGE(PG8_SA(0, 1), a2 + hstep, voffA);
;             PG8_WAIT_V(8); PG8_WAIT_L(0); PG8_BAR; PG8_MMA(0, 0, At, B0); PG8_MMA(0, 1, At, B1); PG8_BAR; PG8_SCHED;
;             PG8_LDA(At, 1, 1); PG8_STAGE(PG8_SB(1, 0), b3, voffB); PG8_STAGE(PG8_SB(1, 1), b3 + hstep, voffB); PG8_STAGE(PG8_SA(1, 0), a3, voffA);
;             PG8_WAIT_V(8); PG8_WAIT_L(0); PG8_BAR; PG8_MMA(1, 0, At, B0); PG8_MMA(1, 1, At, B1); PG8_BAR; PG8_SCHED;
	ds_read_b128 v[104:107], v172
	ds_read_b128 v[112:115], v172 offset:1024
	ds_read_b128 v[120:123], v172 offset:2048
	ds_read_b128 v[124:127], v172 offset:3072
	ds_read_b128 v[162:165], v173
	ds_read_b128 v[174:177], v173 offset:1024
	ds_read_b128 v[178:181], v173 offset:2048
	ds_read_b128 v[182:185], v173 offset:3072
	s_add_u32 s100, s34, 0x40000
	s_addc_u32 s101, s35, 0
	s_mov_b32 m0, s41
	ds_read_b128 v[186:189], v171 offset:32768
	ds_read_b128 v[190:193], v171 offset:33792
	ds_read_b128 v[194:197], v171 offset:34816
	ds_read_b128 v[198:201], v171 offset:35840
	ds_read_b128 v[202:205], v171 offset:36864
	ds_read_b128 v[206:209], v171 offset:37888
	ds_read_b128 v[210:213], v171 offset:38912
	ds_read_b128 v[214:217], v171 offset:39936
	global_load_lds_dwordx4 v146, s[100:101]
	s_mov_b32 m0, s42
	s_nop 0
	global_load_lds_dwordx4 v150, s[100:101]
	s_waitcnt vmcnt(8)
	s_waitcnt lgkmcnt(0)
	s_barrier
	s_setprio 1
	s_waitcnt lgkmcnt(0)
	v_mfma_f32_16x16x32_bf16 v[140:143], v[104:107], v[186:189], v[140:143]
	v_mfma_f32_16x16x32_bf16 v[136:139], v[120:123], v[186:189], v[136:139]
	v_mfma_f32_16x16x32_bf16 v[116:119], v[104:107], v[194:197], v[116:119]
	v_mfma_f32_16x16x32_bf16 v[108:111], v[120:123], v[194:197], v[108:111]
	v_mfma_f32_16x16x32_bf16 v[92:95], v[104:107], v[202:205], v[92:95]
	v_mfma_f32_16x16x32_bf16 v[88:91], v[120:123], v[202:205], v[88:91]
	v_mfma_f32_16x16x32_bf16 v[76:79], v[104:107], v[210:213], v[76:79]
	v_mfma_f32_16x16x32_bf16 v[72:75], v[120:123], v[210:213], v[72:75]
	v_mfma_f32_16x16x32_bf16 v[140:143], v[112:115], v[190:193], v[140:143]
	v_mfma_f32_16x16x32_bf16 v[136:139], v[124:127], v[190:193], v[136:139]
	v_mfma_f32_16x16x32_bf16 v[116:119], v[112:115], v[198:201], v[116:119]
	v_mfma_f32_16x16x32_bf16 v[108:111], v[124:127], v[198:201], v[108:111]
	v_mfma_f32_16x16x32_bf16 v[92:95], v[112:115], v[206:209], v[92:95]
	v_mfma_f32_16x16x32_bf16 v[88:91], v[124:127], v[206:209], v[88:91]
	v_mfma_f32_16x16x32_bf16 v[76:79], v[112:115], v[214:217], v[76:79]
	v_mfma_f32_16x16x32_bf16 v[72:75], v[124:127], v[214:217], v[72:75]
	s_setprio 0
	s_setprio 1
	v_mfma_f32_16x16x32_bf16 v[132:135], v[162:165], v[186:189], v[132:135]
	v_mfma_f32_16x16x32_bf16 v[128:131], v[178:181], v[186:189], v[128:131]
	v_mfma_f32_16x16x32_bf16 v[100:103], v[162:165], v[194:197], v[100:103]
	v_mfma_f32_16x16x32_bf16 v[96:99], v[178:181], v[194:197], v[96:99]
	v_mfma_f32_16x16x32_bf16 v[84:87], v[162:165], v[202:205], v[84:87]
	v_mfma_f32_16x16x32_bf16 v[80:83], v[178:181], v[202:205], v[80:83]
	v_mfma_f32_16x16x32_bf16 v[68:71], v[162:165], v[210:213], v[68:71]
	v_mfma_f32_16x16x32_bf16 v[64:67], v[178:181], v[210:213], v[64:67]
	v_mfma_f32_16x16x32_bf16 v[132:135], v[174:177], v[190:193], v[132:135]
	v_mfma_f32_16x16x32_bf16 v[128:131], v[182:185], v[190:193], v[128:131]
	v_mfma_f32_16x16x32_bf16 v[100:103], v[174:177], v[198:201], v[100:103]
	v_mfma_f32_16x16x32_bf16 v[96:99], v[182:185], v[198:201], v[96:99]
	v_mfma_f32_16x16x32_bf16 v[84:87], v[174:177], v[206:209], v[84:87]
	v_mfma_f32_16x16x32_bf16 v[80:83], v[182:185], v[206:209], v[80:83]
	v_mfma_f32_16x16x32_bf16 v[68:71], v[174:177], v[214:217], v[68:71]
	v_mfma_f32_16x16x32_bf16 v[64:67], v[182:185], v[214:217], v[64:67]
	s_setprio 0
	s_barrier
	s_add_u32 s100, s30, 0x80
	s_addc_u32 s101, s31, 0
	s_add_i32 s98, s52, s39
	s_mov_b32 m0, s98
	ds_read_b128 v[186:189], v171 offset:49152
	ds_read_b128 v[190:193], v171 offset:50176
	ds_read_b128 v[194:197], v171 offset:51200
	ds_read_b128 v[198:201], v171 offset:52224
	ds_read_b128 v[202:205], v171 offset:53248
	ds_read_b128 v[206:209], v171 offset:54272
	ds_read_b128 v[210:213], v171 offset:55296
	ds_read_b128 v[214:217], v171 offset:56320
	global_load_lds_dwordx4 v148, s[100:101]
	s_add_i32 m0, s98, 0x2000
	s_add_u32 s30, s30, 0x40080
	s_addc_u32 s31, s31, 0
	s_add_i32 s98, s53, s39
	global_load_lds_dwordx4 v152, s[100:101]
	s_mov_b32 m0, s98
	s_nop 0
	global_load_lds_dwordx4 v148, s[30:31]
	s_add_i32 m0, s98, 0x2000
	s_nop 0
	global_load_lds_dwordx4 v152, s[30:31]
	s_add_u32 s100, s34, 0x80
	s_addc_u32 s101, s35, 0
	s_mov_b32 m0, s45
	s_nop 0
	global_load_lds_dwordx4 v146, s[100:101]
	s_mov_b32 m0, s46
	s_nop 0
	global_load_lds_dwordx4 v150, s[100:101]
	s_waitcnt vmcnt(8)
	s_waitcnt lgkmcnt(0)
	s_barrier
	s_setprio 1
	s_waitcnt lgkmcnt(0)
	v_mfma_f32_16x16x32_bf16 v[60:63], v[104:107], v[186:189], v[60:63]
	v_mfma_f32_16x16x32_bf16 v[56:59], v[120:123], v[186:189], v[56:59]
	v_mfma_f32_16x16x32_bf16 v[44:47], v[104:107], v[194:197], v[44:47]
	v_mfma_f32_16x16x32_bf16 v[40:43], v[120:123], v[194:197], v[40:43]
	v_mfma_f32_16x16x32_bf16 v[28:31], v[104:107], v[202:205], v[28:31]
	v_mfma_f32_16x16x32_bf16 v[24:27], v[120:123], v[202:205], v[24:27]
	v_mfma_f32_16x16x32_bf16 v[12:15], v[104:107], v[210:213], v[12:15]
	v_mfma_f32_16x16x32_bf16 v[8:11], v[120:123], v[210:213], v[8:11]
	v_mfma_f32_16x16x32_bf16 v[60:63], v[112:115], v[190:193], v[60:63]
	v_mfma_f32_16x16x32_bf16 v[56:59], v[124:127], v[190:193], v[56:59]
	v_mfma_f32_16x16x32_bf16 v[44:47], v[112:115], v[198:201], v[44:47]
	v_mfma_f32_16x16x32_bf16 v[40:43], v[124:127], v[198:201], v[40:43]
	v_mfma_f32_16x16x32_bf16 v[28:31], v[112:115], v[206:209], v[28:31]
	v_mfma_f32_16x16x32_bf16 v[24:27], v[124:127], v[206:209], v[24:27]
	v_mfma_f32_16x16x32_bf16 v[12:15], v[112:115], v[214:217], v[12:15]
	v_mfma_f32_16x16x32_bf16 v[8:11], v[124:127], v[214:217], v[8:11]
	s_setprio 0
	s_setprio 1
	v_mfma_f32_16x16x32_bf16 v[52:55], v[162:165], v[186:189], v[52:55]
	v_mfma_f32_16x16x32_bf16 v[48:51], v[178:181], v[186:189], v[48:51]
	v_mfma_f32_16x16x32_bf16 v[36:39], v[162:165], v[194:197], v[36:39]
	v_mfma_f32_16x16x32_bf16 v[32:35], v[178:181], v[194:197], v[32:35]
	v_mfma_f32_16x16x32_bf16 v[20:23], v[162:165], v[202:205], v[20:23]
	v_mfma_f32_16x16x32_bf16 v[16:19], v[178:181], v[202:205], v[16:19]
	v_mfma_f32_16x16x32_bf16 v[4:7], v[162:165], v[210:213], v[4:7]
	v_mfma_f32_16x16x32_bf16 v[0:3], v[178:181], v[210:213], v[0:3]
	v_mfma_f32_16x16x32_bf16 v[52:55], v[174:177], v[190:193], v[52:55]
	v_mfma_f32_16x16x32_bf16 v[48:51], v[182:185], v[190:193], v[48:51]
	v_mfma_f32_16x16x32_bf16 v[36:39], v[174:177], v[198:201], v[36:39]
	v_mfma_f32_16x16x32_bf16 v[32:35], v[182:185], v[198:201], v[32:35]
	v_mfma_f32_16x16x32_bf16 v[20:23], v[174:177], v[206:209], v[20:23]
	v_mfma_f32_16x16x32_bf16 v[16:19], v[182:185], v[206:209], v[16:19]
	v_mfma_f32_16x16x32_bf16 v[4:7], v[174:177], v[214:217], v[4:7]
	v_mfma_f32_16x16x32_bf16 v[0:3], v[182:185], v[214:217], v[0:3]
	s_setprio 0
	s_barrier
	s_add_i32 s58, s58, 2
	s_add_u32 s28, s28, 0x100
	s_addc_u32 s29, s29, 0
	s_add_u32 s56, s56, 0x100
	s_addc_u32 s57, s57, 0
	s_cmp_gt_u32 s58, 13
	s_cbranch_scc0 .LBB0_2061
	s_nop 0
	s_nop 0
	s_nop 0
	s_nop 0
	s_nop 0
	s_nop 0
	s_nop 0
	s_nop 0
	s_nop 0
	s_nop 0
	s_nop 0
	s_nop 0
	s_nop 0
	s_nop 0
	s_nop 0
	s_nop 0
	s_nop 0
	s_nop 0
	s_nop 0
	s_nop 0
	s_nop 0
	s_nop 0
	s_nop 0
	s_nop 0
	s_nop 0
	s_and_b64 vcc, exec, s[10:11]
	s_cbranch_vccz .LBB0_2064
	s_barrier

; #define PG8_STAGE(bufoff, gbase, voff) do { _Pragma("unroll") for (int _i = 0; _i < 2; ++_i) \
;         __builtin_amdgcn_global_load_lds((const unsigned*)((const char*)(gbase) + (voff)[_i]), (PG8_LAS unsigned*)(lds + (bufoff) + ldsw + _i * 8192), 16, 0, 0); } while (0)
; #define PG8_LDA(dst, b, h) do { _Pragma("unroll") for (int m = 0; m < 4; ++m) _Pragma("unroll") for (int k = 0; k < 2; ++k) dst[m][k] = *(const PG8_LAS bf16x8*)(lds + PG8_SA(b, h) + aoff + m * 2048 + k * 1024); } while (0)
; #define PG8_LDB(dst, b, h) do { _Pragma("unroll") for (int n = 0; n < 2; ++n) _Pragma("unroll") for (int k = 0; k < 2; ++k) dst[n][k] = *(const PG8_LAS bf16x8*)(lds + PG8_SB(b, h) + boff + n * 2048 + k * 1024); } while (0)
; #define PG8_MMA(ai, bj, At, Bt) do { __builtin_amdgcn_s_setprio(1); _Pragma("unroll") for (int m = 0; m < 4; ++m) _Pragma("unroll") for (int n = 0; n < 2; ++n) _Pragma("unroll") for (int k = 0; k < 2; ++k) \
;         acc[ai][bj][m][n] = __builtin_amdgcn_mfma_f32_16x16x32_bf16(Bt[n][k], At[m][k], acc[ai][bj][m][n], 0, 0, 0); __builtin_amdgcn_s_setprio(0); } while (0)
; #define PG8_WAIT_V(n) asm volatile("s_waitcnt vmcnt(" #n ")" ::: "memory")
; #define PG8_WAIT_L(n) asm volatile("s_waitcnt lgkmcnt(" #n ")" ::: "memory")
; template <class Epi, class Sched, bool ALIGN_EPI = false, bool SP2 = false>
; __device__ __forceinline__ void gemm_phase(PG8_LAS unsigned char* lds, const Gemm g, const Sched& S, const Epi& E) {
;     ...
;             const bool last = (t == nt - 2);
;             const char* a1 = cA + (size_t)(t + 1) * kstep;
;             const char* a2 = last ? nA : cA + (size_t)(t + 2) * kstep; const char* b2 = last ? nB : cB + (size_t)(t + 2) * kstep;
;             const char* a3 = a2 + kstep; const char* b3 = b2 + kstep;
;             if (last && has_next) S.a_ready(nxt);
;             if constexpr (SP2) {
;             PG8_LDB(B0, 0, 0); PG8_LDB(B1, 0, 1); PG8_SCHED; PG8_LDA(At, 0, 0); PG8_STAGE(PG8_SA(1, 1), a1 + hstep, voffA);
;             PG8_WAIT_V(8); PG8_WAIT_L(0); PG8_BAR; PG8_MMA(0, 0, At, B0); PG8_MMA(0, 1, At, B1); PG8_BAR; PG8_SCHED;
;             PG8_LDA(At, 0, 1); PG8_STAGE(PG8_SB(0, 0), b2, voffB); PG8_STAGE(PG8_SB(0, 1), b2 + hstep, voffB); PG8_STAGE(PG8_SA(0, 0), a2, voffA);
;             PG8_WAIT_V(8); PG8_WAIT_L(0); PG8_BAR; PG8_MMA(1, 0, At, B0); PG8_MMA(1, 1, At, B1); PG8_BAR; PG8_SCHED;
.LBB0_2190:
	ds_read_b128 v[154:157], v149
	ds_read_b128 v[158:161], v149 offset:1024
	ds_read_b128 v[162:165], v149 offset:2048
	ds_read_b128 v[166:169], v149 offset:3072
	ds_read_b128 v[170:173], v150
	ds_read_b128 v[174:177], v150 offset:1024
	ds_read_b128 v[178:181], v150 offset:2048
	ds_read_b128 v[182:185], v150 offset:3072
	s_add_u32 s22, s20, 0xfffc0080
	s_addc_u32 s23, s21, -1
	s_cmp_eq_u32 s50, 12
	s_cselect_b32 s25, s13, s23
	s_cselect_b32 s24, s46, s22
	s_cselect_b32 s23, s11, s49
	s_cselect_b32 s22, s47, s48
	s_add_i32 m0, s19, 0xc000
	ds_read_b128 v[186:189], v151
	ds_read_b128 v[190:193], v151 offset:1024
	ds_read_b128 v[194:197], v151 offset:2048
	ds_read_b128 v[198:201], v151 offset:3072
	ds_read_b128 v[202:205], v151 offset:4096
	ds_read_b128 v[206:209], v151 offset:5120
	ds_read_b128 v[210:213], v151 offset:6144
	ds_read_b128 v[214:217], v151 offset:7168
	global_load_lds_dwordx4 v136, s[20:21]
	s_add_i32 m0, s19, 0xe000
	s_nop 0
	global_load_lds_dwordx4 v138, s[20:21]
	s_waitcnt vmcnt(8)
	s_waitcnt lgkmcnt(0)
	s_barrier
	s_setprio 1
	s_waitcnt lgkmcnt(0)
	v_mfma_f32_16x16x32_bf16 v[124:127], v[154:157], v[186:189], v[124:127]
	v_mfma_f32_16x16x32_bf16 v[120:123], v[162:165], v[186:189], v[120:123]
	v_mfma_f32_16x16x32_bf16 v[108:111], v[154:157], v[194:197], v[108:111]
	v_mfma_f32_16x16x32_bf16 v[104:107], v[162:165], v[194:197], v[104:107]
	v_mfma_f32_16x16x32_bf16 v[92:95], v[154:157], v[202:205], v[92:95]
	v_mfma_f32_16x16x32_bf16 v[88:91], v[162:165], v[202:205], v[88:91]
	v_mfma_f32_16x16x32_bf16 v[76:79], v[154:157], v[210:213], v[76:79]
	v_mfma_f32_16x16x32_bf16 v[72:75], v[162:165], v[210:213], v[72:75]
	v_mfma_f32_16x16x32_bf16 v[124:127], v[158:161], v[190:193], v[124:127]
	v_mfma_f32_16x16x32_bf16 v[120:123], v[166:169], v[190:193], v[120:123]
	v_mfma_f32_16x16x32_bf16 v[108:111], v[158:161], v[198:201], v[108:111]
	v_mfma_f32_16x16x32_bf16 v[104:107], v[166:169], v[198:201], v[104:107]
	v_mfma_f32_16x16x32_bf16 v[92:95], v[158:161], v[206:209], v[92:95]
	v_mfma_f32_16x16x32_bf16 v[88:91], v[166:169], v[206:209], v[88:91]
	v_mfma_f32_16x16x32_bf16 v[76:79], v[158:161], v[214:217], v[76:79]
	v_mfma_f32_16x16x32_bf16 v[72:75], v[166:169], v[214:217], v[72:75]
	s_setprio 0
	s_setprio 1
	v_mfma_f32_16x16x32_bf16 v[116:119], v[170:173], v[186:189], v[116:119]
	v_mfma_f32_16x16x32_bf16 v[112:115], v[178:181], v[186:189], v[112:115]
	v_mfma_f32_16x16x32_bf16 v[100:103], v[170:173], v[194:197], v[100:103]
	v_mfma_f32_16x16x32_bf16 v[96:99], v[178:181], v[194:197], v[96:99]
	v_mfma_f32_16x16x32_bf16 v[84:87], v[170:173], v[202:205], v[84:87]
	v_mfma_f32_16x16x32_bf16 v[80:83], v[178:181], v[202:205], v[80:83]
	v_mfma_f32_16x16x32_bf16 v[68:71], v[170:173], v[210:213], v[68:71]
	v_mfma_f32_16x16x32_bf16 v[64:67], v[178:181], v[210:213], v[64:67]
	v_mfma_f32_16x16x32_bf16 v[116:119], v[174:177], v[190:193], v[116:119]
	v_mfma_f32_16x16x32_bf16 v[112:115], v[182:185], v[190:193], v[112:115]
	v_mfma_f32_16x16x32_bf16 v[100:103], v[174:177], v[198:201], v[100:103]
	v_mfma_f32_16x16x32_bf16 v[96:99], v[182:185], v[198:201], v[96:99]
	v_mfma_f32_16x16x32_bf16 v[84:87], v[174:177], v[206:209], v[84:87]
	v_mfma_f32_16x16x32_bf16 v[80:83], v[182:185], v[206:209], v[80:83]
	v_mfma_f32_16x16x32_bf16 v[68:71], v[174:177], v[214:217], v[68:71]
	v_mfma_f32_16x16x32_bf16 v[64:67], v[182:185], v[214:217], v[64:67]
	s_setprio 0
	s_barrier
	s_add_i32 s51, s41, s28
	s_mov_b32 m0, s51
	ds_read_b128 v[186:189], v151 offset:16384
	ds_read_b128 v[190:193], v151 offset:17408
	ds_read_b128 v[194:197], v151 offset:18432
	ds_read_b128 v[198:201], v151 offset:19456
	ds_read_b128 v[202:205], v151 offset:20480
	ds_read_b128 v[206:209], v151 offset:21504
	ds_read_b128 v[210:213], v151 offset:22528
	ds_read_b128 v[214:217], v151 offset:23552
	global_load_lds_dwordx4 v132, s[22:23]
	s_add_i32 m0, s51, 0x2000
	s_add_u32 s52, s22, 0x40000
	s_addc_u32 s53, s23, 0
	s_add_i32 s51, s42, s28
	global_load_lds_dwordx4 v128, s[22:23]
	s_mov_b32 m0, s51
	s_nop 0
	global_load_lds_dwordx4 v132, s[52:53]
	s_add_i32 m0, s51, 0x2000
	s_nop 0
	global_load_lds_dwordx4 v128, s[52:53]
	s_mov_b32 m0, s19
	s_nop 0
	global_load_lds_dwordx4 v134, s[24:25]
	s_mov_b32 m0, s31
	s_nop 0
	global_load_lds_dwordx4 v130, s[24:25]
	s_waitcnt vmcnt(8)
	s_waitcnt lgkmcnt(0)
	s_barrier
	s_setprio 1
	s_waitcnt lgkmcnt(0)
	v_mfma_f32_16x16x32_bf16 v[60:63], v[154:157], v[186:189], v[60:63]
	v_mfma_f32_16x16x32_bf16 v[56:59], v[162:165], v[186:189], v[56:59]
	v_mfma_f32_16x16x32_bf16 v[44:47], v[154:157], v[194:197], v[44:47]
	v_mfma_f32_16x16x32_bf16 v[40:43], v[162:165], v[194:197], v[40:43]
	v_mfma_f32_16x16x32_bf16 v[28:31], v[154:157], v[202:205], v[28:31]
	v_mfma_f32_16x16x32_bf16 v[24:27], v[162:165], v[202:205], v[24:27]
	v_mfma_f32_16x16x32_bf16 v[12:15], v[154:157], v[210:213], v[12:15]
	v_mfma_f32_16x16x32_bf16 v[8:11], v[162:165], v[210:213], v[8:11]
	v_mfma_f32_16x16x32_bf16 v[60:63], v[158:161], v[190:193], v[60:63]
	v_mfma_f32_16x16x32_bf16 v[56:59], v[166:169], v[190:193], v[56:59]
	v_mfma_f32_16x16x32_bf16 v[44:47], v[158:161], v[198:201], v[44:47]
	v_mfma_f32_16x16x32_bf16 v[40:43], v[166:169], v[198:201], v[40:43]
	v_mfma_f32_16x16x32_bf16 v[28:31], v[158:161], v[206:209], v[28:31]
	v_mfma_f32_16x16x32_bf16 v[24:27], v[166:169], v[206:209], v[24:27]
	v_mfma_f32_16x16x32_bf16 v[12:15], v[158:161], v[214:217], v[12:15]
	v_mfma_f32_16x16x32_bf16 v[8:11], v[166:169], v[214:217], v[8:11]
	s_setprio 0
	s_setprio 1
	v_mfma_f32_16x16x32_bf16 v[52:55], v[170:173], v[186:189], v[52:55]
	v_mfma_f32_16x16x32_bf16 v[48:51], v[178:181], v[186:189], v[48:51]
	v_mfma_f32_16x16x32_bf16 v[36:39], v[170:173], v[194:197], v[36:39]
	v_mfma_f32_16x16x32_bf16 v[32:35], v[178:181], v[194:197], v[32:35]
	v_mfma_f32_16x16x32_bf16 v[20:23], v[170:173], v[202:205], v[20:23]
	v_mfma_f32_16x16x32_bf16 v[16:19], v[178:181], v[202:205], v[16:19]
	v_mfma_f32_16x16x32_bf16 v[4:7], v[170:173], v[210:213], v[4:7]
	v_mfma_f32_16x16x32_bf16 v[0:3], v[178:181], v[210:213], v[0:3]
	v_mfma_f32_16x16x32_bf16 v[52:55], v[174:177], v[190:193], v[52:55]
	v_mfma_f32_16x16x32_bf16 v[48:51], v[182:185], v[190:193], v[48:51]
	v_mfma_f32_16x16x32_bf16 v[36:39], v[174:177], v[198:201], v[36:39]
	v_mfma_f32_16x16x32_bf16 v[32:35], v[182:185], v[198:201], v[32:35]
	v_mfma_f32_16x16x32_bf16 v[20:23], v[174:177], v[206:209], v[20:23]
	v_mfma_f32_16x16x32_bf16 v[16:19], v[182:185], v[206:209], v[16:19]
	v_mfma_f32_16x16x32_bf16 v[4:7], v[174:177], v[214:217], v[4:7]
	v_mfma_f32_16x16x32_bf16 v[0:3], v[182:185], v[214:217], v[0:3]
	s_setprio 0
	s_barrier
; #define PG8_STAGE(bufoff, gbase, voff) do { _Pragma("unroll") for (int _i = 0; _i < 2; ++_i) \
;         __builtin_amdgcn_global_load_lds((const unsigned*)((const char*)(gbase) + (voff)[_i]), (PG8_LAS unsigned*)(lds + (bufoff) + ldsw + _i * 8192), 16, 0, 0); } while (0)
; #define PG8_LDA(dst, b, h) do { _Pragma("unroll") for (int m = 0; m < 4; ++m) _Pragma("unroll") for (int k = 0; k < 2; ++k) dst[m][k] = *(const PG8_LAS bf16x8*)(lds + PG8_SA(b, h) + aoff + m * 2048 + k * 1024); } while (0)
; #define PG8_LDB(dst, b, h) do { _Pragma("unroll") for (int n = 0; n < 2; ++n) _Pragma("unroll") for (int k = 0; k < 2; ++k) dst[n][k] = *(const PG8_LAS bf16x8*)(lds + PG8_SB(b, h) + boff + n * 2048 + k * 1024); } while (0)
; #define PG8_MMA(ai, bj, At, Bt) do { __builtin_amdgcn_s_setprio(1); _Pragma("unroll") for (int m = 0; m < 4; ++m) _Pragma("unroll") for (int n = 0; n < 2; ++n) _Pragma("unroll") for (int k = 0; k < 2; ++k) \
;         acc[ai][bj][m][n] = __builtin_amdgcn_mfma_f32_16x16x32_bf16(Bt[n][k], At[m][k], acc[ai][bj][m][n], 0, 0, 0); __builtin_amdgcn_s_setprio(0); } while (0)
; #define PG8_WAIT_V(n) asm volatile("s_waitcnt vmcnt(" #n ")" ::: "memory")
; #define PG8_WAIT_L(n) asm volatile("s_waitcnt lgkmcnt(" #n ")" ::: "memory")
; #define PG8_BAR __builtin_amdgcn_s_barrier()
; #define PG8_SCHED __builtin_amdgcn_sched_barrier(0)
; template <class Epi, class Sched, bool ALIGN_EPI = false, bool SP2 = false>
; __device__ __forceinline__ void gemm_phase(PG8_LAS unsigned char* lds, const Gemm g, const Sched& S, const Epi& E) {
;     ...
;         for (int t = 0; t < nt; t += 2) {
;     ...
;             PG8_LDB(B0, 1, 0); PG8_LDB(B1, 1, 1); PG8_SCHED; PG8_LDA(At, 1, 0); PG8_STAGE(PG8_SA(0, 1), a2 + hstep, voffA);
;             PG8_WAIT_V(8); PG8_WAIT_L(0); PG8_BAR; PG8_MMA(0, 0, At, B0); PG8_MMA(0, 1, At, B1); PG8_BAR; PG8_SCHED;
;             PG8_LDA(At, 1, 1); PG8_STAGE(PG8_SB(1, 0), b3, voffB); PG8_STAGE(PG8_SB(1, 1), b3 + hstep, voffB); PG8_STAGE(PG8_SA(1, 0), a3, voffA);
;             PG8_WAIT_V(8); PG8_WAIT_L(0); PG8_BAR; PG8_MMA(1, 0, At, B0); PG8_MMA(1, 1, At, B1); PG8_BAR; PG8_SCHED;
	ds_read_b128 v[154:157], v152
	ds_read_b128 v[158:161], v152 offset:1024
	ds_read_b128 v[162:165], v152 offset:2048
	ds_read_b128 v[166:169], v152 offset:3072
	ds_read_b128 v[170:173], v153
	ds_read_b128 v[174:177], v153 offset:1024
	ds_read_b128 v[178:181], v153 offset:2048
	ds_read_b128 v[182:185], v153 offset:3072
	s_add_u32 s100, s24, 0x40000
	s_addc_u32 s101, s25, 0
	s_mov_b32 m0, s34
	ds_read_b128 v[186:189], v151 offset:32768
	ds_read_b128 v[190:193], v151 offset:33792
	ds_read_b128 v[194:197], v151 offset:34816
	ds_read_b128 v[198:201], v151 offset:35840
	ds_read_b128 v[202:205], v151 offset:36864
	ds_read_b128 v[206:209], v151 offset:37888
	ds_read_b128 v[210:213], v151 offset:38912
	ds_read_b128 v[214:217], v151 offset:39936
	global_load_lds_dwordx4 v134, s[100:101]
	s_mov_b32 m0, s35
	s_nop 0
	global_load_lds_dwordx4 v130, s[100:101]
	s_waitcnt vmcnt(8)
	s_waitcnt lgkmcnt(0)
	s_barrier
	s_setprio 1
	s_waitcnt lgkmcnt(0)
	v_mfma_f32_16x16x32_bf16 v[124:127], v[154:157], v[186:189], v[124:127]
	v_mfma_f32_16x16x32_bf16 v[120:123], v[162:165], v[186:189], v[120:123]
	v_mfma_f32_16x16x32_bf16 v[108:111], v[154:157], v[194:197], v[108:111]
	v_mfma_f32_16x16x32_bf16 v[104:107], v[162:165], v[194:197], v[104:107]
	v_mfma_f32_16x16x32_bf16 v[92:95], v[154:157], v[202:205], v[92:95]
	v_mfma_f32_16x16x32_bf16 v[88:91], v[162:165], v[202:205], v[88:91]
	v_mfma_f32_16x16x32_bf16 v[76:79], v[154:157], v[210:213], v[76:79]
	v_mfma_f32_16x16x32_bf16 v[72:75], v[162:165], v[210:213], v[72:75]
	v_mfma_f32_16x16x32_bf16 v[124:127], v[158:161], v[190:193], v[124:127]
	v_mfma_f32_16x16x32_bf16 v[120:123], v[166:169], v[190:193], v[120:123]
	v_mfma_f32_16x16x32_bf16 v[108:111], v[158:161], v[198:201], v[108:111]
	v_mfma_f32_16x16x32_bf16 v[104:107], v[166:169], v[198:201], v[104:107]
	v_mfma_f32_16x16x32_bf16 v[92:95], v[158:161], v[206:209], v[92:95]
	v_mfma_f32_16x16x32_bf16 v[88:91], v[166:169], v[206:209], v[88:91]
	v_mfma_f32_16x16x32_bf16 v[76:79], v[158:161], v[214:217], v[76:79]
	v_mfma_f32_16x16x32_bf16 v[72:75], v[166:169], v[214:217], v[72:75]
	s_setprio 0
	s_setprio 1
	v_mfma_f32_16x16x32_bf16 v[116:119], v[170:173], v[186:189], v[116:119]
	v_mfma_f32_16x16x32_bf16 v[112:115], v[178:181], v[186:189], v[112:115]
	v_mfma_f32_16x16x32_bf16 v[100:103], v[170:173], v[194:197], v[100:103]
	v_mfma_f32_16x16x32_bf16 v[96:99], v[178:181], v[194:197], v[96:99]
	v_mfma_f32_16x16x32_bf16 v[84:87], v[170:173], v[202:205], v[84:87]
	v_mfma_f32_16x16x32_bf16 v[80:83], v[178:181], v[202:205], v[80:83]
	v_mfma_f32_16x16x32_bf16 v[68:71], v[170:173], v[210:213], v[68:71]
	v_mfma_f32_16x16x32_bf16 v[64:67], v[178:181], v[210:213], v[64:67]
	v_mfma_f32_16x16x32_bf16 v[116:119], v[174:177], v[190:193], v[116:119]
	v_mfma_f32_16x16x32_bf16 v[112:115], v[182:185], v[190:193], v[112:115]
	v_mfma_f32_16x16x32_bf16 v[100:103], v[174:177], v[198:201], v[100:103]
	v_mfma_f32_16x16x32_bf16 v[96:99], v[182:185], v[198:201], v[96:99]
	v_mfma_f32_16x16x32_bf16 v[84:87], v[174:177], v[206:209], v[84:87]
	v_mfma_f32_16x16x32_bf16 v[80:83], v[182:185], v[206:209], v[80:83]
	v_mfma_f32_16x16x32_bf16 v[68:71], v[174:177], v[214:217], v[68:71]
	v_mfma_f32_16x16x32_bf16 v[64:67], v[182:185], v[214:217], v[64:67]
	s_setprio 0
	s_barrier
	s_add_u32 s100, s22, 0x80
	s_addc_u32 s101, s23, 0
	s_add_i32 s98, s44, s28
	s_mov_b32 m0, s98
	ds_read_b128 v[186:189], v151 offset:49152
	ds_read_b128 v[190:193], v151 offset:50176
	ds_read_b128 v[194:197], v151 offset:51200
	ds_read_b128 v[198:201], v151 offset:52224
	ds_read_b128 v[202:205], v151 offset:53248
	ds_read_b128 v[206:209], v151 offset:54272
	ds_read_b128 v[210:213], v151 offset:55296
	ds_read_b128 v[214:217], v151 offset:56320
	global_load_lds_dwordx4 v132, s[100:101]
	s_add_i32 m0, s98, 0x2000
	s_add_u32 s22, s22, 0x40080
	s_addc_u32 s23, s23, 0
	s_add_i32 s98, s45, s28
	global_load_lds_dwordx4 v128, s[100:101]
	s_mov_b32 m0, s98
	s_nop 0
	global_load_lds_dwordx4 v132, s[22:23]
	s_add_i32 m0, s98, 0x2000
	s_nop 0
	global_load_lds_dwordx4 v128, s[22:23]
	s_add_u32 s100, s24, 0x80
	s_addc_u32 s101, s25, 0
	s_mov_b32 m0, s37
	s_nop 0
	global_load_lds_dwordx4 v134, s[100:101]
	s_mov_b32 m0, s38
	s_nop 0
	global_load_lds_dwordx4 v130, s[100:101]
	s_waitcnt vmcnt(8)
	s_waitcnt lgkmcnt(0)
	s_barrier
	s_setprio 1
	s_waitcnt lgkmcnt(0)
	v_mfma_f32_16x16x32_bf16 v[60:63], v[154:157], v[186:189], v[60:63]
	v_mfma_f32_16x16x32_bf16 v[56:59], v[162:165], v[186:189], v[56:59]
	v_mfma_f32_16x16x32_bf16 v[44:47], v[154:157], v[194:197], v[44:47]
	v_mfma_f32_16x16x32_bf16 v[40:43], v[162:165], v[194:197], v[40:43]
	v_mfma_f32_16x16x32_bf16 v[28:31], v[154:157], v[202:205], v[28:31]
	v_mfma_f32_16x16x32_bf16 v[24:27], v[162:165], v[202:205], v[24:27]
	v_mfma_f32_16x16x32_bf16 v[12:15], v[154:157], v[210:213], v[12:15]
	v_mfma_f32_16x16x32_bf16 v[8:11], v[162:165], v[210:213], v[8:11]
	v_mfma_f32_16x16x32_bf16 v[60:63], v[158:161], v[190:193], v[60:63]
	v_mfma_f32_16x16x32_bf16 v[56:59], v[166:169], v[190:193], v[56:59]
	v_mfma_f32_16x16x32_bf16 v[44:47], v[158:161], v[198:201], v[44:47]
	v_mfma_f32_16x16x32_bf16 v[40:43], v[166:169], v[198:201], v[40:43]
	v_mfma_f32_16x16x32_bf16 v[28:31], v[158:161], v[206:209], v[28:31]
	v_mfma_f32_16x16x32_bf16 v[24:27], v[166:169], v[206:209], v[24:27]
	v_mfma_f32_16x16x32_bf16 v[12:15], v[158:161], v[214:217], v[12:15]
	v_mfma_f32_16x16x32_bf16 v[8:11], v[166:169], v[214:217], v[8:11]
	s_setprio 0
	s_setprio 1
	v_mfma_f32_16x16x32_bf16 v[52:55], v[170:173], v[186:189], v[52:55]
	v_mfma_f32_16x16x32_bf16 v[48:51], v[178:181], v[186:189], v[48:51]
	v_mfma_f32_16x16x32_bf16 v[36:39], v[170:173], v[194:197], v[36:39]
	v_mfma_f32_16x16x32_bf16 v[32:35], v[178:181], v[194:197], v[32:35]
	v_mfma_f32_16x16x32_bf16 v[20:23], v[170:173], v[202:205], v[20:23]
	v_mfma_f32_16x16x32_bf16 v[16:19], v[178:181], v[202:205], v[16:19]
	v_mfma_f32_16x16x32_bf16 v[4:7], v[170:173], v[210:213], v[4:7]
	v_mfma_f32_16x16x32_bf16 v[0:3], v[178:181], v[210:213], v[0:3]
	v_mfma_f32_16x16x32_bf16 v[52:55], v[174:177], v[190:193], v[52:55]
	v_mfma_f32_16x16x32_bf16 v[48:51], v[182:185], v[190:193], v[48:51]
	v_mfma_f32_16x16x32_bf16 v[36:39], v[174:177], v[198:201], v[36:39]
	v_mfma_f32_16x16x32_bf16 v[32:35], v[182:185], v[198:201], v[32:35]
	v_mfma_f32_16x16x32_bf16 v[20:23], v[174:177], v[206:209], v[20:23]
	v_mfma_f32_16x16x32_bf16 v[16:19], v[182:185], v[206:209], v[16:19]
	v_mfma_f32_16x16x32_bf16 v[4:7], v[174:177], v[214:217], v[4:7]
	v_mfma_f32_16x16x32_bf16 v[0:3], v[182:185], v[214:217], v[0:3]
	s_setprio 0
	s_barrier
	s_add_i32 s50, s50, 2
	s_add_u32 s20, s20, 0x100
	s_addc_u32 s21, s21, 0
	s_add_u32 s48, s48, 0x100
	s_addc_u32 s49, s49, 0
	s_cmp_gt_u32 s50, 13
	s_cbranch_scc0 .LBB0_2190
	s_nop 0
	s_nop 0
	s_nop 0
	s_nop 0
	s_nop 0
	s_nop 0
	s_nop 0
	s_nop 0
	s_nop 0
	s_nop 0
	s_nop 0
	s_nop 0
	s_nop 0
	s_nop 0
	s_nop 0
	s_nop 0
	s_nop 0
	s_nop 0
	s_nop 0
	s_nop 0
	s_nop 0
	s_nop 0
	s_nop 0
	s_nop 0
	s_nop 0
	s_and_b64 vcc, exec, s[8:9]
	s_cbranch_vccz .LBB0_2193
	s_barrier

; #define PG8_STAGE(bufoff, gbase, voff) do { _Pragma("unroll") for (int _i = 0; _i < 2; ++_i) \
;         __builtin_amdgcn_global_load_lds((const unsigned*)((const char*)(gbase) + (voff)[_i]), (PG8_LAS unsigned*)(lds + (bufoff) + ldsw + _i * 8192), 16, 0, 0); } while (0)
; #define PG8_LDA(dst, b, h) do { _Pragma("unroll") for (int m = 0; m < 4; ++m) _Pragma("unroll") for (int k = 0; k < 2; ++k) dst[m][k] = *(const PG8_LAS bf16x8*)(lds + PG8_SA(b, h) + aoff + m * 2048 + k * 1024); } while (0)
; #define PG8_LDB(dst, b, h) do { _Pragma("unroll") for (int n = 0; n < 2; ++n) _Pragma("unroll") for (int k = 0; k < 2; ++k) dst[n][k] = *(const PG8_LAS bf16x8*)(lds + PG8_SB(b, h) + boff + n * 2048 + k * 1024); } while (0)
; #define PG8_MMA(ai, bj, At, Bt) do { __builtin_amdgcn_s_setprio(1); _Pragma("unroll") for (int m = 0; m < 4; ++m) _Pragma("unroll") for (int n = 0; n < 2; ++n) _Pragma("unroll") for (int k = 0; k < 2; ++k) \
;         acc[ai][bj][m][n] = __builtin_amdgcn_mfma_f32_16x16x32_bf16(Bt[n][k], At[m][k], acc[ai][bj][m][n], 0, 0, 0); __builtin_amdgcn_s_setprio(0); } while (0)
; #define PG8_WAIT_V(n) asm volatile("s_waitcnt vmcnt(" #n ")" ::: "memory")
; #define PG8_WAIT_L(n) asm volatile("s_waitcnt lgkmcnt(" #n ")" ::: "memory")
; template <class Epi, class Sched, bool ALIGN_EPI = false, bool SP2 = false>
; __device__ __forceinline__ void gemm_phase(PG8_LAS unsigned char* lds, const Gemm g, const Sched& S, const Epi& E) {
;     ...
;             const bool last = (t == nt - 2);
;             const char* a1 = cA + (size_t)(t + 1) * kstep;
;             const char* a2 = last ? nA : cA + (size_t)(t + 2) * kstep; const char* b2 = last ? nB : cB + (size_t)(t + 2) * kstep;
;             const char* a3 = a2 + kstep; const char* b3 = b2 + kstep;
;             if (last && has_next) S.a_ready(nxt);
;             if constexpr (SP2) {
;             PG8_LDB(B0, 0, 0); PG8_LDB(B1, 0, 1); PG8_SCHED; PG8_LDA(At, 0, 0); PG8_STAGE(PG8_SA(1, 1), a1 + hstep, voffA);
;             PG8_WAIT_V(8); PG8_WAIT_L(0); PG8_BAR; PG8_MMA(0, 0, At, B0); PG8_MMA(0, 1, At, B1); PG8_BAR; PG8_SCHED;
;             PG8_LDA(At, 0, 1); PG8_STAGE(PG8_SB(0, 0), b2, voffB); PG8_STAGE(PG8_SB(0, 1), b2 + hstep, voffB); PG8_STAGE(PG8_SA(0, 0), a2, voffA);
;             PG8_WAIT_V(8); PG8_WAIT_L(0); PG8_BAR; PG8_MMA(1, 0, At, B0); PG8_MMA(1, 1, At, B1); PG8_BAR; PG8_SCHED;
.LBB0_2271:
	ds_read_b128 v[144:147], v160
	ds_read_b128 v[148:151], v160 offset:1024
	ds_read_b128 v[152:155], v160 offset:2048
	ds_read_b128 v[166:169], v160 offset:3072
	ds_read_b128 v[170:173], v161
	ds_read_b128 v[174:177], v161 offset:1024
	ds_read_b128 v[178:181], v161 offset:2048
	ds_read_b128 v[182:185], v161 offset:3072
	s_add_u32 s26, s24, 0xfff50080
	s_addc_u32 s27, s25, -1
	s_cmp_eq_u32 s55, 40
	s_cselect_b32 s29, s3, s27
	s_cselect_b32 s28, s2, s26
	s_cselect_b32 s27, s23, s54
	s_cselect_b32 s26, s22, s53
	s_add_i32 m0, s36, 0xc000
	ds_read_b128 v[186:189], v162
	ds_read_b128 v[190:193], v162 offset:1024
	ds_read_b128 v[194:197], v162 offset:2048
	ds_read_b128 v[198:201], v162 offset:3072
	ds_read_b128 v[202:205], v162 offset:4096
	ds_read_b128 v[206:209], v162 offset:5120
	ds_read_b128 v[210:213], v162 offset:6144
	ds_read_b128 v[214:217], v162 offset:7168
	global_load_lds_dwordx4 v136, s[24:25]
	s_add_i32 m0, s36, 0xe000
	s_nop 0
	global_load_lds_dwordx4 v138, s[24:25]
	s_waitcnt vmcnt(8)
	s_waitcnt lgkmcnt(0)
	s_barrier
	s_setprio 1
	s_waitcnt lgkmcnt(0)
	v_mfma_f32_16x16x32_bf16 v[124:127], v[144:147], v[186:189], v[124:127]
	v_mfma_f32_16x16x32_bf16 v[120:123], v[152:155], v[186:189], v[120:123]
	v_mfma_f32_16x16x32_bf16 v[108:111], v[144:147], v[194:197], v[108:111]
	v_mfma_f32_16x16x32_bf16 v[104:107], v[152:155], v[194:197], v[104:107]
	v_mfma_f32_16x16x32_bf16 v[92:95], v[144:147], v[202:205], v[92:95]
	v_mfma_f32_16x16x32_bf16 v[88:91], v[152:155], v[202:205], v[88:91]
	v_mfma_f32_16x16x32_bf16 v[76:79], v[144:147], v[210:213], v[76:79]
	v_mfma_f32_16x16x32_bf16 v[72:75], v[152:155], v[210:213], v[72:75]
	v_mfma_f32_16x16x32_bf16 v[124:127], v[148:151], v[190:193], v[124:127]
	v_mfma_f32_16x16x32_bf16 v[120:123], v[166:169], v[190:193], v[120:123]
	v_mfma_f32_16x16x32_bf16 v[108:111], v[148:151], v[198:201], v[108:111]
	v_mfma_f32_16x16x32_bf16 v[104:107], v[166:169], v[198:201], v[104:107]
	v_mfma_f32_16x16x32_bf16 v[92:95], v[148:151], v[206:209], v[92:95]
	v_mfma_f32_16x16x32_bf16 v[88:91], v[166:169], v[206:209], v[88:91]
	v_mfma_f32_16x16x32_bf16 v[76:79], v[148:151], v[214:217], v[76:79]
	v_mfma_f32_16x16x32_bf16 v[72:75], v[166:169], v[214:217], v[72:75]
	s_setprio 0
	s_setprio 1
	v_mfma_f32_16x16x32_bf16 v[116:119], v[170:173], v[186:189], v[116:119]
	v_mfma_f32_16x16x32_bf16 v[112:115], v[178:181], v[186:189], v[112:115]
	v_mfma_f32_16x16x32_bf16 v[100:103], v[170:173], v[194:197], v[100:103]
	v_mfma_f32_16x16x32_bf16 v[96:99], v[178:181], v[194:197], v[96:99]
	v_mfma_f32_16x16x32_bf16 v[84:87], v[170:173], v[202:205], v[84:87]
	v_mfma_f32_16x16x32_bf16 v[80:83], v[178:181], v[202:205], v[80:83]
	v_mfma_f32_16x16x32_bf16 v[68:71], v[170:173], v[210:213], v[68:71]
	v_mfma_f32_16x16x32_bf16 v[64:67], v[178:181], v[210:213], v[64:67]
	v_mfma_f32_16x16x32_bf16 v[116:119], v[174:177], v[190:193], v[116:119]
	v_mfma_f32_16x16x32_bf16 v[112:115], v[182:185], v[190:193], v[112:115]
	v_mfma_f32_16x16x32_bf16 v[100:103], v[174:177], v[198:201], v[100:103]
	v_mfma_f32_16x16x32_bf16 v[96:99], v[182:185], v[198:201], v[96:99]
	v_mfma_f32_16x16x32_bf16 v[84:87], v[174:177], v[206:209], v[84:87]
	v_mfma_f32_16x16x32_bf16 v[80:83], v[182:185], v[206:209], v[80:83]
	v_mfma_f32_16x16x32_bf16 v[68:71], v[174:177], v[214:217], v[68:71]
	v_mfma_f32_16x16x32_bf16 v[64:67], v[182:185], v[214:217], v[64:67]
	s_setprio 0
	s_barrier
	s_add_i32 s56, s46, s35
	s_mov_b32 m0, s56
	ds_read_b128 v[186:189], v162 offset:16384
	ds_read_b128 v[190:193], v162 offset:17408
	ds_read_b128 v[194:197], v162 offset:18432
	ds_read_b128 v[198:201], v162 offset:19456
	ds_read_b128 v[202:205], v162 offset:20480
	ds_read_b128 v[206:209], v162 offset:21504
	ds_read_b128 v[210:213], v162 offset:22528
	ds_read_b128 v[214:217], v162 offset:23552
	global_load_lds_dwordx4 v130, s[26:27]
	s_add_i32 m0, s56, 0x2000
	s_add_u32 s56, s26, 0xb0000
	s_addc_u32 s57, s27, 0
	s_add_i32 s58, s47, s35
	global_load_lds_dwordx4 v134, s[26:27]
	s_mov_b32 m0, s58
	s_nop 0
	global_load_lds_dwordx4 v130, s[56:57]
	s_add_i32 m0, s58, 0x2000
	s_nop 0
	global_load_lds_dwordx4 v134, s[56:57]
	s_mov_b32 m0, s36
	s_nop 0
	global_load_lds_dwordx4 v128, s[28:29]
	s_mov_b32 m0, s37
	s_nop 0
	global_load_lds_dwordx4 v132, s[28:29]
	s_waitcnt vmcnt(8)
	s_waitcnt lgkmcnt(0)
	s_barrier
	s_setprio 1
	s_waitcnt lgkmcnt(0)
	v_mfma_f32_16x16x32_bf16 v[60:63], v[144:147], v[186:189], v[60:63]
	v_mfma_f32_16x16x32_bf16 v[56:59], v[152:155], v[186:189], v[56:59]
	v_mfma_f32_16x16x32_bf16 v[44:47], v[144:147], v[194:197], v[44:47]
	v_mfma_f32_16x16x32_bf16 v[40:43], v[152:155], v[194:197], v[40:43]
	v_mfma_f32_16x16x32_bf16 v[28:31], v[144:147], v[202:205], v[28:31]
	v_mfma_f32_16x16x32_bf16 v[24:27], v[152:155], v[202:205], v[24:27]
	v_mfma_f32_16x16x32_bf16 v[12:15], v[144:147], v[210:213], v[12:15]
	v_mfma_f32_16x16x32_bf16 v[8:11], v[152:155], v[210:213], v[8:11]
	v_mfma_f32_16x16x32_bf16 v[60:63], v[148:151], v[190:193], v[60:63]
	v_mfma_f32_16x16x32_bf16 v[56:59], v[166:169], v[190:193], v[56:59]
	v_mfma_f32_16x16x32_bf16 v[44:47], v[148:151], v[198:201], v[44:47]
	v_mfma_f32_16x16x32_bf16 v[40:43], v[166:169], v[198:201], v[40:43]
	v_mfma_f32_16x16x32_bf16 v[28:31], v[148:151], v[206:209], v[28:31]
	v_mfma_f32_16x16x32_bf16 v[24:27], v[166:169], v[206:209], v[24:27]
	v_mfma_f32_16x16x32_bf16 v[12:15], v[148:151], v[214:217], v[12:15]
	v_mfma_f32_16x16x32_bf16 v[8:11], v[166:169], v[214:217], v[8:11]
	s_setprio 0
	s_setprio 1
	v_mfma_f32_16x16x32_bf16 v[52:55], v[170:173], v[186:189], v[52:55]
	v_mfma_f32_16x16x32_bf16 v[48:51], v[178:181], v[186:189], v[48:51]
	v_mfma_f32_16x16x32_bf16 v[36:39], v[170:173], v[194:197], v[36:39]
	v_mfma_f32_16x16x32_bf16 v[32:35], v[178:181], v[194:197], v[32:35]
	v_mfma_f32_16x16x32_bf16 v[20:23], v[170:173], v[202:205], v[20:23]
	v_mfma_f32_16x16x32_bf16 v[16:19], v[178:181], v[202:205], v[16:19]
	v_mfma_f32_16x16x32_bf16 v[4:7], v[170:173], v[210:213], v[4:7]
	v_mfma_f32_16x16x32_bf16 v[0:3], v[178:181], v[210:213], v[0:3]
	v_mfma_f32_16x16x32_bf16 v[52:55], v[174:177], v[190:193], v[52:55]
	v_mfma_f32_16x16x32_bf16 v[48:51], v[182:185], v[190:193], v[48:51]
	v_mfma_f32_16x16x32_bf16 v[36:39], v[174:177], v[198:201], v[36:39]
	v_mfma_f32_16x16x32_bf16 v[32:35], v[182:185], v[198:201], v[32:35]
	v_mfma_f32_16x16x32_bf16 v[20:23], v[174:177], v[206:209], v[20:23]
	v_mfma_f32_16x16x32_bf16 v[16:19], v[182:185], v[206:209], v[16:19]
	v_mfma_f32_16x16x32_bf16 v[4:7], v[174:177], v[214:217], v[4:7]
	v_mfma_f32_16x16x32_bf16 v[0:3], v[182:185], v[214:217], v[0:3]
	s_setprio 0
	s_barrier
; #define PG8_STAGE(bufoff, gbase, voff) do { _Pragma("unroll") for (int _i = 0; _i < 2; ++_i) \
;         __builtin_amdgcn_global_load_lds((const unsigned*)((const char*)(gbase) + (voff)[_i]), (PG8_LAS unsigned*)(lds + (bufoff) + ldsw + _i * 8192), 16, 0, 0); } while (0)
; #define PG8_LDA(dst, b, h) do { _Pragma("unroll") for (int m = 0; m < 4; ++m) _Pragma("unroll") for (int k = 0; k < 2; ++k) dst[m][k] = *(const PG8_LAS bf16x8*)(lds + PG8_SA(b, h) + aoff + m * 2048 + k * 1024); } while (0)
; #define PG8_LDB(dst, b, h) do { _Pragma("unroll") for (int n = 0; n < 2; ++n) _Pragma("unroll") for (int k = 0; k < 2; ++k) dst[n][k] = *(const PG8_LAS bf16x8*)(lds + PG8_SB(b, h) + boff + n * 2048 + k * 1024); } while (0)
; #define PG8_MMA(ai, bj, At, Bt) do { __builtin_amdgcn_s_setprio(1); _Pragma("unroll") for (int m = 0; m < 4; ++m) _Pragma("unroll") for (int n = 0; n < 2; ++n) _Pragma("unroll") for (int k = 0; k < 2; ++k) \
;         acc[ai][bj][m][n] = __builtin_amdgcn_mfma_f32_16x16x32_bf16(Bt[n][k], At[m][k], acc[ai][bj][m][n], 0, 0, 0); __builtin_amdgcn_s_setprio(0); } while (0)
; #define PG8_WAIT_V(n) asm volatile("s_waitcnt vmcnt(" #n ")" ::: "memory")
; template <class Epi, class Sched, bool ALIGN_EPI = false, bool SP2 = false>
; __device__ __forceinline__ void gemm_phase(PG8_LAS unsigned char* lds, const Gemm g, const Sched& S, const Epi& E) {
;     ...
;             PG8_LDB(B0, 0, 0); PG8_LDB(B1, 0, 1); PG8_SCHED; PG8_LDA(At, 0, 0); PG8_STAGE(PG8_SA(1, 1), a1 + hstep, voffA);
;             PG8_WAIT_V(8); PG8_WAIT_L(0); PG8_BAR; PG8_MMA(0, 0, At, B0); PG8_MMA(0, 1, At, B1); PG8_BAR; PG8_SCHED;
;             PG8_LDA(At, 0, 1); PG8_STAGE(PG8_SB(0, 0), b2, voffB); PG8_STAGE(PG8_SB(0, 1), b2 + hstep, voffB); PG8_STAGE(PG8_SA(0, 0), a2, voffA);
;             PG8_WAIT_V(8); PG8_WAIT_L(0); PG8_BAR; PG8_MMA(1, 0, At, B0); PG8_MMA(1, 1, At, B1); PG8_BAR; PG8_SCHED;
;             PG8_LDB(B0, 1, 0); PG8_LDB(B1, 1, 1); PG8_SCHED; PG8_LDA(At, 1, 0); PG8_STAGE(PG8_SA(0, 1), a2 + hstep, voffA);
;             PG8_WAIT_V(8); PG8_WAIT_L(0); PG8_BAR; PG8_MMA(0, 0, At, B0); PG8_MMA(0, 1, At, B1); PG8_BAR; PG8_SCHED;
;             PG8_LDA(At, 1, 1); PG8_STAGE(PG8_SB(1, 0), b3, voffB); PG8_STAGE(PG8_SB(1, 1), b3 + hstep, voffB); PG8_STAGE(PG8_SA(1, 0), a3, voffA);
;             PG8_WAIT_V(8); PG8_WAIT_L(0); PG8_BAR; PG8_MMA(1, 0, At, B0); PG8_MMA(1, 1, At, B1); PG8_BAR; PG8_SCHED;
	ds_read_b128 v[144:147], v163
	ds_read_b128 v[148:151], v163 offset:1024
	ds_read_b128 v[152:155], v163 offset:2048
	ds_read_b128 v[166:169], v163 offset:3072
	ds_read_b128 v[170:173], v164
	ds_read_b128 v[174:177], v164 offset:1024
	ds_read_b128 v[178:181], v164 offset:2048
	ds_read_b128 v[182:185], v164 offset:3072
	s_add_u32 s100, s28, 0xb0000
	s_addc_u32 s101, s29, 0
	s_mov_b32 m0, s38
	ds_read_b128 v[186:189], v162 offset:32768
	ds_read_b128 v[190:193], v162 offset:33792
	ds_read_b128 v[194:197], v162 offset:34816
	ds_read_b128 v[198:201], v162 offset:35840
	ds_read_b128 v[202:205], v162 offset:36864
	ds_read_b128 v[206:209], v162 offset:37888
	ds_read_b128 v[210:213], v162 offset:38912
	ds_read_b128 v[214:217], v162 offset:39936
	global_load_lds_dwordx4 v128, s[100:101]
	s_mov_b32 m0, s39
	s_nop 0
	global_load_lds_dwordx4 v132, s[100:101]
	s_waitcnt vmcnt(8)
	s_waitcnt lgkmcnt(0)
	s_barrier
	s_setprio 1
	s_waitcnt lgkmcnt(0)
	v_mfma_f32_16x16x32_bf16 v[124:127], v[144:147], v[186:189], v[124:127]
	v_mfma_f32_16x16x32_bf16 v[120:123], v[152:155], v[186:189], v[120:123]
	v_mfma_f32_16x16x32_bf16 v[108:111], v[144:147], v[194:197], v[108:111]
	v_mfma_f32_16x16x32_bf16 v[104:107], v[152:155], v[194:197], v[104:107]
	v_mfma_f32_16x16x32_bf16 v[92:95], v[144:147], v[202:205], v[92:95]
	v_mfma_f32_16x16x32_bf16 v[88:91], v[152:155], v[202:205], v[88:91]
	v_mfma_f32_16x16x32_bf16 v[76:79], v[144:147], v[210:213], v[76:79]
	v_mfma_f32_16x16x32_bf16 v[72:75], v[152:155], v[210:213], v[72:75]
	v_mfma_f32_16x16x32_bf16 v[124:127], v[148:151], v[190:193], v[124:127]
	v_mfma_f32_16x16x32_bf16 v[120:123], v[166:169], v[190:193], v[120:123]
	v_mfma_f32_16x16x32_bf16 v[108:111], v[148:151], v[198:201], v[108:111]
	v_mfma_f32_16x16x32_bf16 v[104:107], v[166:169], v[198:201], v[104:107]
	v_mfma_f32_16x16x32_bf16 v[92:95], v[148:151], v[206:209], v[92:95]
	v_mfma_f32_16x16x32_bf16 v[88:91], v[166:169], v[206:209], v[88:91]
	v_mfma_f32_16x16x32_bf16 v[76:79], v[148:151], v[214:217], v[76:79]
	v_mfma_f32_16x16x32_bf16 v[72:75], v[166:169], v[214:217], v[72:75]
	s_setprio 0
	s_setprio 1
	v_mfma_f32_16x16x32_bf16 v[116:119], v[170:173], v[186:189], v[116:119]
	v_mfma_f32_16x16x32_bf16 v[112:115], v[178:181], v[186:189], v[112:115]
	v_mfma_f32_16x16x32_bf16 v[100:103], v[170:173], v[194:197], v[100:103]
	v_mfma_f32_16x16x32_bf16 v[96:99], v[178:181], v[194:197], v[96:99]
	v_mfma_f32_16x16x32_bf16 v[84:87], v[170:173], v[202:205], v[84:87]
	v_mfma_f32_16x16x32_bf16 v[80:83], v[178:181], v[202:205], v[80:83]
	v_mfma_f32_16x16x32_bf16 v[68:71], v[170:173], v[210:213], v[68:71]
	v_mfma_f32_16x16x32_bf16 v[64:67], v[178:181], v[210:213], v[64:67]
	v_mfma_f32_16x16x32_bf16 v[116:119], v[174:177], v[190:193], v[116:119]
	v_mfma_f32_16x16x32_bf16 v[112:115], v[182:185], v[190:193], v[112:115]
	v_mfma_f32_16x16x32_bf16 v[100:103], v[174:177], v[198:201], v[100:103]
	v_mfma_f32_16x16x32_bf16 v[96:99], v[182:185], v[198:201], v[96:99]
	v_mfma_f32_16x16x32_bf16 v[84:87], v[174:177], v[206:209], v[84:87]
	v_mfma_f32_16x16x32_bf16 v[80:83], v[182:185], v[206:209], v[80:83]
	v_mfma_f32_16x16x32_bf16 v[68:71], v[174:177], v[214:217], v[68:71]
	v_mfma_f32_16x16x32_bf16 v[64:67], v[182:185], v[214:217], v[64:67]
	s_setprio 0
	s_barrier
	s_add_u32 s100, s26, 0x80
	s_addc_u32 s101, s27, 0
	s_add_i32 s98, s48, s35
	s_mov_b32 m0, s98
	ds_read_b128 v[186:189], v162 offset:49152
	ds_read_b128 v[190:193], v162 offset:50176
	ds_read_b128 v[194:197], v162 offset:51200
	ds_read_b128 v[198:201], v162 offset:52224
	ds_read_b128 v[202:205], v162 offset:53248
	ds_read_b128 v[206:209], v162 offset:54272
	ds_read_b128 v[210:213], v162 offset:55296
	ds_read_b128 v[214:217], v162 offset:56320
	global_load_lds_dwordx4 v130, s[100:101]
	s_add_i32 m0, s98, 0x2000
	s_add_u32 s26, s26, 0xb0080
	s_addc_u32 s27, s27, 0
	s_add_i32 s98, s49, s35
	global_load_lds_dwordx4 v134, s[100:101]
	s_mov_b32 m0, s98
	s_nop 0
	global_load_lds_dwordx4 v130, s[26:27]
	s_add_i32 m0, s98, 0x2000
	s_nop 0
	global_load_lds_dwordx4 v134, s[26:27]
	s_add_u32 s100, s28, 0x80
	s_addc_u32 s101, s29, 0
	s_mov_b32 m0, s42
	s_nop 0
	global_load_lds_dwordx4 v128, s[100:101]
	s_mov_b32 m0, s43
	s_nop 0
	global_load_lds_dwordx4 v132, s[100:101]
	s_waitcnt vmcnt(8)
	s_waitcnt lgkmcnt(0)
	s_barrier
	s_setprio 1
	s_waitcnt lgkmcnt(0)
	v_mfma_f32_16x16x32_bf16 v[60:63], v[144:147], v[186:189], v[60:63]
	v_mfma_f32_16x16x32_bf16 v[56:59], v[152:155], v[186:189], v[56:59]
	v_mfma_f32_16x16x32_bf16 v[44:47], v[144:147], v[194:197], v[44:47]
	v_mfma_f32_16x16x32_bf16 v[40:43], v[152:155], v[194:197], v[40:43]
	v_mfma_f32_16x16x32_bf16 v[28:31], v[144:147], v[202:205], v[28:31]
	v_mfma_f32_16x16x32_bf16 v[24:27], v[152:155], v[202:205], v[24:27]
	v_mfma_f32_16x16x32_bf16 v[12:15], v[144:147], v[210:213], v[12:15]
	v_mfma_f32_16x16x32_bf16 v[8:11], v[152:155], v[210:213], v[8:11]
	v_mfma_f32_16x16x32_bf16 v[60:63], v[148:151], v[190:193], v[60:63]
	v_mfma_f32_16x16x32_bf16 v[56:59], v[166:169], v[190:193], v[56:59]
	v_mfma_f32_16x16x32_bf16 v[44:47], v[148:151], v[198:201], v[44:47]
	v_mfma_f32_16x16x32_bf16 v[40:43], v[166:169], v[198:201], v[40:43]
	v_mfma_f32_16x16x32_bf16 v[28:31], v[148:151], v[206:209], v[28:31]
	v_mfma_f32_16x16x32_bf16 v[24:27], v[166:169], v[206:209], v[24:27]
	v_mfma_f32_16x16x32_bf16 v[12:15], v[148:151], v[214:217], v[12:15]
	v_mfma_f32_16x16x32_bf16 v[8:11], v[166:169], v[214:217], v[8:11]
	s_setprio 0
	s_setprio 1
	v_mfma_f32_16x16x32_bf16 v[52:55], v[170:173], v[186:189], v[52:55]
	v_mfma_f32_16x16x32_bf16 v[48:51], v[178:181], v[186:189], v[48:51]
	v_mfma_f32_16x16x32_bf16 v[36:39], v[170:173], v[194:197], v[36:39]
	v_mfma_f32_16x16x32_bf16 v[32:35], v[178:181], v[194:197], v[32:35]
	v_mfma_f32_16x16x32_bf16 v[20:23], v[170:173], v[202:205], v[20:23]
	v_mfma_f32_16x16x32_bf16 v[16:19], v[178:181], v[202:205], v[16:19]
	v_mfma_f32_16x16x32_bf16 v[4:7], v[170:173], v[210:213], v[4:7]
	v_mfma_f32_16x16x32_bf16 v[0:3], v[178:181], v[210:213], v[0:3]
	v_mfma_f32_16x16x32_bf16 v[52:55], v[174:177], v[190:193], v[52:55]
	v_mfma_f32_16x16x32_bf16 v[48:51], v[182:185], v[190:193], v[48:51]
	v_mfma_f32_16x16x32_bf16 v[36:39], v[174:177], v[198:201], v[36:39]
	v_mfma_f32_16x16x32_bf16 v[32:35], v[182:185], v[198:201], v[32:35]
	v_mfma_f32_16x16x32_bf16 v[20:23], v[174:177], v[206:209], v[20:23]
	v_mfma_f32_16x16x32_bf16 v[16:19], v[182:185], v[206:209], v[16:19]
	v_mfma_f32_16x16x32_bf16 v[4:7], v[174:177], v[214:217], v[4:7]
	v_mfma_f32_16x16x32_bf16 v[0:3], v[182:185], v[214:217], v[0:3]
	s_setprio 0
	s_barrier
	s_add_i32 s55, s55, 2
	s_add_u32 s24, s24, 0x100
	s_addc_u32 s25, s25, 0
	s_add_u32 s53, s53, 0x100
	s_addc_u32 s54, s54, 0
	s_cmp_gt_u32 s55, 41
	s_cbranch_scc0 .LBB0_2271
	s_nop 0
	s_nop 0
	s_nop 0
	s_nop 0
	s_nop 0
	s_nop 0
	s_nop 0
	s_nop 0
	s_nop 0
	s_nop 0
	s_nop 0
	s_nop 0
	s_nop 0
	s_nop 0
	s_nop 0
	s_nop 0
	s_nop 0
	s_nop 0
	s_nop 0
	s_nop 0
	s_nop 0
	s_nop 0
	s_nop 0
	s_nop 0
	s_nop 0
	s_and_b64 vcc, exec, s[12:13]
	s_cbranch_vccz .LBB0_2274
	s_barrier
